# strategy 7.4: one static s_setprio 1 for waves 4-7 during the GEMM phases, hipcc's per-segment priority flips deleted; rest as v150
# baseline (speedup 1.0000x reference)
;     __device__ __forceinline__ bool next(int i, Unit& u) const { if (i != 0) return false; return base.next(which, u); }
;     __device__ __forceinline__ bool next(int i, Unit& u) const { if (i >= nrd) return false; u.pm = (rd0 + i) * 16 + 4 * xl + (j >> 3); u.pn = j & 7; return true; }
;     __host__ __device__ bool next(int i, Unit& u) const {
;         const long L = (long)i * G + c; if (L >= nwg) return false;
;         int wgid = (int)L; { const int q = nwg / NXCD, r = nwg % NXCD, xcd = wgid % NXCD, off = wgid / NXCD; wgid = (xcd < r ? xcd * (q + 1) : r * (q + 1) + (xcd - r) * q) + off; }
;         const int nig = WGM * nN, gid = wgid / nig, fm = gid * WGM, gsz = (nM - fm) < WGM ? (nM - fm) : WGM;
;         u.pm = fm + ((wgid % nig) % gsz); u.pn = (wgid % nig) / gsz; return true;
; template <class Epi, class Sched, bool ALIGN_EPI = false, bool SP2 = false>
; __device__ __forceinline__ void gemm_phase(PG8_LAS unsigned char* lds, const Gemm g, const Sched& S, const Epi& E, const int wave_id) {
;     ...
;     Unit cur, nxt; int ui = 0;
;     if (!S.next(0, cur)) return;
.LBB0_153:
	s_and_b32 s55, s83, 3
	s_lshl_b32 s0, s86, 2
	s_or_b32 s69, s0, s55
	s_cmpk_lt_i32 s69, 0x200
	s_cselect_b64 s[0:1], -1, 0
	s_cmpk_gt_i32 s69, 0x1ff
	s_waitcnt lgkmcnt(0)
	s_barrier
	v_readlane_b32 s99, v254, 4
	s_cmp_ge_u32 s99, 0x100
	s_cbranch_scc0 .Lprio_done1
	s_setprio 1
.Lprio_done1:
	s_cmpk_gt_i32 s69, 0x1ff
	v_mbcnt_lo_u32_b32 v8, -1, 0
	v_mbcnt_hi_u32_b32 v8, -1, v8
	s_cbranch_scc1 .LBB0_159
	s_ashr_i32 s2, s69, 31
	s_lshr_b32 s2, s2, 29
	s_add_i32 s6, s69, s2
	s_and_b32 s2, s6, -8
	s_sub_i32 s4, s69, s2
	s_cmp_gt_i32 s4, -1
	s_cbranch_scc0 .LBB0_156
	s_lshl_b32 s5, s4, 6
	s_ashr_i32 s2, s6, 3
	s_cbranch_execz .LBB0_157
	s_branch .LBB0_158

; #define PG8_STAGE(bufoff, gbase, voff) do { _Pragma("unroll") for (int _i = 0; _i < 2; ++_i) \
;         __builtin_amdgcn_global_load_lds((const unsigned*)((const char*)(gbase) + (voff)[_i]), (PG8_LAS unsigned*)(lds + (bufoff) + ldsw + _i * 8192), 16, 0, 0); } while (0)
; #define PG8_LDA(dst, b, h) do { _Pragma("unroll") for (int m = 0; m < 4; ++m) _Pragma("unroll") for (int k = 0; k < 2; ++k) dst[m][k] = *(const PG8_LAS bf16x8*)(lds + PG8_SA(b, h) + aoff + m * 2048 + k * 1024); } while (0)
; #define PG8_LDB(dst, b, h) do { _Pragma("unroll") for (int n = 0; n < 2; ++n) _Pragma("unroll") for (int k = 0; k < 2; ++k) dst[n][k] = *(const PG8_LAS bf16x8*)(lds + PG8_SB(b, h) + boff + n * 2048 + k * 1024); } while (0)
; #define PG8_MMA(ai, bj, At, Bt) do { __builtin_amdgcn_s_setprio(1); _Pragma("unroll") for (int m = 0; m < 4; ++m) _Pragma("unroll") for (int n = 0; n < 2; ++n) _Pragma("unroll") for (int k = 0; k < 2; ++k) \
;         acc[ai][bj][m][n] = __builtin_amdgcn_mfma_f32_16x16x32_bf16(Bt[n][k], At[m][k], acc[ai][bj][m][n], 0, 0, 0); __builtin_amdgcn_s_setprio(0); } while (0)
; #define PG8_WAIT_V(n) asm volatile("s_waitcnt vmcnt(" #n ")" ::: "memory")
; #define PG8_WAIT_L(n) asm volatile("s_waitcnt lgkmcnt(" #n ")" ::: "memory")
; #define PG8_BAR __builtin_amdgcn_s_barrier()
; #define PG8_SCHED __builtin_amdgcn_sched_barrier(0)
; template <class Epi, class Sched, bool ALIGN_EPI = false, bool SP2 = false>
; __device__ __forceinline__ void gemm_phase(PG8_LAS unsigned char* lds, const Gemm g, const Sched& S, const Epi& E, const int wave_id) {
;     ...
;             PG8_LDB(B0, 0, 0); PG8_LDB(B1, 0, 1); PG8_SCHED; PG8_LDA(At, 0, 0); PG8_STAGE(PG8_SA(1, 1), a1 + hstep, voffA);
;             PG8_WAIT_V(8); PG8_WAIT_L(0); PG8_BAR; PG8_MMA(0, 0, At, B0); PG8_MMA(0, 1, At, B1); PG8_BAR; PG8_SCHED;
;             PG8_LDA(At, 0, 1); PG8_STAGE(PG8_SB(0, 0), b2, voffB); PG8_STAGE(PG8_SB(0, 1), b2 + hstep, voffB); PG8_STAGE(PG8_SA(0, 0), a2, voffA);
;             PG8_WAIT_V(8); PG8_WAIT_L(0); PG8_BAR; PG8_MMA(1, 0, At, B0); PG8_MMA(1, 1, At, B1); PG8_BAR; PG8_SCHED;
.LBB0_172:
	ds_read_b128 v[148:151], v159
	ds_read_b128 v[152:155], v159 offset:1024
	ds_read_b128 v[162:165], v159 offset:2048
	ds_read_b128 v[166:169], v159 offset:3072
	ds_read_b128 v[170:173], v160
	ds_read_b128 v[174:177], v160 offset:1024
	ds_read_b128 v[178:181], v160 offset:2048
	ds_read_b128 v[182:185], v160 offset:3072
	s_add_u32 s48, s46, 0xfff80080
	s_addc_u32 s49, s47, -1
	s_cmp_eq_u32 s79, 28
	s_cselect_b32 s51, s5, s49
	s_cselect_b32 s50, s7, s48
	s_cselect_b32 s49, s37, s78
	s_cselect_b32 s48, s41, s67
	v_lshl_add_u64 v[218:219], s[46:47], 0, v[138:139]
	s_add_i32 m0, s68, 0xc000
	ds_read_b128 v[186:189], v161
	ds_read_b128 v[190:193], v161 offset:1024
	ds_read_b128 v[194:197], v161 offset:2048
	ds_read_b128 v[198:201], v161 offset:3072
	ds_read_b128 v[202:205], v161 offset:4096
	ds_read_b128 v[206:209], v161 offset:5120
	ds_read_b128 v[210:213], v161 offset:6144
	ds_read_b128 v[214:217], v161 offset:7168
	global_load_lds_dwordx4 v[218:219], off
	v_lshl_add_u64 v[218:219], s[46:47], 0, v[140:141]
	s_add_i32 m0, s68, 0xe000
	s_nop 0
	global_load_lds_dwordx4 v[218:219], off
	s_waitcnt vmcnt(8)
	s_waitcnt lgkmcnt(0)
	s_barrier
	s_waitcnt lgkmcnt(0)
	v_mfma_f32_16x16x32_bf16 v[124:127], v[148:151], v[186:189], v[124:127]
	v_mfma_f32_16x16x32_bf16 v[120:123], v[162:165], v[186:189], v[120:123]
	v_mfma_f32_16x16x32_bf16 v[108:111], v[148:151], v[194:197], v[108:111]
	v_mfma_f32_16x16x32_bf16 v[104:107], v[162:165], v[194:197], v[104:107]
	v_mfma_f32_16x16x32_bf16 v[92:95], v[148:151], v[202:205], v[92:95]
	v_mfma_f32_16x16x32_bf16 v[88:91], v[162:165], v[202:205], v[88:91]
	v_mfma_f32_16x16x32_bf16 v[76:79], v[148:151], v[210:213], v[76:79]
	v_mfma_f32_16x16x32_bf16 v[72:75], v[162:165], v[210:213], v[72:75]
	v_mfma_f32_16x16x32_bf16 v[124:127], v[152:155], v[190:193], v[124:127]
	v_mfma_f32_16x16x32_bf16 v[120:123], v[166:169], v[190:193], v[120:123]
	v_mfma_f32_16x16x32_bf16 v[108:111], v[152:155], v[198:201], v[108:111]
	v_mfma_f32_16x16x32_bf16 v[104:107], v[166:169], v[198:201], v[104:107]
	v_mfma_f32_16x16x32_bf16 v[92:95], v[152:155], v[206:209], v[92:95]
	v_mfma_f32_16x16x32_bf16 v[88:91], v[166:169], v[206:209], v[88:91]
	v_mfma_f32_16x16x32_bf16 v[76:79], v[152:155], v[214:217], v[76:79]
	v_mfma_f32_16x16x32_bf16 v[72:75], v[166:169], v[214:217], v[72:75]
	v_mfma_f32_16x16x32_bf16 v[116:119], v[170:173], v[186:189], v[116:119]
	v_mfma_f32_16x16x32_bf16 v[112:115], v[178:181], v[186:189], v[112:115]
	v_mfma_f32_16x16x32_bf16 v[100:103], v[170:173], v[194:197], v[100:103]
	v_mfma_f32_16x16x32_bf16 v[96:99], v[178:181], v[194:197], v[96:99]
	v_mfma_f32_16x16x32_bf16 v[84:87], v[170:173], v[202:205], v[84:87]
	v_mfma_f32_16x16x32_bf16 v[80:83], v[178:181], v[202:205], v[80:83]
	v_mfma_f32_16x16x32_bf16 v[68:71], v[170:173], v[210:213], v[68:71]
	v_mfma_f32_16x16x32_bf16 v[64:67], v[178:181], v[210:213], v[64:67]
	v_mfma_f32_16x16x32_bf16 v[116:119], v[174:177], v[190:193], v[116:119]
	v_mfma_f32_16x16x32_bf16 v[112:115], v[182:185], v[190:193], v[112:115]
	v_mfma_f32_16x16x32_bf16 v[100:103], v[174:177], v[198:201], v[100:103]
	v_mfma_f32_16x16x32_bf16 v[96:99], v[182:185], v[198:201], v[96:99]
	v_mfma_f32_16x16x32_bf16 v[84:87], v[174:177], v[206:209], v[84:87]
	v_mfma_f32_16x16x32_bf16 v[80:83], v[182:185], v[206:209], v[80:83]
	v_mfma_f32_16x16x32_bf16 v[68:71], v[174:177], v[214:217], v[68:71]
	v_mfma_f32_16x16x32_bf16 v[64:67], v[182:185], v[214:217], v[64:67]
	s_barrier
	s_add_i32 s80, s76, s56
	v_lshl_add_u64 v[218:219], s[48:49], 0, v[130:131]
	s_mov_b32 m0, s80
	ds_read_b128 v[186:189], v161 offset:16384
	ds_read_b128 v[190:193], v161 offset:17408
	ds_read_b128 v[194:197], v161 offset:18432
	ds_read_b128 v[198:201], v161 offset:19456
	ds_read_b128 v[202:205], v161 offset:20480
	ds_read_b128 v[206:209], v161 offset:21504
	ds_read_b128 v[210:213], v161 offset:22528
	ds_read_b128 v[214:217], v161 offset:23552
	global_load_lds_dwordx4 v[218:219], off
	s_add_i32 m0, s80, 0x2000
	s_add_u32 s80, s48, 0x80000
	v_lshl_add_u64 v[220:221], s[48:49], 0, v[134:135]
	s_addc_u32 s81, s49, 0
	s_add_i32 s82, s77, s56
	global_load_lds_dwordx4 v[220:221], off
	v_lshl_add_u64 v[222:223], s[80:81], 0, v[130:131]
	s_mov_b32 m0, s82
	v_lshl_add_u64 v[224:225], s[50:51], 0, v[132:133]
	global_load_lds_dwordx4 v[222:223], off
	v_lshl_add_u64 v[222:223], s[80:81], 0, v[134:135]
	s_add_i32 m0, s82, 0x2000
	s_nop 0
	global_load_lds_dwordx4 v[222:223], off
	v_lshl_add_u64 v[222:223], s[50:51], 0, v[128:129]
	s_mov_b32 m0, s68
	s_nop 0
	global_load_lds_dwordx4 v[222:223], off
	s_mov_b32 m0, s70
	s_nop 0
	global_load_lds_dwordx4 v[224:225], off
	s_waitcnt vmcnt(8)
	s_waitcnt lgkmcnt(0)
	s_barrier
; #define PG8_STAGE(bufoff, gbase, voff) do { _Pragma("unroll") for (int _i = 0; _i < 2; ++_i) \
;         __builtin_amdgcn_global_load_lds((const unsigned*)((const char*)(gbase) + (voff)[_i]), (PG8_LAS unsigned*)(lds + (bufoff) + ldsw + _i * 8192), 16, 0, 0); } while (0)
; #define PG8_LDA(dst, b, h) do { _Pragma("unroll") for (int m = 0; m < 4; ++m) _Pragma("unroll") for (int k = 0; k < 2; ++k) dst[m][k] = *(const PG8_LAS bf16x8*)(lds + PG8_SA(b, h) + aoff + m * 2048 + k * 1024); } while (0)
; #define PG8_LDB(dst, b, h) do { _Pragma("unroll") for (int n = 0; n < 2; ++n) _Pragma("unroll") for (int k = 0; k < 2; ++k) dst[n][k] = *(const PG8_LAS bf16x8*)(lds + PG8_SB(b, h) + boff + n * 2048 + k * 1024); } while (0)
; #define PG8_MMA(ai, bj, At, Bt) do { __builtin_amdgcn_s_setprio(1); _Pragma("unroll") for (int m = 0; m < 4; ++m) _Pragma("unroll") for (int n = 0; n < 2; ++n) _Pragma("unroll") for (int k = 0; k < 2; ++k) \
;         acc[ai][bj][m][n] = __builtin_amdgcn_mfma_f32_16x16x32_bf16(Bt[n][k], At[m][k], acc[ai][bj][m][n], 0, 0, 0); __builtin_amdgcn_s_setprio(0); } while (0)
; #define PG8_WAIT_V(n) asm volatile("s_waitcnt vmcnt(" #n ")" ::: "memory")
; #define PG8_WAIT_L(n) asm volatile("s_waitcnt lgkmcnt(" #n ")" ::: "memory")
; #define PG8_BAR __builtin_amdgcn_s_barrier()
; #define PG8_SCHED __builtin_amdgcn_sched_barrier(0)
; template <class Epi, class Sched, bool ALIGN_EPI = false, bool SP2 = false>
; __device__ __forceinline__ void gemm_phase(PG8_LAS unsigned char* lds, const Gemm g, const Sched& S, const Epi& E, const int wave_id) {
;     ...
;             PG8_WAIT_V(8); PG8_WAIT_L(0); PG8_BAR; PG8_MMA(1, 0, At, B0); PG8_MMA(1, 1, At, B1); PG8_BAR; PG8_SCHED;
;             PG8_LDB(B0, 1, 0); PG8_LDB(B1, 1, 1); PG8_SCHED; PG8_LDA(At, 1, 0); PG8_STAGE(PG8_SA(0, 1), a2 + hstep, voffA);
;             PG8_WAIT_V(8); PG8_WAIT_L(0); PG8_BAR; PG8_MMA(0, 0, At, B0); PG8_MMA(0, 1, At, B1); PG8_BAR; PG8_SCHED;
	s_waitcnt lgkmcnt(0)
	v_mfma_f32_16x16x32_bf16 v[60:63], v[148:151], v[186:189], v[60:63]
	v_mfma_f32_16x16x32_bf16 v[56:59], v[162:165], v[186:189], v[56:59]
	v_mfma_f32_16x16x32_bf16 v[44:47], v[148:151], v[194:197], v[44:47]
	v_mfma_f32_16x16x32_bf16 v[40:43], v[162:165], v[194:197], v[40:43]
	v_mfma_f32_16x16x32_bf16 v[28:31], v[148:151], v[202:205], v[28:31]
	v_mfma_f32_16x16x32_bf16 v[24:27], v[162:165], v[202:205], v[24:27]
	v_mfma_f32_16x16x32_bf16 v[12:15], v[148:151], v[210:213], v[12:15]
	v_mfma_f32_16x16x32_bf16 v[8:11], v[162:165], v[210:213], v[8:11]
	v_mfma_f32_16x16x32_bf16 v[60:63], v[152:155], v[190:193], v[60:63]
	v_mfma_f32_16x16x32_bf16 v[56:59], v[166:169], v[190:193], v[56:59]
	v_mfma_f32_16x16x32_bf16 v[44:47], v[152:155], v[198:201], v[44:47]
	v_mfma_f32_16x16x32_bf16 v[40:43], v[166:169], v[198:201], v[40:43]
	v_mfma_f32_16x16x32_bf16 v[28:31], v[152:155], v[206:209], v[28:31]
	v_mfma_f32_16x16x32_bf16 v[24:27], v[166:169], v[206:209], v[24:27]
	v_mfma_f32_16x16x32_bf16 v[12:15], v[152:155], v[214:217], v[12:15]
	v_mfma_f32_16x16x32_bf16 v[8:11], v[166:169], v[214:217], v[8:11]
	v_mfma_f32_16x16x32_bf16 v[52:55], v[170:173], v[186:189], v[52:55]
	v_mfma_f32_16x16x32_bf16 v[48:51], v[178:181], v[186:189], v[48:51]
	v_mfma_f32_16x16x32_bf16 v[36:39], v[170:173], v[194:197], v[36:39]
	v_mfma_f32_16x16x32_bf16 v[32:35], v[178:181], v[194:197], v[32:35]
	v_mfma_f32_16x16x32_bf16 v[20:23], v[170:173], v[202:205], v[20:23]
	v_mfma_f32_16x16x32_bf16 v[16:19], v[178:181], v[202:205], v[16:19]
	v_mfma_f32_16x16x32_bf16 v[4:7], v[170:173], v[210:213], v[4:7]
	v_mfma_f32_16x16x32_bf16 v[0:3], v[178:181], v[210:213], v[0:3]
	v_mfma_f32_16x16x32_bf16 v[52:55], v[174:177], v[190:193], v[52:55]
	v_mfma_f32_16x16x32_bf16 v[48:51], v[182:185], v[190:193], v[48:51]
	v_mfma_f32_16x16x32_bf16 v[36:39], v[174:177], v[198:201], v[36:39]
	v_mfma_f32_16x16x32_bf16 v[32:35], v[182:185], v[198:201], v[32:35]
	v_mfma_f32_16x16x32_bf16 v[20:23], v[174:177], v[206:209], v[20:23]
	v_mfma_f32_16x16x32_bf16 v[16:19], v[182:185], v[206:209], v[16:19]
	v_mfma_f32_16x16x32_bf16 v[4:7], v[174:177], v[214:217], v[4:7]
	v_mfma_f32_16x16x32_bf16 v[0:3], v[182:185], v[214:217], v[0:3]
	s_barrier
	s_add_i32 s80, 0, 0x18000
	v_add_u32_e32 v136, s80, v157
	s_add_i32 s81, 0, 0x1c000
	ds_read_b128 v[148:151], v136
	ds_read_b128 v[152:155], v136 offset:1024
	ds_read_b128 v[162:165], v136 offset:2048
	ds_read_b128 v[166:169], v136 offset:3072
	v_add_u32_e32 v136, s81, v157
	ds_read_b128 v[170:173], v136
	ds_read_b128 v[174:177], v136 offset:1024
	ds_read_b128 v[178:181], v136 offset:2048
	ds_read_b128 v[182:185], v136 offset:3072
	s_add_u32 s50, s50, 0x80000
	s_addc_u32 s51, s51, 0
	s_mov_b32 m0, s71
	v_lshl_add_u64 v[226:227], s[50:51], 0, v[128:129]
	ds_read_b128 v[186:189], v161 offset:32768
	ds_read_b128 v[190:193], v161 offset:33792
	ds_read_b128 v[194:197], v161 offset:34816
	ds_read_b128 v[198:201], v161 offset:35840
	ds_read_b128 v[202:205], v161 offset:36864
	ds_read_b128 v[206:209], v161 offset:37888
	ds_read_b128 v[210:213], v161 offset:38912
	ds_read_b128 v[214:217], v161 offset:39936
	global_load_lds_dwordx4 v[226:227], off
	v_lshl_add_u64 v[226:227], s[50:51], 0, v[132:133]
	s_mov_b32 m0, s72
	s_nop 0
	global_load_lds_dwordx4 v[226:227], off
	s_waitcnt vmcnt(8)
	s_waitcnt lgkmcnt(0)
	s_barrier
	s_waitcnt lgkmcnt(0)
	v_mfma_f32_16x16x32_bf16 v[124:127], v[148:151], v[186:189], v[124:127]
	v_mfma_f32_16x16x32_bf16 v[120:123], v[162:165], v[186:189], v[120:123]
	v_mfma_f32_16x16x32_bf16 v[108:111], v[148:151], v[194:197], v[108:111]
	v_mfma_f32_16x16x32_bf16 v[104:107], v[162:165], v[194:197], v[104:107]
	v_mfma_f32_16x16x32_bf16 v[92:95], v[148:151], v[202:205], v[92:95]
	v_mfma_f32_16x16x32_bf16 v[88:91], v[162:165], v[202:205], v[88:91]
	v_mfma_f32_16x16x32_bf16 v[76:79], v[148:151], v[210:213], v[76:79]
	v_mfma_f32_16x16x32_bf16 v[72:75], v[162:165], v[210:213], v[72:75]
	v_mfma_f32_16x16x32_bf16 v[124:127], v[152:155], v[190:193], v[124:127]
	v_mfma_f32_16x16x32_bf16 v[120:123], v[166:169], v[190:193], v[120:123]
	v_mfma_f32_16x16x32_bf16 v[108:111], v[152:155], v[198:201], v[108:111]
	v_mfma_f32_16x16x32_bf16 v[104:107], v[166:169], v[198:201], v[104:107]
	v_mfma_f32_16x16x32_bf16 v[92:95], v[152:155], v[206:209], v[92:95]
	v_mfma_f32_16x16x32_bf16 v[88:91], v[166:169], v[206:209], v[88:91]
	v_mfma_f32_16x16x32_bf16 v[76:79], v[152:155], v[214:217], v[76:79]
	v_mfma_f32_16x16x32_bf16 v[72:75], v[166:169], v[214:217], v[72:75]
	v_mfma_f32_16x16x32_bf16 v[116:119], v[170:173], v[186:189], v[116:119]
	v_mfma_f32_16x16x32_bf16 v[112:115], v[178:181], v[186:189], v[112:115]
	v_mfma_f32_16x16x32_bf16 v[100:103], v[170:173], v[194:197], v[100:103]
	v_mfma_f32_16x16x32_bf16 v[96:99], v[178:181], v[194:197], v[96:99]
	v_mfma_f32_16x16x32_bf16 v[84:87], v[170:173], v[202:205], v[84:87]
	v_mfma_f32_16x16x32_bf16 v[80:83], v[178:181], v[202:205], v[80:83]
	v_mfma_f32_16x16x32_bf16 v[68:71], v[170:173], v[210:213], v[68:71]
	v_mfma_f32_16x16x32_bf16 v[64:67], v[178:181], v[210:213], v[64:67]
	v_mfma_f32_16x16x32_bf16 v[116:119], v[174:177], v[190:193], v[116:119]
	v_mfma_f32_16x16x32_bf16 v[112:115], v[182:185], v[190:193], v[112:115]
	v_mfma_f32_16x16x32_bf16 v[100:103], v[174:177], v[198:201], v[100:103]
	v_mfma_f32_16x16x32_bf16 v[96:99], v[182:185], v[198:201], v[96:99]
	v_mfma_f32_16x16x32_bf16 v[84:87], v[174:177], v[206:209], v[84:87]
	v_mfma_f32_16x16x32_bf16 v[80:83], v[182:185], v[206:209], v[80:83]
	v_mfma_f32_16x16x32_bf16 v[68:71], v[174:177], v[214:217], v[68:71]
	v_mfma_f32_16x16x32_bf16 v[64:67], v[182:185], v[214:217], v[64:67]
	s_barrier
; #define PG8_STAGE(bufoff, gbase, voff) do { _Pragma("unroll") for (int _i = 0; _i < 2; ++_i) \
;         __builtin_amdgcn_global_load_lds((const unsigned*)((const char*)(gbase) + (voff)[_i]), (PG8_LAS unsigned*)(lds + (bufoff) + ldsw + _i * 8192), 16, 0, 0); } while (0)
; #define PG8_LDA(dst, b, h) do { _Pragma("unroll") for (int m = 0; m < 4; ++m) _Pragma("unroll") for (int k = 0; k < 2; ++k) dst[m][k] = *(const PG8_LAS bf16x8*)(lds + PG8_SA(b, h) + aoff + m * 2048 + k * 1024); } while (0)
; #define PG8_MMA(ai, bj, At, Bt) do { __builtin_amdgcn_s_setprio(1); _Pragma("unroll") for (int m = 0; m < 4; ++m) _Pragma("unroll") for (int n = 0; n < 2; ++n) _Pragma("unroll") for (int k = 0; k < 2; ++k) \
;         acc[ai][bj][m][n] = __builtin_amdgcn_mfma_f32_16x16x32_bf16(Bt[n][k], At[m][k], acc[ai][bj][m][n], 0, 0, 0); __builtin_amdgcn_s_setprio(0); } while (0)
; #define PG8_WAIT_V(n) asm volatile("s_waitcnt vmcnt(" #n ")" ::: "memory")
; #define PG8_WAIT_L(n) asm volatile("s_waitcnt lgkmcnt(" #n ")" ::: "memory")
; #define PG8_BAR __builtin_amdgcn_s_barrier()
; #define PG8_SCHED __builtin_amdgcn_sched_barrier(0)
; template <class Epi, class Sched, bool ALIGN_EPI = false, bool SP2 = false>
; __device__ __forceinline__ void gemm_phase(PG8_LAS unsigned char* lds, const Gemm g, const Sched& S, const Epi& E, const int wave_id) {
;     ...
;         for (int t = 0; t < nt; t += 2) {
;     ...
;             PG8_LDA(At, 1, 1); PG8_STAGE(PG8_SB(1, 0), b3, voffB); PG8_STAGE(PG8_SB(1, 1), b3 + hstep, voffB); PG8_STAGE(PG8_SA(1, 0), a3, voffA);
;             PG8_WAIT_V(8); PG8_WAIT_L(0); PG8_BAR; PG8_MMA(1, 0, At, B0); PG8_MMA(1, 1, At, B1); PG8_BAR; PG8_SCHED;
	s_add_i32 s50, s80, s56
	v_lshl_add_u64 v[218:219], v[218:219], 0, s[16:17]
	s_mov_b32 m0, s50
	ds_read_b128 v[186:189], v161 offset:49152
	ds_read_b128 v[190:193], v161 offset:50176
	ds_read_b128 v[194:197], v161 offset:51200
	ds_read_b128 v[198:201], v161 offset:52224
	ds_read_b128 v[202:205], v161 offset:53248
	ds_read_b128 v[206:209], v161 offset:54272
	ds_read_b128 v[210:213], v161 offset:55296
	ds_read_b128 v[214:217], v161 offset:56320
	global_load_lds_dwordx4 v[218:219], off
	s_add_i32 m0, s50, 0x2000
	s_add_u32 s48, s48, 0x80080
	v_lshl_add_u64 v[218:219], v[220:221], 0, s[16:17]
	s_addc_u32 s49, s49, 0
	s_add_i32 s50, s81, s56
	global_load_lds_dwordx4 v[218:219], off
	v_lshl_add_u64 v[218:219], s[48:49], 0, v[130:131]
	s_mov_b32 m0, s50
	s_nop 0
	global_load_lds_dwordx4 v[218:219], off
	v_lshl_add_u64 v[218:219], s[48:49], 0, v[134:135]
	s_add_i32 m0, s50, 0x2000
	s_nop 0
	global_load_lds_dwordx4 v[218:219], off
	v_lshl_add_u64 v[218:219], v[222:223], 0, s[16:17]
	s_mov_b32 m0, s73
	s_nop 0
	global_load_lds_dwordx4 v[218:219], off
	v_lshl_add_u64 v[218:219], v[224:225], 0, s[16:17]
	s_mov_b32 m0, s74
	s_nop 0
	global_load_lds_dwordx4 v[218:219], off
	s_waitcnt vmcnt(8)
	s_waitcnt lgkmcnt(0)
	s_barrier
	s_waitcnt lgkmcnt(0)
	v_mfma_f32_16x16x32_bf16 v[60:63], v[148:151], v[186:189], v[60:63]
	v_mfma_f32_16x16x32_bf16 v[56:59], v[162:165], v[186:189], v[56:59]
	v_mfma_f32_16x16x32_bf16 v[44:47], v[148:151], v[194:197], v[44:47]
	v_mfma_f32_16x16x32_bf16 v[40:43], v[162:165], v[194:197], v[40:43]
	v_mfma_f32_16x16x32_bf16 v[28:31], v[148:151], v[202:205], v[28:31]
	v_mfma_f32_16x16x32_bf16 v[24:27], v[162:165], v[202:205], v[24:27]
	v_mfma_f32_16x16x32_bf16 v[12:15], v[148:151], v[210:213], v[12:15]
	v_mfma_f32_16x16x32_bf16 v[8:11], v[162:165], v[210:213], v[8:11]
	v_mfma_f32_16x16x32_bf16 v[60:63], v[152:155], v[190:193], v[60:63]
	v_mfma_f32_16x16x32_bf16 v[56:59], v[166:169], v[190:193], v[56:59]
	v_mfma_f32_16x16x32_bf16 v[44:47], v[152:155], v[198:201], v[44:47]
	v_mfma_f32_16x16x32_bf16 v[40:43], v[166:169], v[198:201], v[40:43]
	v_mfma_f32_16x16x32_bf16 v[28:31], v[152:155], v[206:209], v[28:31]
	v_mfma_f32_16x16x32_bf16 v[24:27], v[166:169], v[206:209], v[24:27]
	v_mfma_f32_16x16x32_bf16 v[12:15], v[152:155], v[214:217], v[12:15]
	v_mfma_f32_16x16x32_bf16 v[8:11], v[166:169], v[214:217], v[8:11]
	v_mfma_f32_16x16x32_bf16 v[52:55], v[170:173], v[186:189], v[52:55]
	v_mfma_f32_16x16x32_bf16 v[48:51], v[178:181], v[186:189], v[48:51]
	v_mfma_f32_16x16x32_bf16 v[36:39], v[170:173], v[194:197], v[36:39]
	v_mfma_f32_16x16x32_bf16 v[32:35], v[178:181], v[194:197], v[32:35]
	v_mfma_f32_16x16x32_bf16 v[20:23], v[170:173], v[202:205], v[20:23]
	v_mfma_f32_16x16x32_bf16 v[16:19], v[178:181], v[202:205], v[16:19]
	v_mfma_f32_16x16x32_bf16 v[4:7], v[170:173], v[210:213], v[4:7]
	v_mfma_f32_16x16x32_bf16 v[0:3], v[178:181], v[210:213], v[0:3]
	v_mfma_f32_16x16x32_bf16 v[52:55], v[174:177], v[190:193], v[52:55]
	v_mfma_f32_16x16x32_bf16 v[48:51], v[182:185], v[190:193], v[48:51]
	v_mfma_f32_16x16x32_bf16 v[36:39], v[174:177], v[198:201], v[36:39]
	v_mfma_f32_16x16x32_bf16 v[32:35], v[182:185], v[198:201], v[32:35]
	v_mfma_f32_16x16x32_bf16 v[20:23], v[174:177], v[206:209], v[20:23]
	v_mfma_f32_16x16x32_bf16 v[16:19], v[182:185], v[206:209], v[16:19]
	v_mfma_f32_16x16x32_bf16 v[4:7], v[174:177], v[214:217], v[4:7]
	v_mfma_f32_16x16x32_bf16 v[0:3], v[182:185], v[214:217], v[0:3]
	s_barrier
	s_add_i32 s79, s79, 2
	s_add_u32 s46, s46, 0x100
	s_addc_u32 s47, s47, 0
	s_add_u32 s67, s67, 0x100
	s_addc_u32 s78, s78, 0
	s_cmp_gt_u32 s79, 29
	s_cbranch_scc0 .LBB0_172
	s_and_b64 vcc, exec, s[24:25]
	s_cbranch_vccz .LBB0_175
	s_barrier

; #define PG8_WAIT_V(n) asm volatile("s_waitcnt vmcnt(" #n ")" ::: "memory")
; #define PG8_BAR __builtin_amdgcn_s_barrier()
; __device__ __forceinline__ int lane_id() { int l; asm volatile("v_mbcnt_lo_u32_b32 %0, -1, 0\n\tv_mbcnt_hi_u32_b32 %0, -1, %0" : "=v"(l)); return l; }
; template <class Epi, class Sched, bool ALIGN_EPI = false, bool SP2 = false>
; __device__ __forceinline__ void gemm_phase(PG8_LAS unsigned char* lds, const Gemm g, const Sched& S, const Epi& E, const int wave_id) {
;     ...
;     PG8_WAIT_V(0);
;     if constexpr (!ALIGN_EPI) { if (wr == 0) PG8_BAR; }
;     PG8_BAR;
;     if constexpr (Epi::AFTER_DRAIN) { E.fused(acc, cur, wr, wc, fr, fq, lds, wid, lane); S.done(cur); }
; __device__ __forceinline__ void xcd_arrive(const XcdBarrier& b) {
;     asm volatile("s_waitcnt vmcnt(0)" ::: "memory");
;     __syncthreads();
;     if (b.w0 != 0 && lane_id() == 0) {
;         unsigned* bar = b.bar;
;         __builtin_amdgcn_s_waitcnt(0);
;         unsigned nloc = b.st[0], nx = b.st[1];
;         if (nloc == 0u) { xcd_barrier_complete(bar, b.x, b.G, nloc, nx); b.st[0] = nloc; b.st[1] = nx; }
.LBB0_275:
	s_setprio 0
	v_readlane_b32 s0, v254, 6
	s_waitcnt vmcnt(0)
	s_cmp_lt_u32 s0, 64
	s_cselect_b64 s[2:3], -1, 0
	s_cmp_gt_u32 s0, 63
	s_waitcnt vmcnt(0)
	s_barrier
	s_cbranch_scc1 .LBB0_301
	v_mbcnt_lo_u32_b32 v0, -1, 0
	v_mbcnt_hi_u32_b32 v0, -1, v0
	s_nop 0
	v_cmp_eq_u32_e32 vcc, 0, v0
	s_and_saveexec_b64 s[0:1], vcc
	s_cbranch_execz .LBB0_300
	s_add_i32 s4, 0, 0x20180
	v_mov_b32_e32 v0, s4
	s_waitcnt vmcnt(0) expcnt(0) lgkmcnt(0)
	ds_read_b32 v1, v0
	s_add_i32 s4, 0, 0x20184
	v_mov_b32_e32 v0, s4
	ds_read_b32 v0, v0
	s_waitcnt lgkmcnt(1)
	v_cmp_ne_u32_e32 vcc, 0, v1
	s_cbranch_vccnz .LBB0_292
	s_add_u32 s4, s52, 0x1000
	s_addc_u32 s5, s53, 0
	s_add_u32 s6, s52, 0x1100
	s_addc_u32 s7, s53, 0
	s_add_u32 s16, s52, 0x1200
	s_addc_u32 s17, s53, 0
	s_add_u32 s20, s52, 0x1300
	s_addc_u32 s21, s53, 0
	s_mov_b32 s42, 1
	v_mov_b32_e32 v16, 0
	s_movk_i32 s43, 0x80
	s_branch .LBB0_280

;     __device__ __forceinline__ bool next(int i, Unit& u) const { if (i != 0) return false; return base.next(which, u); }
;     static __device__ __forceinline__ int lane_() { int l; asm volatile("v_mbcnt_lo_u32_b32 %0, -1, 0\n\tv_mbcnt_hi_u32_b32 %0, -1, %0" : "=v"(l)); return l; }
;     __device__ __forceinline__ bool next(int i, Unit& u) const { if (i >= nrd) return false; u.pm = (rd0 + i) * 16 + 4 * xl + (j >> 3); u.pn = j & 7; return true; }
; #define PG8_BAR __builtin_amdgcn_s_barrier()
; template <class Epi, class Sched, bool ALIGN_EPI = false, bool SP2 = false>
; __device__ __forceinline__ void gemm_phase(PG8_LAS unsigned char* lds, const Gemm g, const Sched& S, const Epi& E, const int wave_id) {
;     int lane_; asm volatile("v_mbcnt_lo_u32_b32 %0, -1, 0\n\tv_mbcnt_hi_u32_b32 %0, -1, %0" : "=v"(lane_));
;     const int wid = wave_id, tid = wave_id * 64 + lane_, lane = tid & 63, wr = wid >> 2, wc = wid & 3, fr = lane & 15, fq = lane >> 4;
;     const int K = g.K, nt = K / BK;
;     unsigned voffA[2], voffB[2];
; #pragma unroll
;     for (int i = 0; i < 2; ++i) { int R, C; stage_rc(tid * 16 + i * 8192, R, C); const int Rb = Epi::PERM ? ((R & ~31) + perm32(R & 31)) : R;
;         voffA[i] = (unsigned)(R * K + C) * 2u; voffB[i] = (unsigned)(Rb * K + C) * 2u; }
;     const size_t kstep = (size_t)(BK * 2);
;     const size_t hstep = (size_t)HALF * K * 2;
;     const size_t tstep = 2 * hstep;
;     const unsigned ldsw = (unsigned)wid * 1024u;
;     const int aoff = lds_byte(wr * 64 + fr, fq * 8), boff = lds_byte(wc * 32 + fr, fq * 8);
;     ...
;     Unit cur, nxt; int ui = 0;
;     if (!S.next(0, cur)) return;
;     f32x4 acc[2][2][4][2];
; #pragma unroll
;     for (int a = 0; a < 2; ++a)
; #pragma unroll
;         for (int b = 0; b < 2; ++b)
; #pragma unroll
;             for (int m = 0; m < 4; ++m)
; #pragma unroll
;                 for (int n = 0; n < 2; ++n) acc[a][b][m][n] = (f32x4){0.f, 0.f, 0.f, 0.f};
;     bf16x8 At[4][2], B0[2][2], B1[2][2];
;     const char* cA = (const char*)g.A + (size_t)cur.pm * tstep; const char* cB = (const char*)g.Bt + (size_t)cur.pn * tstep;
;     S.a_ready(cur);
;     if constexpr (SP2) {
;         PG8_STAGE(PG8_SB(0, 0), cB, voffB); PG8_STAGE(PG8_SB(0, 1), cB + hstep, voffB); PG8_STAGE(PG8_SA(0, 0), cA, voffA); PG8_STAGE(PG8_SA(0, 1), cA + hstep, voffA);
;         if (wr == 1) PG8_BAR;
.LBB0_444:
	s_barrier
	v_readlane_b32 s99, v254, 4
	s_cmp_ge_u32 s99, 0x100
	s_cbranch_scc0 .Lprio_done2
	s_setprio 1
.Lprio_done2:
	v_mbcnt_lo_u32_b32 v10, -1, 0
	v_mbcnt_hi_u32_b32 v10, -1, v10
	s_add_u32 s0, s34, s96
	v_lshl_add_u32 v0, v10, 4, s56
	v_ashrrev_i32_e32 v1, 31, v0
	v_lshrrev_b32_e32 v1, 22, v1
	v_add_u32_e32 v1, v0, v1
	v_ashrrev_i32_e32 v8, 10, v1
	v_mul_i32_i24_e32 v1, 0x400, v8
	v_sub_u32_e32 v1, v0, v1
	v_lshrrev_b32_e32 v2, 4, v1
	v_bitop3_b32 v1, v2, v1, 32 bitop3:0x6c
	v_ashrrev_i32_e32 v3, 31, v1
	v_lshrrev_b32_e32 v3, 26, v3
	v_add_u32_e32 v3, v1, v3
	v_lshlrev_b32_e32 v2, 3, v8
	v_ashrrev_i32_e32 v9, 6, v3
	v_and_b32_e32 v3, 0xc0, v3
	v_and_b32_e32 v2, -16, v2
	v_sub_u32_e32 v1, v1, v3
	v_mov_b32_e32 v3, 1
	s_addc_u32 s1, s35, 0
	v_add_u32_e32 v2, v9, v2
	v_ashrrev_i16_sdwa v1, v3, sext(v1) dst_sel:DWORD dst_unused:UNUSED_PAD src0_sel:DWORD src1_sel:BYTE_0
	s_add_u32 s38, s0, 0x11200000
	v_lshlrev_b32_e32 v4, 5, v8
	v_bfe_i32 v11, v1, 0, 16
	v_lshlrev_b32_e32 v1, 1, v2
	v_lshrrev_b32_e32 v5, 2, v2
	v_and_b32_e32 v6, 3, v9
	s_mov_b32 s0, 0x1fffe0
	v_and_b32_e32 v4, 32, v4
	v_and_b32_e32 v1, 24, v1
	v_and_b32_e32 v5, 4, v5
	v_and_or_b32 v6, v2, s0, v6
	v_or3_b32 v1, v6, v5, v1
	v_add_lshl_u32 v4, v4, v11, 1
	v_add_u32_e32 v0, 0x2000, v0
	v_lshl_add_u32 v162, v1, 11, v4
	v_ashrrev_i32_e32 v1, 31, v0
	v_lshrrev_b32_e32 v1, 22, v1
	v_add_u32_e32 v1, v0, v1
	v_ashrrev_i32_e32 v12, 10, v1
	v_mul_i32_i24_e32 v1, 0x400, v12
	v_sub_u32_e32 v0, v0, v1
	v_lshrrev_b32_e32 v1, 4, v0
	v_bitop3_b32 v0, v1, v0, 32 bitop3:0x6c
	v_lshl_add_u32 v160, v2, 11, v4
	v_ashrrev_i32_e32 v2, 31, v0
	v_lshrrev_b32_e32 v2, 26, v2
	v_add_u32_e32 v2, v0, v2
	v_ashrrev_i32_e32 v13, 6, v2
	v_and_b32_e32 v2, 0xffc0, v2
	v_sub_u32_e32 v0, v0, v2
	v_lshrrev_b16_e32 v2, 7, v0
	v_lshlrev_b32_e32 v1, 3, v12
	v_and_b32_e32 v2, 1, v2
	v_and_b32_e32 v1, -16, v1
	v_add_u16_e32 v0, v0, v2
	v_add_u32_e32 v1, v13, v1
	v_ashrrev_i16_sdwa v0, v3, sext(v0) dst_sel:DWORD dst_unused:UNUSED_PAD src0_sel:DWORD src1_sel:BYTE_0
	v_and_b32_e32 v3, 3, v13
	s_addc_u32 s39, s1, 0
	v_and_or_b32 v3, v1, s0, v3
	s_lshl_b32 s0, s55, 2
	s_ashr_i32 s1, s83, 6
	s_add_i32 s12, s0, s1
	v_writelane_b32 v254, s0, 19
	s_ashr_i32 s13, s12, 31
	v_writelane_b32 v254, s1, 21
	s_bfe_u32 s91, s83, 0x30003
	s_lshl_b64 s[0:1], s[12:13], 19
	s_add_u32 s14, s38, s0
	s_addc_u32 s15, s39, s1
	s_lshl_b32 s0, s91, 19
	v_readlane_b32 s2, v254, 23
	v_readlane_b32 s3, v254, 24
	s_add_u32 s4, s2, s0
	v_lshlrev_b32_e32 v4, 5, v12
	v_bfe_i32 v14, v0, 0, 16
	v_lshlrev_b32_e32 v0, 1, v1
	v_lshrrev_b32_e32 v2, 2, v1
	s_addc_u32 s5, s3, 0
	s_add_i32 s33, s56, 0
	v_and_b32_e32 v4, 32, v4
	v_and_b32_e32 v0, 24, v0
	v_and_b32_e32 v2, 4, v2
	s_add_i32 s59, s33, 0x10000
	s_add_i32 s60, s33, 0x12000
	v_or3_b32 v0, v3, v2, v0
	v_add_lshl_u32 v2, v4, v14, 1
	s_mov_b32 m0, s59
	s_add_u32 s2, s4, 0x40000
	v_lshl_add_u32 v166, v0, 11, v2
	global_load_lds_dwordx4 v162, s[4:5]
	s_mov_b32 m0, s60
	s_addc_u32 s3, s5, 0
	s_add_i32 s61, s33, 0x14000
	global_load_lds_dwordx4 v166, s[4:5]
	s_mov_b32 m0, s61
	s_add_i32 s62, s33, 0x16000
	global_load_lds_dwordx4 v162, s[2:3]
	s_mov_b32 m0, s62
	s_add_i32 s63, s33, 0x2000
	global_load_lds_dwordx4 v166, s[2:3]
	s_mov_b32 m0, s33
	s_add_u32 s2, s14, 0x40000
	v_lshl_add_u32 v164, v1, 11, v2
	global_load_lds_dwordx4 v160, s[14:15]
	s_mov_b32 m0, s63
	s_addc_u32 s3, s15, 0
	s_add_i32 s69, s33, 0x4000
	global_load_lds_dwordx4 v164, s[14:15]
	s_mov_b32 m0, s69
	s_add_i32 s70, s33, 0x6000
	global_load_lds_dwordx4 v160, s[2:3]
	s_mov_b32 m0, s70
	v_mov_b32_e32 v169, 0
	global_load_lds_dwordx4 v164, s[2:3]
	v_mov_b32_e32 v163, v169
	v_mov_b32_e32 v167, v169
	v_mov_b32_e32 v161, v169
	v_mov_b32_e32 v165, v169
	s_cmp_eq_u32 s85, 1
	v_lshl_add_u64 v[6:7], s[4:5], 0, v[162:163]
	v_lshl_add_u64 v[2:3], s[4:5], 0, v[166:167]
	v_lshl_add_u64 v[0:1], s[14:15], 0, v[160:161]
	s_cselect_b64 s[2:3], -1, 0
	s_cmp_lg_u32 s85, 1
	v_lshl_add_u64 v[4:5], s[14:15], 0, v[164:165]
	v_writelane_b32 v254, s85, 15
	s_cbranch_scc1 .LBB0_446
	s_barrier

; #define PG8_STAGE(bufoff, gbase, voff) do { _Pragma("unroll") for (int _i = 0; _i < 2; ++_i) \
;         __builtin_amdgcn_global_load_lds((const unsigned*)((const char*)(gbase) + (voff)[_i]), (PG8_LAS unsigned*)(lds + (bufoff) + ldsw + _i * 8192), 16, 0, 0); } while (0)
; #define PG8_LDA(dst, b, h) do { _Pragma("unroll") for (int m = 0; m < 4; ++m) _Pragma("unroll") for (int k = 0; k < 2; ++k) dst[m][k] = *(const PG8_LAS bf16x8*)(lds + PG8_SA(b, h) + aoff + m * 2048 + k * 1024); } while (0)
; #define PG8_LDB(dst, b, h) do { _Pragma("unroll") for (int n = 0; n < 2; ++n) _Pragma("unroll") for (int k = 0; k < 2; ++k) dst[n][k] = *(const PG8_LAS bf16x8*)(lds + PG8_SB(b, h) + boff + n * 2048 + k * 1024); } while (0)
; #define PG8_MMA(ai, bj, At, Bt) do { __builtin_amdgcn_s_setprio(1); _Pragma("unroll") for (int m = 0; m < 4; ++m) _Pragma("unroll") for (int n = 0; n < 2; ++n) _Pragma("unroll") for (int k = 0; k < 2; ++k) \
;         acc[ai][bj][m][n] = __builtin_amdgcn_mfma_f32_16x16x32_bf16(Bt[n][k], At[m][k], acc[ai][bj][m][n], 0, 0, 0); __builtin_amdgcn_s_setprio(0); } while (0)
; #define PG8_WAIT_V(n) asm volatile("s_waitcnt vmcnt(" #n ")" ::: "memory")
; #define PG8_WAIT_L(n) asm volatile("s_waitcnt lgkmcnt(" #n ")" ::: "memory")
; #define PG8_BAR __builtin_amdgcn_s_barrier()
; #define PG8_SCHED __builtin_amdgcn_sched_barrier(0)
; template <class Epi, class Sched, bool ALIGN_EPI = false, bool SP2 = false>
; __device__ __forceinline__ void gemm_phase(PG8_LAS unsigned char* lds, const Gemm g, const Sched& S, const Epi& E, const int wave_id) {
;     ...
;             PG8_LDB(B0, 0, 0); PG8_LDB(B1, 0, 1); PG8_SCHED; PG8_LDA(At, 0, 0); PG8_STAGE(PG8_SA(1, 1), a1 + hstep, voffA);
;             PG8_WAIT_V(8); PG8_WAIT_L(0); PG8_BAR; PG8_MMA(0, 0, At, B0); PG8_MMA(0, 1, At, B1); PG8_BAR; PG8_SCHED;
;             PG8_LDA(At, 0, 1); PG8_STAGE(PG8_SB(0, 0), b2, voffB); PG8_STAGE(PG8_SB(0, 1), b2 + hstep, voffB); PG8_STAGE(PG8_SA(0, 0), a2, voffA);
;             PG8_WAIT_V(8); PG8_WAIT_L(0); PG8_BAR; PG8_MMA(1, 0, At, B0); PG8_MMA(1, 1, At, B1); PG8_BAR; PG8_SCHED;
.LBB0_450:
	ds_read_b128 v[132:135], v193
	ds_read_b128 v[136:139], v193 offset:1024
	ds_read_b128 v[140:143], v193 offset:2048
	ds_read_b128 v[144:147], v193 offset:3072
	ds_read_b128 v[148:151], v194
	ds_read_b128 v[152:155], v194 offset:1024
	ds_read_b128 v[156:159], v194 offset:2048
	ds_read_b128 v[176:179], v194 offset:3072
	s_add_u32 s26, s22, s24
	s_addc_u32 s27, s23, s25
	s_add_u32 s26, s26, 0x100
	s_addc_u32 s27, s27, 0
	s_add_u32 s45, s40, s24
	s_addc_u32 s47, s41, s25
	s_cmpk_eq_i32 s24, 0x700
	s_cselect_b32 s37, s1, s27
	s_cselect_b32 s36, s43, s26
	s_cselect_b32 s27, s5, s47
	s_cselect_b32 s26, s4, s45
	s_mov_b32 m0, s79
	v_lshl_add_u64 v[218:219], v[112:113], 0, s[24:25]
	ds_read_b128 v[180:183], v195
	ds_read_b128 v[184:187], v195 offset:1024
	ds_read_b128 v[188:191], v195 offset:2048
	ds_read_b128 v[198:201], v195 offset:3072
	ds_read_b128 v[202:205], v195 offset:4096
	ds_read_b128 v[206:209], v195 offset:5120
	ds_read_b128 v[210:213], v195 offset:6144
	ds_read_b128 v[214:217], v195 offset:7168
	global_load_lds_dwordx4 v[218:219], off
	v_lshl_add_u64 v[218:219], v[114:115], 0, s[24:25]
	s_mov_b32 m0, s80
	s_nop 0
	global_load_lds_dwordx4 v[218:219], off
	s_waitcnt vmcnt(8)
	s_waitcnt lgkmcnt(0)
	s_barrier
	s_waitcnt lgkmcnt(0)
	v_mfma_f32_16x16x32_bf16 v[128:131], v[132:135], v[180:183], v[128:131]
	v_mfma_f32_16x16x32_bf16 v[120:123], v[140:143], v[180:183], v[120:123]
	v_mfma_f32_16x16x32_bf16 v[108:111], v[132:135], v[188:191], v[108:111]
	v_mfma_f32_16x16x32_bf16 v[100:103], v[140:143], v[188:191], v[100:103]
	v_mfma_f32_16x16x32_bf16 v[92:95], v[132:135], v[202:205], v[92:95]
	v_mfma_f32_16x16x32_bf16 v[84:87], v[140:143], v[202:205], v[84:87]
	v_mfma_f32_16x16x32_bf16 v[76:79], v[132:135], v[210:213], v[76:79]
	v_mfma_f32_16x16x32_bf16 v[68:71], v[140:143], v[210:213], v[68:71]
	v_mfma_f32_16x16x32_bf16 v[128:131], v[136:139], v[184:187], v[128:131]
	v_mfma_f32_16x16x32_bf16 v[120:123], v[144:147], v[184:187], v[120:123]
	v_mfma_f32_16x16x32_bf16 v[108:111], v[136:139], v[198:201], v[108:111]
	v_mfma_f32_16x16x32_bf16 v[100:103], v[144:147], v[198:201], v[100:103]
	v_mfma_f32_16x16x32_bf16 v[92:95], v[136:139], v[206:209], v[92:95]
	v_mfma_f32_16x16x32_bf16 v[84:87], v[144:147], v[206:209], v[84:87]
	v_mfma_f32_16x16x32_bf16 v[76:79], v[136:139], v[214:217], v[76:79]
	v_mfma_f32_16x16x32_bf16 v[68:71], v[144:147], v[214:217], v[68:71]
	v_mfma_f32_16x16x32_bf16 v[124:127], v[148:151], v[180:183], v[124:127]
	v_mfma_f32_16x16x32_bf16 v[116:119], v[156:159], v[180:183], v[116:119]
	v_mfma_f32_16x16x32_bf16 v[104:107], v[148:151], v[188:191], v[104:107]
	v_mfma_f32_16x16x32_bf16 v[96:99], v[156:159], v[188:191], v[96:99]
	v_mfma_f32_16x16x32_bf16 v[88:91], v[148:151], v[202:205], v[88:91]
	v_mfma_f32_16x16x32_bf16 v[80:83], v[156:159], v[202:205], v[80:83]
	v_mfma_f32_16x16x32_bf16 v[72:75], v[148:151], v[210:213], v[72:75]
	v_mfma_f32_16x16x32_bf16 v[64:67], v[156:159], v[210:213], v[64:67]
	v_mfma_f32_16x16x32_bf16 v[124:127], v[152:155], v[184:187], v[124:127]
	v_mfma_f32_16x16x32_bf16 v[116:119], v[176:179], v[184:187], v[116:119]
	v_mfma_f32_16x16x32_bf16 v[104:107], v[152:155], v[198:201], v[104:107]
	v_mfma_f32_16x16x32_bf16 v[96:99], v[176:179], v[198:201], v[96:99]
	v_mfma_f32_16x16x32_bf16 v[88:91], v[152:155], v[206:209], v[88:91]
	v_mfma_f32_16x16x32_bf16 v[80:83], v[176:179], v[206:209], v[80:83]
	v_mfma_f32_16x16x32_bf16 v[72:75], v[152:155], v[214:217], v[72:75]
	v_mfma_f32_16x16x32_bf16 v[64:67], v[176:179], v[214:217], v[64:67]
	s_barrier
	s_mov_b32 m0, s81
	v_lshl_add_u64 v[218:219], s[26:27], 0, v[162:163]
	s_add_u32 s50, s26, 0x40000
	ds_read_b128 v[180:183], v195 offset:16384
	ds_read_b128 v[184:187], v195 offset:17408
	ds_read_b128 v[188:191], v195 offset:18432
	ds_read_b128 v[198:201], v195 offset:19456
	ds_read_b128 v[202:205], v195 offset:20480
	ds_read_b128 v[206:209], v195 offset:21504
	ds_read_b128 v[210:213], v195 offset:22528
	ds_read_b128 v[214:217], v195 offset:23552
	global_load_lds_dwordx4 v[218:219], off
	v_lshl_add_u64 v[220:221], s[26:27], 0, v[166:167]
	s_mov_b32 m0, s82
	s_addc_u32 s51, s27, 0
	global_load_lds_dwordx4 v[220:221], off
	v_lshl_add_u64 v[222:223], s[50:51], 0, v[162:163]
	s_mov_b32 m0, s83
	v_lshl_add_u64 v[224:225], s[36:37], 0, v[164:165]
	global_load_lds_dwordx4 v[222:223], off
	v_lshl_add_u64 v[222:223], s[50:51], 0, v[166:167]
	s_mov_b32 m0, s84
	s_nop 0
	global_load_lds_dwordx4 v[222:223], off
	v_lshl_add_u64 v[222:223], s[36:37], 0, v[160:161]
	s_mov_b32 m0, s33
	s_nop 0
	global_load_lds_dwordx4 v[222:223], off
	s_mov_b32 m0, s63
	s_nop 0
	global_load_lds_dwordx4 v[224:225], off
	s_waitcnt vmcnt(8)
	s_waitcnt lgkmcnt(0)
	s_barrier
; #define PG8_STAGE(bufoff, gbase, voff) do { _Pragma("unroll") for (int _i = 0; _i < 2; ++_i) \
;         __builtin_amdgcn_global_load_lds((const unsigned*)((const char*)(gbase) + (voff)[_i]), (PG8_LAS unsigned*)(lds + (bufoff) + ldsw + _i * 8192), 16, 0, 0); } while (0)
; #define PG8_LDA(dst, b, h) do { _Pragma("unroll") for (int m = 0; m < 4; ++m) _Pragma("unroll") for (int k = 0; k < 2; ++k) dst[m][k] = *(const PG8_LAS bf16x8*)(lds + PG8_SA(b, h) + aoff + m * 2048 + k * 1024); } while (0)
; #define PG8_LDB(dst, b, h) do { _Pragma("unroll") for (int n = 0; n < 2; ++n) _Pragma("unroll") for (int k = 0; k < 2; ++k) dst[n][k] = *(const PG8_LAS bf16x8*)(lds + PG8_SB(b, h) + boff + n * 2048 + k * 1024); } while (0)
; #define PG8_MMA(ai, bj, At, Bt) do { __builtin_amdgcn_s_setprio(1); _Pragma("unroll") for (int m = 0; m < 4; ++m) _Pragma("unroll") for (int n = 0; n < 2; ++n) _Pragma("unroll") for (int k = 0; k < 2; ++k) \
;         acc[ai][bj][m][n] = __builtin_amdgcn_mfma_f32_16x16x32_bf16(Bt[n][k], At[m][k], acc[ai][bj][m][n], 0, 0, 0); __builtin_amdgcn_s_setprio(0); } while (0)
; #define PG8_WAIT_V(n) asm volatile("s_waitcnt vmcnt(" #n ")" ::: "memory")
; #define PG8_WAIT_L(n) asm volatile("s_waitcnt lgkmcnt(" #n ")" ::: "memory")
; #define PG8_BAR __builtin_amdgcn_s_barrier()
; #define PG8_SCHED __builtin_amdgcn_sched_barrier(0)
; template <class Epi, class Sched, bool ALIGN_EPI = false, bool SP2 = false>
; __device__ __forceinline__ void gemm_phase(PG8_LAS unsigned char* lds, const Gemm g, const Sched& S, const Epi& E, const int wave_id) {
;     ...
;             PG8_WAIT_V(8); PG8_WAIT_L(0); PG8_BAR; PG8_MMA(1, 0, At, B0); PG8_MMA(1, 1, At, B1); PG8_BAR; PG8_SCHED;
;             PG8_LDB(B0, 1, 0); PG8_LDB(B1, 1, 1); PG8_SCHED; PG8_LDA(At, 1, 0); PG8_STAGE(PG8_SA(0, 1), a2 + hstep, voffA);
;             PG8_WAIT_V(8); PG8_WAIT_L(0); PG8_BAR; PG8_MMA(0, 0, At, B0); PG8_MMA(0, 1, At, B1); PG8_BAR; PG8_SCHED;
	s_waitcnt lgkmcnt(0)
	v_mfma_f32_16x16x32_bf16 v[60:63], v[132:135], v[180:183], v[60:63]
	v_mfma_f32_16x16x32_bf16 v[52:55], v[140:143], v[180:183], v[52:55]
	v_mfma_f32_16x16x32_bf16 v[44:47], v[132:135], v[188:191], v[44:47]
	v_mfma_f32_16x16x32_bf16 v[36:39], v[140:143], v[188:191], v[36:39]
	v_mfma_f32_16x16x32_bf16 v[28:31], v[132:135], v[202:205], v[28:31]
	v_mfma_f32_16x16x32_bf16 v[20:23], v[140:143], v[202:205], v[20:23]
	v_mfma_f32_16x16x32_bf16 v[12:15], v[132:135], v[210:213], v[12:15]
	v_mfma_f32_16x16x32_bf16 v[4:7], v[140:143], v[210:213], v[4:7]
	v_mfma_f32_16x16x32_bf16 v[60:63], v[136:139], v[184:187], v[60:63]
	v_mfma_f32_16x16x32_bf16 v[52:55], v[144:147], v[184:187], v[52:55]
	v_mfma_f32_16x16x32_bf16 v[44:47], v[136:139], v[198:201], v[44:47]
	v_mfma_f32_16x16x32_bf16 v[36:39], v[144:147], v[198:201], v[36:39]
	v_mfma_f32_16x16x32_bf16 v[28:31], v[136:139], v[206:209], v[28:31]
	v_mfma_f32_16x16x32_bf16 v[20:23], v[144:147], v[206:209], v[20:23]
	v_mfma_f32_16x16x32_bf16 v[12:15], v[136:139], v[214:217], v[12:15]
	v_mfma_f32_16x16x32_bf16 v[4:7], v[144:147], v[214:217], v[4:7]
	v_mfma_f32_16x16x32_bf16 v[56:59], v[148:151], v[180:183], v[56:59]
	v_mfma_f32_16x16x32_bf16 v[48:51], v[156:159], v[180:183], v[48:51]
	v_mfma_f32_16x16x32_bf16 v[40:43], v[148:151], v[188:191], v[40:43]
	v_mfma_f32_16x16x32_bf16 v[32:35], v[156:159], v[188:191], v[32:35]
	v_mfma_f32_16x16x32_bf16 v[24:27], v[148:151], v[202:205], v[24:27]
	v_mfma_f32_16x16x32_bf16 v[16:19], v[156:159], v[202:205], v[16:19]
	v_mfma_f32_16x16x32_bf16 v[8:11], v[148:151], v[210:213], v[8:11]
	v_mfma_f32_16x16x32_bf16 v[0:3], v[156:159], v[210:213], v[0:3]
	v_mfma_f32_16x16x32_bf16 v[56:59], v[152:155], v[184:187], v[56:59]
	v_mfma_f32_16x16x32_bf16 v[48:51], v[176:179], v[184:187], v[48:51]
	v_mfma_f32_16x16x32_bf16 v[40:43], v[152:155], v[198:201], v[40:43]
	v_mfma_f32_16x16x32_bf16 v[32:35], v[176:179], v[198:201], v[32:35]
	v_mfma_f32_16x16x32_bf16 v[24:27], v[152:155], v[206:209], v[24:27]
	v_mfma_f32_16x16x32_bf16 v[16:19], v[176:179], v[206:209], v[16:19]
	v_mfma_f32_16x16x32_bf16 v[8:11], v[152:155], v[214:217], v[8:11]
	v_mfma_f32_16x16x32_bf16 v[0:3], v[176:179], v[214:217], v[0:3]
	s_barrier
	ds_read_b128 v[132:135], v196
	ds_read_b128 v[136:139], v196 offset:1024
	ds_read_b128 v[140:143], v196 offset:2048
	ds_read_b128 v[144:147], v196 offset:3072
	ds_read_b128 v[148:151], v197
	ds_read_b128 v[152:155], v197 offset:1024
	ds_read_b128 v[156:159], v197 offset:2048
	ds_read_b128 v[176:179], v197 offset:3072
	s_add_u32 s36, s36, 0x40000
	s_addc_u32 s37, s37, 0
	s_mov_b32 m0, s69
	v_lshl_add_u64 v[226:227], s[36:37], 0, v[160:161]
	ds_read_b128 v[180:183], v195 offset:32768
	ds_read_b128 v[184:187], v195 offset:33792
	ds_read_b128 v[188:191], v195 offset:34816
	ds_read_b128 v[198:201], v195 offset:35840
	ds_read_b128 v[202:205], v195 offset:36864
	ds_read_b128 v[206:209], v195 offset:37888
	ds_read_b128 v[210:213], v195 offset:38912
	ds_read_b128 v[214:217], v195 offset:39936
	global_load_lds_dwordx4 v[226:227], off
	v_lshl_add_u64 v[226:227], s[36:37], 0, v[164:165]
	s_mov_b32 m0, s70
	s_nop 0
	global_load_lds_dwordx4 v[226:227], off
	s_waitcnt vmcnt(8)
	s_waitcnt lgkmcnt(0)
	s_barrier
	s_waitcnt lgkmcnt(0)
	v_mfma_f32_16x16x32_bf16 v[128:131], v[132:135], v[180:183], v[128:131]
	v_mfma_f32_16x16x32_bf16 v[120:123], v[140:143], v[180:183], v[120:123]
	v_mfma_f32_16x16x32_bf16 v[108:111], v[132:135], v[188:191], v[108:111]
	v_mfma_f32_16x16x32_bf16 v[100:103], v[140:143], v[188:191], v[100:103]
	v_mfma_f32_16x16x32_bf16 v[92:95], v[132:135], v[202:205], v[92:95]
	v_mfma_f32_16x16x32_bf16 v[84:87], v[140:143], v[202:205], v[84:87]
	v_mfma_f32_16x16x32_bf16 v[76:79], v[132:135], v[210:213], v[76:79]
	v_mfma_f32_16x16x32_bf16 v[68:71], v[140:143], v[210:213], v[68:71]
	v_mfma_f32_16x16x32_bf16 v[128:131], v[136:139], v[184:187], v[128:131]
	v_mfma_f32_16x16x32_bf16 v[120:123], v[144:147], v[184:187], v[120:123]
	v_mfma_f32_16x16x32_bf16 v[108:111], v[136:139], v[198:201], v[108:111]
	v_mfma_f32_16x16x32_bf16 v[100:103], v[144:147], v[198:201], v[100:103]
	v_mfma_f32_16x16x32_bf16 v[92:95], v[136:139], v[206:209], v[92:95]
	v_mfma_f32_16x16x32_bf16 v[84:87], v[144:147], v[206:209], v[84:87]
	v_mfma_f32_16x16x32_bf16 v[76:79], v[136:139], v[214:217], v[76:79]
	v_mfma_f32_16x16x32_bf16 v[68:71], v[144:147], v[214:217], v[68:71]
	v_mfma_f32_16x16x32_bf16 v[124:127], v[148:151], v[180:183], v[124:127]
	v_mfma_f32_16x16x32_bf16 v[116:119], v[156:159], v[180:183], v[116:119]
	v_mfma_f32_16x16x32_bf16 v[104:107], v[148:151], v[188:191], v[104:107]
	v_mfma_f32_16x16x32_bf16 v[96:99], v[156:159], v[188:191], v[96:99]
	v_mfma_f32_16x16x32_bf16 v[88:91], v[148:151], v[202:205], v[88:91]
	v_mfma_f32_16x16x32_bf16 v[80:83], v[156:159], v[202:205], v[80:83]
	v_mfma_f32_16x16x32_bf16 v[72:75], v[148:151], v[210:213], v[72:75]
	v_mfma_f32_16x16x32_bf16 v[64:67], v[156:159], v[210:213], v[64:67]
	v_mfma_f32_16x16x32_bf16 v[124:127], v[152:155], v[184:187], v[124:127]
	v_mfma_f32_16x16x32_bf16 v[116:119], v[176:179], v[184:187], v[116:119]
	v_mfma_f32_16x16x32_bf16 v[104:107], v[152:155], v[198:201], v[104:107]
	v_mfma_f32_16x16x32_bf16 v[96:99], v[176:179], v[198:201], v[96:99]
	v_mfma_f32_16x16x32_bf16 v[88:91], v[152:155], v[206:209], v[88:91]
	v_mfma_f32_16x16x32_bf16 v[80:83], v[176:179], v[206:209], v[80:83]
	v_mfma_f32_16x16x32_bf16 v[72:75], v[152:155], v[214:217], v[72:75]
	v_mfma_f32_16x16x32_bf16 v[64:67], v[176:179], v[214:217], v[64:67]
	s_barrier
; #define PG8_STAGE(bufoff, gbase, voff) do { _Pragma("unroll") for (int _i = 0; _i < 2; ++_i) \
;         __builtin_amdgcn_global_load_lds((const unsigned*)((const char*)(gbase) + (voff)[_i]), (PG8_LAS unsigned*)(lds + (bufoff) + ldsw + _i * 8192), 16, 0, 0); } while (0)
; #define PG8_LDA(dst, b, h) do { _Pragma("unroll") for (int m = 0; m < 4; ++m) _Pragma("unroll") for (int k = 0; k < 2; ++k) dst[m][k] = *(const PG8_LAS bf16x8*)(lds + PG8_SA(b, h) + aoff + m * 2048 + k * 1024); } while (0)
; #define PG8_MMA(ai, bj, At, Bt) do { __builtin_amdgcn_s_setprio(1); _Pragma("unroll") for (int m = 0; m < 4; ++m) _Pragma("unroll") for (int n = 0; n < 2; ++n) _Pragma("unroll") for (int k = 0; k < 2; ++k) \
;         acc[ai][bj][m][n] = __builtin_amdgcn_mfma_f32_16x16x32_bf16(Bt[n][k], At[m][k], acc[ai][bj][m][n], 0, 0, 0); __builtin_amdgcn_s_setprio(0); } while (0)
; #define PG8_WAIT_V(n) asm volatile("s_waitcnt vmcnt(" #n ")" ::: "memory")
; #define PG8_WAIT_L(n) asm volatile("s_waitcnt lgkmcnt(" #n ")" ::: "memory")
; #define PG8_BAR __builtin_amdgcn_s_barrier()
; #define PG8_SCHED __builtin_amdgcn_sched_barrier(0)
; template <class Epi, class Sched, bool ALIGN_EPI = false, bool SP2 = false>
; __device__ __forceinline__ void gemm_phase(PG8_LAS unsigned char* lds, const Gemm g, const Sched& S, const Epi& E, const int wave_id) {
;     ...
;         for (int t = 0; t < nt; t += 2) {
;     ...
;             PG8_LDA(At, 1, 1); PG8_STAGE(PG8_SB(1, 0), b3, voffB); PG8_STAGE(PG8_SB(1, 1), b3 + hstep, voffB); PG8_STAGE(PG8_SA(1, 0), a3, voffA);
;             PG8_WAIT_V(8); PG8_WAIT_L(0); PG8_BAR; PG8_MMA(1, 0, At, B0); PG8_MMA(1, 1, At, B1); PG8_BAR; PG8_SCHED;
	s_mov_b32 m0, s87
	v_lshl_add_u64 v[218:219], v[218:219], 0, s[18:19]
	s_add_u32 s26, s26, 0x40080
	ds_read_b128 v[180:183], v195 offset:49152
	ds_read_b128 v[184:187], v195 offset:50176
	ds_read_b128 v[188:191], v195 offset:51200
	ds_read_b128 v[198:201], v195 offset:52224
	ds_read_b128 v[202:205], v195 offset:53248
	ds_read_b128 v[206:209], v195 offset:54272
	ds_read_b128 v[210:213], v195 offset:55296
	ds_read_b128 v[214:217], v195 offset:56320
	global_load_lds_dwordx4 v[218:219], off
	v_lshl_add_u64 v[218:219], v[220:221], 0, s[18:19]
	s_mov_b32 m0, s88
	s_addc_u32 s27, s27, 0
	global_load_lds_dwordx4 v[218:219], off
	v_lshl_add_u64 v[218:219], s[26:27], 0, v[162:163]
	s_mov_b32 m0, s89
	s_nop 0
	global_load_lds_dwordx4 v[218:219], off
	v_lshl_add_u64 v[218:219], s[26:27], 0, v[166:167]
	s_mov_b32 m0, s90
	s_nop 0
	global_load_lds_dwordx4 v[218:219], off
	v_lshl_add_u64 v[218:219], v[222:223], 0, s[18:19]
	s_mov_b32 m0, s73
	s_nop 0
	global_load_lds_dwordx4 v[218:219], off
	v_lshl_add_u64 v[218:219], v[224:225], 0, s[18:19]
	s_mov_b32 m0, s74
	s_nop 0
	global_load_lds_dwordx4 v[218:219], off
	s_waitcnt vmcnt(8)
	s_waitcnt lgkmcnt(0)
	s_barrier
	s_waitcnt lgkmcnt(0)
	v_mfma_f32_16x16x32_bf16 v[60:63], v[132:135], v[180:183], v[60:63]
	v_mfma_f32_16x16x32_bf16 v[52:55], v[140:143], v[180:183], v[52:55]
	v_mfma_f32_16x16x32_bf16 v[44:47], v[132:135], v[188:191], v[44:47]
	v_mfma_f32_16x16x32_bf16 v[36:39], v[140:143], v[188:191], v[36:39]
	v_mfma_f32_16x16x32_bf16 v[28:31], v[132:135], v[202:205], v[28:31]
	v_mfma_f32_16x16x32_bf16 v[20:23], v[140:143], v[202:205], v[20:23]
	v_mfma_f32_16x16x32_bf16 v[12:15], v[132:135], v[210:213], v[12:15]
	v_mfma_f32_16x16x32_bf16 v[4:7], v[140:143], v[210:213], v[4:7]
	v_mfma_f32_16x16x32_bf16 v[60:63], v[136:139], v[184:187], v[60:63]
	v_mfma_f32_16x16x32_bf16 v[52:55], v[144:147], v[184:187], v[52:55]
	v_mfma_f32_16x16x32_bf16 v[44:47], v[136:139], v[198:201], v[44:47]
	v_mfma_f32_16x16x32_bf16 v[36:39], v[144:147], v[198:201], v[36:39]
	v_mfma_f32_16x16x32_bf16 v[28:31], v[136:139], v[206:209], v[28:31]
	v_mfma_f32_16x16x32_bf16 v[20:23], v[144:147], v[206:209], v[20:23]
	v_mfma_f32_16x16x32_bf16 v[12:15], v[136:139], v[214:217], v[12:15]
	v_mfma_f32_16x16x32_bf16 v[4:7], v[144:147], v[214:217], v[4:7]
	v_mfma_f32_16x16x32_bf16 v[56:59], v[148:151], v[180:183], v[56:59]
	v_mfma_f32_16x16x32_bf16 v[48:51], v[156:159], v[180:183], v[48:51]
	v_mfma_f32_16x16x32_bf16 v[40:43], v[148:151], v[188:191], v[40:43]
	v_mfma_f32_16x16x32_bf16 v[32:35], v[156:159], v[188:191], v[32:35]
	v_mfma_f32_16x16x32_bf16 v[24:27], v[148:151], v[202:205], v[24:27]
	v_mfma_f32_16x16x32_bf16 v[16:19], v[156:159], v[202:205], v[16:19]
	v_mfma_f32_16x16x32_bf16 v[8:11], v[148:151], v[210:213], v[8:11]
	v_mfma_f32_16x16x32_bf16 v[0:3], v[156:159], v[210:213], v[0:3]
	v_mfma_f32_16x16x32_bf16 v[56:59], v[152:155], v[184:187], v[56:59]
	v_mfma_f32_16x16x32_bf16 v[48:51], v[176:179], v[184:187], v[48:51]
	v_mfma_f32_16x16x32_bf16 v[40:43], v[152:155], v[198:201], v[40:43]
	v_mfma_f32_16x16x32_bf16 v[32:35], v[176:179], v[198:201], v[32:35]
	v_mfma_f32_16x16x32_bf16 v[24:27], v[152:155], v[206:209], v[24:27]
	v_mfma_f32_16x16x32_bf16 v[16:19], v[176:179], v[206:209], v[16:19]
	v_mfma_f32_16x16x32_bf16 v[8:11], v[152:155], v[214:217], v[8:11]
	v_mfma_f32_16x16x32_bf16 v[0:3], v[176:179], v[214:217], v[0:3]
	s_barrier
	s_add_i32 s44, s44, 2
	s_add_u32 s24, s24, 0x100
	s_addc_u32 s25, s25, 0
	s_cmp_gt_u32 s44, 13
	s_cbranch_scc0 .LBB0_450
	s_and_b64 vcc, exec, s[16:17]
	s_cbranch_vccz .LBB0_453
	s_barrier

;     __device__ __forceinline__ bool next(int i, Unit& u) const { if (i != 0) return false; return base.next(which, u); }
;     __device__ __forceinline__ bool next(int i, Unit& u) const { if (i >= nrd) return false; u.pm = (rd0 + i) * 16 + 4 * xl + (j >> 3); u.pn = j & 7; return true; }
; template <class Epi, class Sched, bool ALIGN_EPI = false, bool SP2 = false>
; __device__ __forceinline__ void gemm_phase(PG8_LAS unsigned char* lds, const Gemm g, const Sched& S, const Epi& E, const int wave_id) {
;     ...
;         PG8_WAIT_V(2); PG8_BAR;
;         PG8_STAGE(PG8_SB(1, 0), cB + kstep, voffB); PG8_STAGE(PG8_SA(1, 0), cA + kstep, voffA); PG8_STAGE(PG8_SB(1, 1), cB + hstep + kstep, voffB);
;         PG8_WAIT_V(6); PG8_BAR;
;     } else {
;         PG8_STAGE(PG8_SB(0, 0), cB, voffB); PG8_STAGE(PG8_SA(0, 0), cA, voffA); PG8_STAGE(PG8_SB(0, 1), cB + hstep, voffB); PG8_STAGE(PG8_SA(0, 1), cA + hstep, voffA);
;         if (wr == 1) PG8_BAR;
;         PG8_WAIT_V(4); PG8_BAR;
;         PG8_STAGE(PG8_SB(1, 0), cB + kstep, voffB); PG8_STAGE(PG8_SA(1, 0), cA + kstep, voffA); PG8_STAGE(PG8_SB(1, 1), cB + hstep + kstep, voffB);
;         PG8_WAIT_V(6); PG8_BAR;
;     }
;     for (;;) {
;         const bool has_next = S.next(ui + 1, nxt);
;         const char* nA = has_next ? (const char*)g.A + (size_t)nxt.pm * tstep : cA; const char* nB = has_next ? (const char*)g.Bt + (size_t)nxt.pn * tstep : cB;
;         for (int t = 0; t < nt; t += 2) {
;             const bool last = (t == nt - 2);
;             const char* a1 = cA + (size_t)(t + 1) * kstep;
;             const char* a2 = last ? nA : cA + (size_t)(t + 2) * kstep; const char* b2 = last ? nB : cB + (size_t)(t + 2) * kstep;
;             const char* a3 = a2 + kstep; const char* b3 = b2 + kstep;
;             if (last && has_next) S.a_ready(nxt);
;             if constexpr (SP2) {
;             PG8_LDB(B0, 0, 0); PG8_LDB(B1, 0, 1); PG8_SCHED; PG8_LDA(At, 0, 0); PG8_STAGE(PG8_SA(1, 1), a1 + hstep, voffA);
;             PG8_WAIT_V(8); PG8_WAIT_L(0); PG8_BAR; PG8_MMA(0, 0, At, B0); PG8_MMA(0, 1, At, B1); PG8_BAR; PG8_SCHED;
;             PG8_LDA(At, 0, 1); PG8_STAGE(PG8_SB(0, 0), b2, voffB); PG8_STAGE(PG8_SB(0, 1), b2 + hstep, voffB); PG8_STAGE(PG8_SA(0, 0), a2, voffA);
;             PG8_WAIT_V(8); PG8_WAIT_L(0); PG8_BAR; PG8_MMA(1, 0, At, B0); PG8_MMA(1, 1, At, B1); PG8_BAR; PG8_SCHED;
.LBB0_484:
	s_mov_b64 s[0:1], 0x80
	s_mov_b32 m0, s87
	v_lshl_add_u64 v[4:5], v[28:29], 0, s[0:1]
	s_waitcnt vmcnt(2)
	s_barrier
	global_load_lds_dwordx4 v[4:5], off
	v_lshl_add_u64 v[6:7], v[30:31], 0, s[0:1]
	s_mov_b32 m0, s88
	v_lshl_add_u64 v[0:1], v[22:23], 0, s[0:1]
	global_load_lds_dwordx4 v[6:7], off
	s_mov_b32 m0, s73
	s_add_u32 s22, s18, 0x10080
	global_load_lds_dwordx4 v[0:1], off
	v_lshl_add_u64 v[2:3], v[24:25], 0, s[0:1]
	s_mov_b32 m0, s74
	s_addc_u32 s23, s19, 0
	global_load_lds_dwordx4 v[2:3], off
	v_lshl_add_u64 v[8:9], s[22:23], 0, v[32:33]
	s_mov_b32 m0, s89
	v_lshl_add_u64 v[10:11], s[22:23], 0, v[34:35]
	global_load_lds_dwordx4 v[8:9], off
	s_mov_b32 m0, s90
	v_lshrrev_b32_e32 v38, 1, v36
	global_load_lds_dwordx4 v[10:11], off
	v_and_b32_e32 v128, 24, v38
	v_and_b32_e32 v37, 15, v36
	v_lshlrev_b32_e32 v39, 1, v128
	v_lshlrev_b32_e32 v36, 2, v36
	v_or_b32_e32 v129, s57, v37
	v_lshl_or_b32 v37, v37, 6, v39
	v_and_b32_e32 v36, 32, v36
	v_lshlrev_b32_e32 v38, 6, v129
	s_movk_i32 s0, 0x3c0
	v_bitop3_b32 v70, v37, s93, v36 bitop3:0xde
	v_and_or_b32 v68, v38, s0, v39
	v_lshlrev_b32_e32 v38, 2, v129
	v_add_u32_e32 v233, s78, v70
	v_and_b32_e32 v69, 32, v38
	s_waitcnt vmcnt(6)
	s_barrier
	v_add_u32_e32 v232, s77, v70
	ds_read_b128 v[36:39], v233 offset:3072
	ds_read_b128 v[40:43], v233 offset:2048
	ds_read_b128 v[44:47], v233 offset:1024
	ds_read_b128 v[48:51], v233
	ds_read_b128 v[52:55], v232 offset:3072
	ds_read_b128 v[56:59], v232 offset:2048
	ds_read_b128 v[60:63], v232 offset:1024
	ds_read_b128 v[64:67], v232
	v_bitop3_b32 v68, v68, s64, v69 bitop3:0xde
	v_writelane_b32 v254, s93, 9
	v_add_u32_e32 v242, 0, v68
	v_add_u32_e32 v234, s85, v70
	v_add_u32_e32 v235, s86, v70
	s_add_u32 s0, s4, 0x10080
	s_addc_u32 s1, s5, 0
	s_mov_b32 m0, s79
	v_lshl_add_u64 v[100:101], s[0:1], 0, v[16:17]
	ds_read_b128 v[68:71], v242
	ds_read_b128 v[72:75], v242 offset:1024
	ds_read_b128 v[76:79], v242 offset:2048
	ds_read_b128 v[80:83], v242 offset:3072
	ds_read_b128 v[84:87], v242 offset:4096
	ds_read_b128 v[88:91], v242 offset:5120
	ds_read_b128 v[92:95], v242 offset:6144
	ds_read_b128 v[96:99], v242 offset:7168
	global_load_lds_dwordx4 v[100:101], off
	v_lshl_add_u64 v[100:101], s[0:1], 0, v[18:19]
	s_mov_b32 m0, s80
	s_nop 0
	global_load_lds_dwordx4 v[100:101], off
	s_waitcnt vmcnt(8)
	s_waitcnt lgkmcnt(0)
	s_barrier
	s_waitcnt lgkmcnt(0)
	v_mfma_f32_16x16x32_bf16 v[100:103], v[64:67], v[68:71], 0
	v_mfma_f32_16x16x32_bf16 v[104:107], v[56:59], v[68:71], 0
	v_mfma_f32_16x16x32_bf16 v[108:111], v[64:67], v[76:79], 0
	v_mfma_f32_16x16x32_bf16 v[112:115], v[56:59], v[76:79], 0
	v_mfma_f32_16x16x32_bf16 v[116:119], v[64:67], v[84:87], 0
	v_mfma_f32_16x16x32_bf16 v[120:123], v[56:59], v[84:87], 0
	v_mfma_f32_16x16x32_bf16 v[124:127], v[64:67], v[92:95], 0
	v_mfma_f32_16x16x32_bf16 v[100:103], v[60:63], v[72:75], v[100:103]
	v_mfma_f32_16x16x32_bf16 v[104:107], v[52:55], v[72:75], v[104:107]
	v_mfma_f32_16x16x32_bf16 v[108:111], v[60:63], v[80:83], v[108:111]
	v_mfma_f32_16x16x32_bf16 v[112:115], v[52:55], v[80:83], v[112:115]
	v_mfma_f32_16x16x32_bf16 v[116:119], v[60:63], v[88:91], v[116:119]
	v_mfma_f32_16x16x32_bf16 v[120:123], v[52:55], v[88:91], v[120:123]
	v_mfma_f32_16x16x32_bf16 v[124:127], v[60:63], v[96:99], v[124:127]
	v_mfma_f32_16x16x32_bf16 v[130:133], v[56:59], v[92:95], 0
	v_mfma_f32_16x16x32_bf16 v[130:133], v[52:55], v[96:99], v[130:133]
	v_mfma_f32_16x16x32_bf16 v[134:137], v[48:51], v[68:71], 0
	v_mfma_f32_16x16x32_bf16 v[68:71], v[40:43], v[68:71], 0
	v_mfma_f32_16x16x32_bf16 v[134:137], v[44:47], v[72:75], v[134:137]
	v_mfma_f32_16x16x32_bf16 v[68:71], v[36:39], v[72:75], v[68:71]
	v_mfma_f32_16x16x32_bf16 v[72:75], v[48:51], v[76:79], 0
	v_mfma_f32_16x16x32_bf16 v[76:79], v[40:43], v[76:79], 0
	v_mfma_f32_16x16x32_bf16 v[72:75], v[44:47], v[80:83], v[72:75]
	v_mfma_f32_16x16x32_bf16 v[76:79], v[36:39], v[80:83], v[76:79]
	v_mfma_f32_16x16x32_bf16 v[80:83], v[48:51], v[84:87], 0
	v_mfma_f32_16x16x32_bf16 v[84:87], v[40:43], v[84:87], 0
	v_mfma_f32_16x16x32_bf16 v[80:83], v[44:47], v[88:91], v[80:83]
	v_mfma_f32_16x16x32_bf16 v[84:87], v[36:39], v[88:91], v[84:87]
	v_mfma_f32_16x16x32_bf16 v[88:91], v[48:51], v[92:95], 0
	v_mfma_f32_16x16x32_bf16 v[92:95], v[40:43], v[92:95], 0
	v_mfma_f32_16x16x32_bf16 v[88:91], v[44:47], v[96:99], v[88:91]
	v_mfma_f32_16x16x32_bf16 v[92:95], v[36:39], v[96:99], v[92:95]
	s_barrier
	s_mov_b64 s[0:1], 0x100
	s_mov_b32 m0, s81
	v_lshl_add_u64 v[166:167], v[28:29], 0, s[0:1]
	s_add_u32 s24, s18, 0x10100
	ds_read_b128 v[96:99], v242 offset:16384
	ds_read_b128 v[138:141], v242 offset:17408
	ds_read_b128 v[142:145], v242 offset:18432
	ds_read_b128 v[146:149], v242 offset:19456
	ds_read_b128 v[150:153], v242 offset:20480
	ds_read_b128 v[154:157], v242 offset:21504
	ds_read_b128 v[158:161], v242 offset:22528
	ds_read_b128 v[162:165], v242 offset:23552
	global_load_lds_dwordx4 v[166:167], off
	v_lshl_add_u64 v[166:167], v[30:31], 0, s[0:1]
	s_mov_b32 m0, s82
	s_addc_u32 s25, s19, 0
	global_load_lds_dwordx4 v[166:167], off
	v_lshl_add_u64 v[166:167], s[24:25], 0, v[32:33]
	s_mov_b32 m0, s83
	s_nop 0
	global_load_lds_dwordx4 v[166:167], off
	v_lshl_add_u64 v[166:167], s[24:25], 0, v[34:35]
	s_mov_b32 m0, s84
	s_nop 0
	global_load_lds_dwordx4 v[166:167], off
	v_lshl_add_u64 v[166:167], v[22:23], 0, s[0:1]
	s_mov_b32 m0, s33
	s_nop 0
	global_load_lds_dwordx4 v[166:167], off
	v_lshl_add_u64 v[166:167], v[24:25], 0, s[0:1]
	s_mov_b32 m0, s63
	s_nop 0
	global_load_lds_dwordx4 v[166:167], off
	s_waitcnt vmcnt(8)
	s_waitcnt lgkmcnt(0)
	s_barrier
; #define PG8_STAGE(bufoff, gbase, voff) do { _Pragma("unroll") for (int _i = 0; _i < 2; ++_i) \
;         __builtin_amdgcn_global_load_lds((const unsigned*)((const char*)(gbase) + (voff)[_i]), (PG8_LAS unsigned*)(lds + (bufoff) + ldsw + _i * 8192), 16, 0, 0); } while (0)
; #define PG8_LDA(dst, b, h) do { _Pragma("unroll") for (int m = 0; m < 4; ++m) _Pragma("unroll") for (int k = 0; k < 2; ++k) dst[m][k] = *(const PG8_LAS bf16x8*)(lds + PG8_SA(b, h) + aoff + m * 2048 + k * 1024); } while (0)
; #define PG8_LDB(dst, b, h) do { _Pragma("unroll") for (int n = 0; n < 2; ++n) _Pragma("unroll") for (int k = 0; k < 2; ++k) dst[n][k] = *(const PG8_LAS bf16x8*)(lds + PG8_SB(b, h) + boff + n * 2048 + k * 1024); } while (0)
; #define PG8_MMA(ai, bj, At, Bt) do { __builtin_amdgcn_s_setprio(1); _Pragma("unroll") for (int m = 0; m < 4; ++m) _Pragma("unroll") for (int n = 0; n < 2; ++n) _Pragma("unroll") for (int k = 0; k < 2; ++k) \
;         acc[ai][bj][m][n] = __builtin_amdgcn_mfma_f32_16x16x32_bf16(Bt[n][k], At[m][k], acc[ai][bj][m][n], 0, 0, 0); __builtin_amdgcn_s_setprio(0); } while (0)
; #define PG8_WAIT_V(n) asm volatile("s_waitcnt vmcnt(" #n ")" ::: "memory")
; #define PG8_WAIT_L(n) asm volatile("s_waitcnt lgkmcnt(" #n ")" ::: "memory")
; #define PG8_BAR __builtin_amdgcn_s_barrier()
; #define PG8_SCHED __builtin_amdgcn_sched_barrier(0)
; template <class Epi, class Sched, bool ALIGN_EPI = false, bool SP2 = false>
; __device__ __forceinline__ void gemm_phase(PG8_LAS unsigned char* lds, const Gemm g, const Sched& S, const Epi& E, const int wave_id) {
;     ...
;             PG8_WAIT_V(8); PG8_WAIT_L(0); PG8_BAR; PG8_MMA(1, 0, At, B0); PG8_MMA(1, 1, At, B1); PG8_BAR; PG8_SCHED;
;             PG8_LDB(B0, 1, 0); PG8_LDB(B1, 1, 1); PG8_SCHED; PG8_LDA(At, 1, 0); PG8_STAGE(PG8_SA(0, 1), a2 + hstep, voffA);
;             PG8_WAIT_V(8); PG8_WAIT_L(0); PG8_BAR; PG8_MMA(0, 0, At, B0); PG8_MMA(0, 1, At, B1); PG8_BAR; PG8_SCHED;
	s_waitcnt lgkmcnt(0)
	v_mfma_f32_16x16x32_bf16 v[166:169], v[64:67], v[96:99], 0
	v_mfma_f32_16x16x32_bf16 v[170:173], v[56:59], v[96:99], 0
	v_mfma_f32_16x16x32_bf16 v[174:177], v[64:67], v[142:145], 0
	v_mfma_f32_16x16x32_bf16 v[178:181], v[56:59], v[142:145], 0
	v_mfma_f32_16x16x32_bf16 v[182:185], v[64:67], v[150:153], 0
	v_mfma_f32_16x16x32_bf16 v[186:189], v[56:59], v[150:153], 0
	v_mfma_f32_16x16x32_bf16 v[64:67], v[64:67], v[158:161], 0
	v_mfma_f32_16x16x32_bf16 v[56:59], v[56:59], v[158:161], 0
	v_mfma_f32_16x16x32_bf16 v[166:169], v[60:63], v[138:141], v[166:169]
	v_mfma_f32_16x16x32_bf16 v[170:173], v[52:55], v[138:141], v[170:173]
	v_mfma_f32_16x16x32_bf16 v[174:177], v[60:63], v[146:149], v[174:177]
	v_mfma_f32_16x16x32_bf16 v[178:181], v[52:55], v[146:149], v[178:181]
	v_mfma_f32_16x16x32_bf16 v[182:185], v[60:63], v[154:157], v[182:185]
	v_mfma_f32_16x16x32_bf16 v[186:189], v[52:55], v[154:157], v[186:189]
	v_mfma_f32_16x16x32_bf16 v[60:63], v[60:63], v[162:165], v[64:67]
	v_mfma_f32_16x16x32_bf16 v[52:55], v[52:55], v[162:165], v[56:59]
	v_mfma_f32_16x16x32_bf16 v[56:59], v[48:51], v[96:99], 0
	v_mfma_f32_16x16x32_bf16 v[64:67], v[40:43], v[96:99], 0
	v_mfma_f32_16x16x32_bf16 v[56:59], v[44:47], v[138:141], v[56:59]
	v_mfma_f32_16x16x32_bf16 v[64:67], v[36:39], v[138:141], v[64:67]
	v_mfma_f32_16x16x32_bf16 v[96:99], v[48:51], v[142:145], 0
	v_mfma_f32_16x16x32_bf16 v[138:141], v[40:43], v[142:145], 0
	v_mfma_f32_16x16x32_bf16 v[96:99], v[44:47], v[146:149], v[96:99]
	v_mfma_f32_16x16x32_bf16 v[138:141], v[36:39], v[146:149], v[138:141]
	v_mfma_f32_16x16x32_bf16 v[142:145], v[48:51], v[150:153], 0
	v_mfma_f32_16x16x32_bf16 v[146:149], v[40:43], v[150:153], 0
	v_mfma_f32_16x16x32_bf16 v[48:51], v[48:51], v[158:161], 0
	v_mfma_f32_16x16x32_bf16 v[40:43], v[40:43], v[158:161], 0
	v_mfma_f32_16x16x32_bf16 v[142:145], v[44:47], v[154:157], v[142:145]
	v_mfma_f32_16x16x32_bf16 v[146:149], v[36:39], v[154:157], v[146:149]
	v_mfma_f32_16x16x32_bf16 v[44:47], v[44:47], v[162:165], v[48:51]
	v_mfma_f32_16x16x32_bf16 v[36:39], v[36:39], v[162:165], v[40:43]
	s_barrier
	s_nop 1
	ds_read_b128 v[40:43], v234
	ds_read_b128 v[48:51], v234 offset:1024
	ds_read_b128 v[150:153], v234 offset:2048
	ds_read_b128 v[154:157], v234 offset:3072
	ds_read_b128 v[158:161], v235
	ds_read_b128 v[162:165], v235 offset:1024
	ds_read_b128 v[190:193], v235 offset:2048
	ds_read_b128 v[194:197], v235 offset:3072
	s_add_u32 s0, s4, 0x10100
	s_addc_u32 s1, s5, 0
	s_mov_b32 m0, s69
	v_lshl_add_u64 v[230:231], s[0:1], 0, v[16:17]
	ds_read_b128 v[198:201], v242 offset:32768
	ds_read_b128 v[202:205], v242 offset:33792
	ds_read_b128 v[206:209], v242 offset:34816
	ds_read_b128 v[210:213], v242 offset:35840
	ds_read_b128 v[214:217], v242 offset:36864
	ds_read_b128 v[218:221], v242 offset:37888
	ds_read_b128 v[222:225], v242 offset:38912
	ds_read_b128 v[226:229], v242 offset:39936
	global_load_lds_dwordx4 v[230:231], off
	v_lshl_add_u64 v[230:231], s[0:1], 0, v[18:19]
	s_mov_b32 m0, s70
	s_nop 0
	global_load_lds_dwordx4 v[230:231], off
	s_waitcnt vmcnt(8)
	s_waitcnt lgkmcnt(0)
	s_barrier
	s_waitcnt lgkmcnt(0)
	v_mfma_f32_16x16x32_bf16 v[100:103], v[40:43], v[198:201], v[100:103]
	v_mfma_f32_16x16x32_bf16 v[104:107], v[150:153], v[198:201], v[104:107]
	v_mfma_f32_16x16x32_bf16 v[108:111], v[40:43], v[206:209], v[108:111]
	v_mfma_f32_16x16x32_bf16 v[112:115], v[150:153], v[206:209], v[112:115]
	v_mfma_f32_16x16x32_bf16 v[116:119], v[40:43], v[214:217], v[116:119]
	v_mfma_f32_16x16x32_bf16 v[120:123], v[150:153], v[214:217], v[120:123]
	v_mfma_f32_16x16x32_bf16 v[124:127], v[40:43], v[222:225], v[124:127]
	v_mfma_f32_16x16x32_bf16 v[100:103], v[48:51], v[202:205], v[100:103]
	v_mfma_f32_16x16x32_bf16 v[104:107], v[154:157], v[202:205], v[104:107]
	v_mfma_f32_16x16x32_bf16 v[108:111], v[48:51], v[210:213], v[108:111]
	v_mfma_f32_16x16x32_bf16 v[112:115], v[154:157], v[210:213], v[112:115]
	v_mfma_f32_16x16x32_bf16 v[116:119], v[48:51], v[218:221], v[116:119]
	v_mfma_f32_16x16x32_bf16 v[120:123], v[154:157], v[218:221], v[120:123]
	v_mfma_f32_16x16x32_bf16 v[124:127], v[48:51], v[226:229], v[124:127]
	v_mfma_f32_16x16x32_bf16 v[130:133], v[150:153], v[222:225], v[130:133]
	v_mfma_f32_16x16x32_bf16 v[130:133], v[154:157], v[226:229], v[130:133]
	v_mfma_f32_16x16x32_bf16 v[68:71], v[190:193], v[198:201], v[68:71]
	v_mfma_f32_16x16x32_bf16 v[72:75], v[158:161], v[206:209], v[72:75]
	v_mfma_f32_16x16x32_bf16 v[76:79], v[190:193], v[206:209], v[76:79]
	v_mfma_f32_16x16x32_bf16 v[80:83], v[158:161], v[214:217], v[80:83]
	v_mfma_f32_16x16x32_bf16 v[84:87], v[190:193], v[214:217], v[84:87]
	v_mfma_f32_16x16x32_bf16 v[88:91], v[158:161], v[222:225], v[88:91]
	v_mfma_f32_16x16x32_bf16 v[92:95], v[190:193], v[222:225], v[92:95]
	v_mfma_f32_16x16x32_bf16 v[134:137], v[158:161], v[198:201], v[134:137]
	v_mfma_f32_16x16x32_bf16 v[68:71], v[194:197], v[202:205], v[68:71]
	v_mfma_f32_16x16x32_bf16 v[72:75], v[162:165], v[210:213], v[72:75]
	v_mfma_f32_16x16x32_bf16 v[76:79], v[194:197], v[210:213], v[76:79]
	v_mfma_f32_16x16x32_bf16 v[80:83], v[162:165], v[218:221], v[80:83]
	v_mfma_f32_16x16x32_bf16 v[84:87], v[194:197], v[218:221], v[84:87]
	v_mfma_f32_16x16x32_bf16 v[88:91], v[162:165], v[226:229], v[88:91]
	v_mfma_f32_16x16x32_bf16 v[92:95], v[194:197], v[226:229], v[92:95]
	v_mfma_f32_16x16x32_bf16 v[134:137], v[162:165], v[202:205], v[134:137]
	s_barrier
; #define PG8_STAGE(bufoff, gbase, voff) do { _Pragma("unroll") for (int _i = 0; _i < 2; ++_i) \
;         __builtin_amdgcn_global_load_lds((const unsigned*)((const char*)(gbase) + (voff)[_i]), (PG8_LAS unsigned*)(lds + (bufoff) + ldsw + _i * 8192), 16, 0, 0); } while (0)
; #define PG8_LDA(dst, b, h) do { _Pragma("unroll") for (int m = 0; m < 4; ++m) _Pragma("unroll") for (int k = 0; k < 2; ++k) dst[m][k] = *(const PG8_LAS bf16x8*)(lds + PG8_SA(b, h) + aoff + m * 2048 + k * 1024); } while (0)
; #define PG8_LDB(dst, b, h) do { _Pragma("unroll") for (int n = 0; n < 2; ++n) _Pragma("unroll") for (int k = 0; k < 2; ++k) dst[n][k] = *(const PG8_LAS bf16x8*)(lds + PG8_SB(b, h) + boff + n * 2048 + k * 1024); } while (0)
; #define PG8_MMA(ai, bj, At, Bt) do { __builtin_amdgcn_s_setprio(1); _Pragma("unroll") for (int m = 0; m < 4; ++m) _Pragma("unroll") for (int n = 0; n < 2; ++n) _Pragma("unroll") for (int k = 0; k < 2; ++k) \
;         acc[ai][bj][m][n] = __builtin_amdgcn_mfma_f32_16x16x32_bf16(Bt[n][k], At[m][k], acc[ai][bj][m][n], 0, 0, 0); __builtin_amdgcn_s_setprio(0); } while (0)
; #define PG8_BAR __builtin_amdgcn_s_barrier()
; template <class Epi, class Sched, bool ALIGN_EPI = false, bool SP2 = false>
; __device__ __forceinline__ void gemm_phase(PG8_LAS unsigned char* lds, const Gemm g, const Sched& S, const Epi& E, const int wave_id) {
;     ...
;             PG8_LDB(B0, 0, 0); PG8_LDB(B1, 0, 1); PG8_SCHED; PG8_LDA(At, 0, 0); PG8_STAGE(PG8_SA(1, 1), a1 + hstep, voffA);
;             PG8_WAIT_V(8); PG8_WAIT_L(0); PG8_BAR; PG8_MMA(0, 0, At, B0); PG8_MMA(0, 1, At, B1); PG8_BAR; PG8_SCHED;
;             PG8_LDA(At, 0, 1); PG8_STAGE(PG8_SB(0, 0), b2, voffB); PG8_STAGE(PG8_SB(0, 1), b2 + hstep, voffB); PG8_STAGE(PG8_SA(0, 0), a2, voffA);
;             PG8_WAIT_V(8); PG8_WAIT_L(0); PG8_BAR; PG8_MMA(1, 0, At, B0); PG8_MMA(1, 1, At, B1); PG8_BAR; PG8_SCHED;
;             PG8_LDB(B0, 1, 0); PG8_LDB(B1, 1, 1); PG8_SCHED; PG8_LDA(At, 1, 0); PG8_STAGE(PG8_SA(0, 1), a2 + hstep, voffA);
;             PG8_WAIT_V(8); PG8_WAIT_L(0); PG8_BAR; PG8_MMA(0, 0, At, B0); PG8_MMA(0, 1, At, B1); PG8_BAR; PG8_SCHED;
;             PG8_LDA(At, 1, 1); PG8_STAGE(PG8_SB(1, 0), b3, voffB); PG8_STAGE(PG8_SB(1, 1), b3 + hstep, voffB); PG8_STAGE(PG8_SA(1, 0), a3, voffA);
;             PG8_WAIT_V(8); PG8_WAIT_L(0); PG8_BAR; PG8_MMA(1, 0, At, B0); PG8_MMA(1, 1, At, B1); PG8_BAR; PG8_SCHED;
	s_mov_b64 s[0:1], 0x180
	s_mov_b32 m0, s87
	v_lshl_add_u64 v[230:231], v[28:29], 0, s[0:1]
	s_add_u32 s26, s18, 0x10180
	ds_read_b128 v[198:201], v242 offset:49152
	ds_read_b128 v[202:205], v242 offset:50176
	ds_read_b128 v[206:209], v242 offset:51200
	ds_read_b128 v[210:213], v242 offset:52224
	ds_read_b128 v[214:217], v242 offset:53248
	ds_read_b128 v[218:221], v242 offset:54272
	ds_read_b128 v[222:225], v242 offset:55296
	ds_read_b128 v[226:229], v242 offset:56320
	global_load_lds_dwordx4 v[230:231], off
	v_lshl_add_u64 v[230:231], v[30:31], 0, s[0:1]
	s_mov_b32 m0, s88
	s_addc_u32 s27, s19, 0
	global_load_lds_dwordx4 v[230:231], off
	v_lshl_add_u64 v[32:33], s[26:27], 0, v[32:33]
	s_mov_b32 m0, s89
	s_nop 0
	global_load_lds_dwordx4 v[32:33], off
	v_lshl_add_u64 v[32:33], s[26:27], 0, v[34:35]
	s_mov_b32 m0, s90
	s_nop 0
	global_load_lds_dwordx4 v[32:33], off
	v_lshl_add_u64 v[32:33], v[22:23], 0, s[0:1]
	s_mov_b32 m0, s73
	s_nop 0
	global_load_lds_dwordx4 v[32:33], off
	v_lshl_add_u64 v[32:33], v[24:25], 0, s[0:1]
	s_mov_b32 m0, s74
	s_nop 0
	global_load_lds_dwordx4 v[32:33], off
	s_waitcnt vmcnt(8)
	s_waitcnt lgkmcnt(0)
	s_barrier
	s_waitcnt lgkmcnt(0)
	v_mfma_f32_16x16x32_bf16 v[32:35], v[40:43], v[198:201], v[166:169]
	v_mfma_f32_16x16x32_bf16 v[166:169], v[150:153], v[198:201], v[170:173]
	v_mfma_f32_16x16x32_bf16 v[170:173], v[40:43], v[206:209], v[174:177]
	v_mfma_f32_16x16x32_bf16 v[174:177], v[150:153], v[206:209], v[178:181]
	v_mfma_f32_16x16x32_bf16 v[178:181], v[40:43], v[214:217], v[182:185]
	v_mfma_f32_16x16x32_bf16 v[40:43], v[40:43], v[222:225], v[60:63]
	v_mfma_f32_16x16x32_bf16 v[32:35], v[48:51], v[202:205], v[32:35]
	v_mfma_f32_16x16x32_bf16 v[170:173], v[48:51], v[210:213], v[170:173]
	v_mfma_f32_16x16x32_bf16 v[178:181], v[48:51], v[218:221], v[178:181]
	v_mfma_f32_16x16x32_bf16 v[40:43], v[48:51], v[226:229], v[40:43]
	v_mfma_f32_16x16x32_bf16 v[48:51], v[150:153], v[222:225], v[52:55]
	v_mfma_f32_16x16x32_bf16 v[182:185], v[150:153], v[214:217], v[186:189]
	v_mfma_f32_16x16x32_bf16 v[48:51], v[154:157], v[226:229], v[48:51]
	v_mfma_f32_16x16x32_bf16 v[166:169], v[154:157], v[202:205], v[166:169]
	v_mfma_f32_16x16x32_bf16 v[174:177], v[154:157], v[210:213], v[174:177]
	v_mfma_f32_16x16x32_bf16 v[182:185], v[154:157], v[218:221], v[182:185]
	v_mfma_f32_16x16x32_bf16 v[52:55], v[158:161], v[198:201], v[56:59]
	v_mfma_f32_16x16x32_bf16 v[56:59], v[190:193], v[198:201], v[64:67]
	v_mfma_f32_16x16x32_bf16 v[60:63], v[158:161], v[206:209], v[96:99]
	v_mfma_f32_16x16x32_bf16 v[64:67], v[190:193], v[206:209], v[138:141]
	v_mfma_f32_16x16x32_bf16 v[96:99], v[158:161], v[214:217], v[142:145]
	v_mfma_f32_16x16x32_bf16 v[44:47], v[158:161], v[222:225], v[44:47]
	v_mfma_f32_16x16x32_bf16 v[36:39], v[190:193], v[222:225], v[36:39]
	v_mfma_f32_16x16x32_bf16 v[52:55], v[162:165], v[202:205], v[52:55]
	v_mfma_f32_16x16x32_bf16 v[56:59], v[194:197], v[202:205], v[56:59]
	v_mfma_f32_16x16x32_bf16 v[60:63], v[162:165], v[210:213], v[60:63]
	v_mfma_f32_16x16x32_bf16 v[64:67], v[194:197], v[210:213], v[64:67]
	v_mfma_f32_16x16x32_bf16 v[96:99], v[162:165], v[218:221], v[96:99]
	v_mfma_f32_16x16x32_bf16 v[138:141], v[190:193], v[214:217], v[146:149]
	v_mfma_f32_16x16x32_bf16 v[44:47], v[162:165], v[226:229], v[44:47]
	v_mfma_f32_16x16x32_bf16 v[36:39], v[194:197], v[226:229], v[36:39]
	v_mfma_f32_16x16x32_bf16 v[138:141], v[194:197], v[218:221], v[138:141]
	s_barrier
	ds_read_b128 v[142:145], v232
	ds_read_b128 v[146:149], v232 offset:1024
	ds_read_b128 v[150:153], v232 offset:2048
	ds_read_b128 v[154:157], v232 offset:3072
	ds_read_b128 v[158:161], v233
	ds_read_b128 v[162:165], v233 offset:1024
	ds_read_b128 v[186:189], v233 offset:2048
	ds_read_b128 v[190:193], v233 offset:3072
	s_add_u32 s0, s4, 0x10180
	s_addc_u32 s1, s5, 0
	s_mov_b32 m0, s79
	v_lshl_add_u64 v[16:17], s[0:1], 0, v[16:17]
	ds_read_b128 v[194:197], v242
	ds_read_b128 v[198:201], v242 offset:1024
	ds_read_b128 v[202:205], v242 offset:2048
	ds_read_b128 v[206:209], v242 offset:3072
	ds_read_b128 v[210:213], v242 offset:4096
	ds_read_b128 v[214:217], v242 offset:5120
	ds_read_b128 v[218:221], v242 offset:6144
	ds_read_b128 v[222:225], v242 offset:7168
	global_load_lds_dwordx4 v[16:17], off
	v_lshl_add_u64 v[16:17], s[0:1], 0, v[18:19]
	s_mov_b32 m0, s80
	s_nop 0
	global_load_lds_dwordx4 v[16:17], off
	s_waitcnt vmcnt(8)
	s_waitcnt lgkmcnt(0)
	s_barrier
	s_waitcnt lgkmcnt(0)
	v_mfma_f32_16x16x32_bf16 v[16:19], v[142:145], v[194:197], v[100:103]
	v_mfma_f32_16x16x32_bf16 v[100:103], v[150:153], v[194:197], v[104:107]
	v_mfma_f32_16x16x32_bf16 v[104:107], v[142:145], v[202:205], v[108:111]
	v_mfma_f32_16x16x32_bf16 v[108:111], v[150:153], v[202:205], v[112:115]
	v_mfma_f32_16x16x32_bf16 v[112:115], v[142:145], v[210:213], v[116:119]
	v_mfma_f32_16x16x32_bf16 v[116:119], v[146:149], v[214:217], v[112:115]
	v_mfma_f32_16x16x32_bf16 v[112:115], v[150:153], v[210:213], v[120:123]
	v_mfma_f32_16x16x32_bf16 v[226:229], v[154:157], v[214:217], v[112:115]
	v_mfma_f32_16x16x32_bf16 v[112:115], v[142:145], v[218:221], v[124:127]
	v_mfma_f32_16x16x32_bf16 v[16:19], v[146:149], v[198:201], v[16:19]
	v_mfma_f32_16x16x32_bf16 v[100:103], v[154:157], v[198:201], v[100:103]
	v_mfma_f32_16x16x32_bf16 v[104:107], v[146:149], v[206:209], v[104:107]
	v_mfma_f32_16x16x32_bf16 v[108:111], v[154:157], v[206:209], v[108:111]
	v_mfma_f32_16x16x32_bf16 v[124:127], v[146:149], v[222:225], v[112:115]
	v_mfma_f32_16x16x32_bf16 v[112:115], v[150:153], v[218:221], v[130:133]
	v_mfma_f32_16x16x32_bf16 v[130:133], v[154:157], v[222:225], v[112:115]
	v_mfma_f32_16x16x32_bf16 v[80:83], v[158:161], v[210:213], v[80:83]
	v_mfma_f32_16x16x32_bf16 v[112:115], v[158:161], v[194:197], v[134:137]
	v_mfma_f32_16x16x32_bf16 v[68:71], v[186:189], v[194:197], v[68:71]
	v_mfma_f32_16x16x32_bf16 v[194:197], v[162:165], v[214:217], v[80:83]
	v_mfma_f32_16x16x32_bf16 v[80:83], v[186:189], v[210:213], v[84:87]
	v_mfma_f32_16x16x32_bf16 v[72:75], v[158:161], v[202:205], v[72:75]
	v_mfma_f32_16x16x32_bf16 v[76:79], v[186:189], v[202:205], v[76:79]
	v_mfma_f32_16x16x32_bf16 v[84:87], v[190:193], v[214:217], v[80:83]
	v_mfma_f32_16x16x32_bf16 v[80:83], v[158:161], v[218:221], v[88:91]
	v_mfma_f32_16x16x32_bf16 v[134:137], v[162:165], v[198:201], v[112:115]
	v_mfma_f32_16x16x32_bf16 v[68:71], v[190:193], v[198:201], v[68:71]
	v_mfma_f32_16x16x32_bf16 v[72:75], v[162:165], v[206:209], v[72:75]
	v_mfma_f32_16x16x32_bf16 v[76:79], v[190:193], v[206:209], v[76:79]
	v_mfma_f32_16x16x32_bf16 v[198:201], v[162:165], v[222:225], v[80:83]
	v_mfma_f32_16x16x32_bf16 v[80:83], v[186:189], v[218:221], v[92:95]
	v_mfma_f32_16x16x32_bf16 v[202:205], v[190:193], v[222:225], v[80:83]
	s_barrier
; #define PG8_STAGE(bufoff, gbase, voff) do { _Pragma("unroll") for (int _i = 0; _i < 2; ++_i) \
;         __builtin_amdgcn_global_load_lds((const unsigned*)((const char*)(gbase) + (voff)[_i]), (PG8_LAS unsigned*)(lds + (bufoff) + ldsw + _i * 8192), 16, 0, 0); } while (0)
; #define PG8_LDA(dst, b, h) do { _Pragma("unroll") for (int m = 0; m < 4; ++m) _Pragma("unroll") for (int k = 0; k < 2; ++k) dst[m][k] = *(const PG8_LAS bf16x8*)(lds + PG8_SA(b, h) + aoff + m * 2048 + k * 1024); } while (0)
; #define PG8_LDB(dst, b, h) do { _Pragma("unroll") for (int n = 0; n < 2; ++n) _Pragma("unroll") for (int k = 0; k < 2; ++k) dst[n][k] = *(const PG8_LAS bf16x8*)(lds + PG8_SB(b, h) + boff + n * 2048 + k * 1024); } while (0)
; #define PG8_MMA(ai, bj, At, Bt) do { __builtin_amdgcn_s_setprio(1); _Pragma("unroll") for (int m = 0; m < 4; ++m) _Pragma("unroll") for (int n = 0; n < 2; ++n) _Pragma("unroll") for (int k = 0; k < 2; ++k) \
;         acc[ai][bj][m][n] = __builtin_amdgcn_mfma_f32_16x16x32_bf16(Bt[n][k], At[m][k], acc[ai][bj][m][n], 0, 0, 0); __builtin_amdgcn_s_setprio(0); } while (0)
; #define PG8_WAIT_V(n) asm volatile("s_waitcnt vmcnt(" #n ")" ::: "memory")
; #define PG8_WAIT_L(n) asm volatile("s_waitcnt lgkmcnt(" #n ")" ::: "memory")
; #define PG8_BAR __builtin_amdgcn_s_barrier()
; #define PG8_SCHED __builtin_amdgcn_sched_barrier(0)
; template <class Epi, class Sched, bool ALIGN_EPI = false, bool SP2 = false>
; __device__ __forceinline__ void gemm_phase(PG8_LAS unsigned char* lds, const Gemm g, const Sched& S, const Epi& E, const int wave_id) {
;     ...
;             PG8_LDB(B0, 0, 0); PG8_LDB(B1, 0, 1); PG8_SCHED; PG8_LDA(At, 0, 0); PG8_STAGE(PG8_SA(1, 1), a1 + hstep, voffA);
;             PG8_WAIT_V(8); PG8_WAIT_L(0); PG8_BAR; PG8_MMA(0, 0, At, B0); PG8_MMA(0, 1, At, B1); PG8_BAR; PG8_SCHED;
;             PG8_LDA(At, 0, 1); PG8_STAGE(PG8_SB(0, 0), b2, voffB); PG8_STAGE(PG8_SB(0, 1), b2 + hstep, voffB); PG8_STAGE(PG8_SA(0, 0), a2, voffA);
;             PG8_WAIT_V(8); PG8_WAIT_L(0); PG8_BAR; PG8_MMA(1, 0, At, B0); PG8_MMA(1, 1, At, B1); PG8_BAR; PG8_SCHED;
;             PG8_LDB(B0, 1, 0); PG8_LDB(B1, 1, 1); PG8_SCHED; PG8_LDA(At, 1, 0); PG8_STAGE(PG8_SA(0, 1), a2 + hstep, voffA);
;             PG8_WAIT_V(8); PG8_WAIT_L(0); PG8_BAR; PG8_MMA(0, 0, At, B0); PG8_MMA(0, 1, At, B1); PG8_BAR; PG8_SCHED;
	s_mov_b32 m0, s81
	s_nop 3
	ds_read_b128 v[80:83], v242 offset:16384
	ds_read_b128 v[88:91], v242 offset:17408
	ds_read_b128 v[92:95], v242 offset:18432
	ds_read_b128 v[112:115], v242 offset:19456
	ds_read_b128 v[120:123], v242 offset:20480
	ds_read_b128 v[206:209], v242 offset:21504
	ds_read_b128 v[210:213], v242 offset:22528
	ds_read_b128 v[214:217], v242 offset:23552
	global_load_lds_dwordx4 v[28:29], off
	s_mov_b32 m0, s82
	s_nop 0
	global_load_lds_dwordx4 v[30:31], off
	s_mov_b32 m0, s83
	s_nop 0
	global_load_lds_dwordx4 v[26:27], off
	s_mov_b32 m0, s84
	s_nop 0
	global_load_lds_dwordx4 v[20:21], off
	s_mov_b32 m0, s33
	s_nop 0
	global_load_lds_dwordx4 v[22:23], off
	s_mov_b32 m0, s63
	s_nop 0
	global_load_lds_dwordx4 v[24:25], off
	s_waitcnt vmcnt(8)
	s_waitcnt lgkmcnt(0)
	s_barrier
	s_waitcnt lgkmcnt(0)
	v_mfma_f32_16x16x32_bf16 v[20:23], v[142:145], v[80:83], v[32:35]
	v_mfma_f32_16x16x32_bf16 v[24:27], v[150:153], v[80:83], v[166:169]
	v_mfma_f32_16x16x32_bf16 v[28:31], v[142:145], v[92:95], v[170:173]
	v_mfma_f32_16x16x32_bf16 v[32:35], v[150:153], v[92:95], v[174:177]
	v_mfma_f32_16x16x32_bf16 v[40:43], v[142:145], v[210:213], v[40:43]
	v_mfma_f32_16x16x32_bf16 v[20:23], v[146:149], v[88:91], v[20:23]
	v_mfma_f32_16x16x32_bf16 v[24:27], v[154:157], v[88:91], v[24:27]
	v_mfma_f32_16x16x32_bf16 v[28:31], v[146:149], v[112:115], v[28:31]
	v_mfma_f32_16x16x32_bf16 v[32:35], v[154:157], v[112:115], v[32:35]
	v_mfma_f32_16x16x32_bf16 v[166:169], v[142:145], v[120:123], v[178:181]
	v_mfma_f32_16x16x32_bf16 v[170:173], v[150:153], v[120:123], v[182:185]
	v_mfma_f32_16x16x32_bf16 v[40:43], v[146:149], v[214:217], v[40:43]
	v_mfma_f32_16x16x32_bf16 v[48:51], v[150:153], v[210:213], v[48:51]
	v_mfma_f32_16x16x32_bf16 v[166:169], v[146:149], v[206:209], v[166:169]
	v_mfma_f32_16x16x32_bf16 v[170:173], v[154:157], v[206:209], v[170:173]
	v_mfma_f32_16x16x32_bf16 v[142:145], v[154:157], v[214:217], v[48:51]
	v_mfma_f32_16x16x32_bf16 v[48:51], v[158:161], v[80:83], v[52:55]
	v_mfma_f32_16x16x32_bf16 v[146:149], v[162:165], v[88:91], v[48:51]
	v_mfma_f32_16x16x32_bf16 v[48:51], v[186:189], v[80:83], v[56:59]
	v_mfma_f32_16x16x32_bf16 v[150:153], v[190:193], v[88:91], v[48:51]
	v_mfma_f32_16x16x32_bf16 v[48:51], v[158:161], v[92:95], v[60:63]
	v_mfma_f32_16x16x32_bf16 v[154:157], v[162:165], v[112:115], v[48:51]
	v_mfma_f32_16x16x32_bf16 v[48:51], v[186:189], v[92:95], v[64:67]
	v_mfma_f32_16x16x32_bf16 v[174:177], v[190:193], v[112:115], v[48:51]
	v_mfma_f32_16x16x32_bf16 v[48:51], v[158:161], v[120:123], v[96:99]
	v_mfma_f32_16x16x32_bf16 v[178:181], v[162:165], v[206:209], v[48:51]
	v_mfma_f32_16x16x32_bf16 v[48:51], v[186:189], v[120:123], v[138:141]
	v_mfma_f32_16x16x32_bf16 v[44:47], v[158:161], v[210:213], v[44:47]
	v_mfma_f32_16x16x32_bf16 v[36:39], v[186:189], v[210:213], v[36:39]
	v_mfma_f32_16x16x32_bf16 v[138:141], v[190:193], v[206:209], v[48:51]
	v_mfma_f32_16x16x32_bf16 v[158:161], v[162:165], v[214:217], v[44:47]
	v_mfma_f32_16x16x32_bf16 v[162:165], v[190:193], v[214:217], v[36:39]
	s_barrier
	ds_read_b128 v[64:67], v234
	ds_read_b128 v[182:185], v234 offset:1024
	ds_read_b128 v[186:189], v234 offset:2048
	ds_read_b128 v[190:193], v234 offset:3072
	ds_read_b128 v[206:209], v235
	ds_read_b128 v[210:213], v235 offset:1024
	ds_read_b128 v[214:217], v235 offset:2048
	ds_read_b128 v[218:221], v235 offset:3072
	s_mov_b32 m0, s69
	ds_read_b128 v[36:39], v242 offset:32768
	ds_read_b128 v[44:47], v242 offset:33792
	ds_read_b128 v[52:55], v242 offset:34816
	ds_read_b128 v[60:63], v242 offset:35840
	ds_read_b128 v[222:225], v242 offset:36864
	ds_read_b128 v[230:233], v242 offset:37888
	ds_read_b128 v[234:237], v242 offset:38912
	ds_read_b128 v[238:241], v242 offset:39936
	global_load_lds_dwordx4 v[12:13], off
	s_mov_b32 m0, s70
	s_nop 0
	global_load_lds_dwordx4 v[14:15], off
	s_waitcnt vmcnt(8)
	s_waitcnt lgkmcnt(0)
	s_barrier
; #define PG8_STAGE(bufoff, gbase, voff) do { _Pragma("unroll") for (int _i = 0; _i < 2; ++_i) \
;         __builtin_amdgcn_global_load_lds((const unsigned*)((const char*)(gbase) + (voff)[_i]), (PG8_LAS unsigned*)(lds + (bufoff) + ldsw + _i * 8192), 16, 0, 0); } while (0)
; #define PG8_LDA(dst, b, h) do { _Pragma("unroll") for (int m = 0; m < 4; ++m) _Pragma("unroll") for (int k = 0; k < 2; ++k) dst[m][k] = *(const PG8_LAS bf16x8*)(lds + PG8_SA(b, h) + aoff + m * 2048 + k * 1024); } while (0)
; #define PG8_MMA(ai, bj, At, Bt) do { __builtin_amdgcn_s_setprio(1); _Pragma("unroll") for (int m = 0; m < 4; ++m) _Pragma("unroll") for (int n = 0; n < 2; ++n) _Pragma("unroll") for (int k = 0; k < 2; ++k) \
;         acc[ai][bj][m][n] = __builtin_amdgcn_mfma_f32_16x16x32_bf16(Bt[n][k], At[m][k], acc[ai][bj][m][n], 0, 0, 0); __builtin_amdgcn_s_setprio(0); } while (0)
; #define PG8_WAIT_V(n) asm volatile("s_waitcnt vmcnt(" #n ")" ::: "memory")
; #define PG8_WAIT_L(n) asm volatile("s_waitcnt lgkmcnt(" #n ")" ::: "memory")
; #define PG8_BAR __builtin_amdgcn_s_barrier()
; #define PG8_SCHED __builtin_amdgcn_sched_barrier(0)
; template <class Epi, class Sched, bool ALIGN_EPI = false, bool SP2 = false>
; __device__ __forceinline__ void gemm_phase(PG8_LAS unsigned char* lds, const Gemm g, const Sched& S, const Epi& E, const int wave_id) {
;     ...
;             PG8_WAIT_V(8); PG8_WAIT_L(0); PG8_BAR; PG8_MMA(0, 0, At, B0); PG8_MMA(0, 1, At, B1); PG8_BAR; PG8_SCHED;
;             PG8_LDA(At, 1, 1); PG8_STAGE(PG8_SB(1, 0), b3, voffB); PG8_STAGE(PG8_SB(1, 1), b3 + hstep, voffB); PG8_STAGE(PG8_SA(1, 0), a3, voffA);
;             PG8_WAIT_V(8); PG8_WAIT_L(0); PG8_BAR; PG8_MMA(1, 0, At, B0); PG8_MMA(1, 1, At, B1); PG8_BAR; PG8_SCHED;
	s_waitcnt lgkmcnt(0)
	v_mfma_f32_16x16x32_bf16 v[12:15], v[64:67], v[36:39], v[16:19]
	v_mfma_f32_16x16x32_bf16 v[120:123], v[182:185], v[44:47], v[12:15]
	v_mfma_f32_16x16x32_bf16 v[12:15], v[186:189], v[36:39], v[100:103]
	v_mfma_f32_16x16x32_bf16 v[112:115], v[190:193], v[44:47], v[12:15]
	v_mfma_f32_16x16x32_bf16 v[12:15], v[64:67], v[52:55], v[104:107]
	v_mfma_f32_16x16x32_bf16 v[104:107], v[182:185], v[60:63], v[12:15]
	v_mfma_f32_16x16x32_bf16 v[12:15], v[186:189], v[52:55], v[108:111]
	v_mfma_f32_16x16x32_bf16 v[96:99], v[190:193], v[60:63], v[12:15]
	v_mfma_f32_16x16x32_bf16 v[12:15], v[64:67], v[222:225], v[116:119]
	v_mfma_f32_16x16x32_bf16 v[88:91], v[182:185], v[230:233], v[12:15]
	v_mfma_f32_16x16x32_bf16 v[12:15], v[186:189], v[222:225], v[226:229]
	v_mfma_f32_16x16x32_bf16 v[80:83], v[190:193], v[230:233], v[12:15]
	v_mfma_f32_16x16x32_bf16 v[12:15], v[64:67], v[234:237], v[124:127]
	v_mfma_f32_16x16x32_bf16 v[56:59], v[182:185], v[238:241], v[12:15]
	v_mfma_f32_16x16x32_bf16 v[12:15], v[186:189], v[234:237], v[130:133]
	v_mfma_f32_16x16x32_bf16 v[48:51], v[190:193], v[238:241], v[12:15]
	v_mfma_f32_16x16x32_bf16 v[12:15], v[206:209], v[36:39], v[134:137]
	v_mfma_f32_16x16x32_bf16 v[124:127], v[210:213], v[44:47], v[12:15]
	v_mfma_f32_16x16x32_bf16 v[12:15], v[214:217], v[36:39], v[68:71]
	v_mfma_f32_16x16x32_bf16 v[116:119], v[218:221], v[44:47], v[12:15]
	v_mfma_f32_16x16x32_bf16 v[12:15], v[206:209], v[52:55], v[72:75]
	v_mfma_f32_16x16x32_bf16 v[108:111], v[210:213], v[60:63], v[12:15]
	v_mfma_f32_16x16x32_bf16 v[12:15], v[214:217], v[52:55], v[76:79]
	v_mfma_f32_16x16x32_bf16 v[100:103], v[218:221], v[60:63], v[12:15]
	v_mfma_f32_16x16x32_bf16 v[12:15], v[206:209], v[222:225], v[194:197]
	v_mfma_f32_16x16x32_bf16 v[92:95], v[210:213], v[230:233], v[12:15]
	v_mfma_f32_16x16x32_bf16 v[12:15], v[214:217], v[222:225], v[84:87]
	v_mfma_f32_16x16x32_bf16 v[84:87], v[218:221], v[230:233], v[12:15]
	v_mfma_f32_16x16x32_bf16 v[12:15], v[206:209], v[234:237], v[198:201]
	v_mfma_f32_16x16x32_bf16 v[60:63], v[210:213], v[238:241], v[12:15]
	v_mfma_f32_16x16x32_bf16 v[12:15], v[214:217], v[234:237], v[202:205]
	v_mfma_f32_16x16x32_bf16 v[52:55], v[218:221], v[238:241], v[12:15]
	s_barrier
	s_mov_b32 m0, s87
	ds_read_b128 v[16:19], v242 offset:49152
	ds_read_b128 v[130:133], v242 offset:50176
	ds_read_b128 v[134:137], v242 offset:51200
	ds_read_b128 v[194:197], v242 offset:52224
	ds_read_b128 v[198:201], v242 offset:53248
	ds_read_b128 v[202:205], v242 offset:54272
	ds_read_b128 v[222:225], v242 offset:55296
	ds_read_b128 v[226:229], v242 offset:56320
	global_load_lds_dwordx4 v[4:5], off
	s_mov_b32 m0, s88
	s_nop 0
	global_load_lds_dwordx4 v[6:7], off
	s_mov_b32 m0, s89
	s_nop 0
	global_load_lds_dwordx4 v[8:9], off
	s_mov_b32 m0, s90
	s_nop 0
	global_load_lds_dwordx4 v[10:11], off
	s_mov_b32 m0, s73
	s_nop 0
	global_load_lds_dwordx4 v[0:1], off
	s_mov_b32 m0, s74
	s_nop 0
	global_load_lds_dwordx4 v[2:3], off
	s_waitcnt vmcnt(8)
	s_waitcnt lgkmcnt(0)
	s_barrier
	s_waitcnt lgkmcnt(0)
	v_mfma_f32_16x16x32_bf16 v[0:3], v[64:67], v[16:19], v[20:23]
	v_mfma_f32_16x16x32_bf16 v[76:79], v[182:185], v[130:133], v[0:3]
	v_mfma_f32_16x16x32_bf16 v[0:3], v[186:189], v[16:19], v[24:27]
	v_mfma_f32_16x16x32_bf16 v[68:71], v[190:193], v[130:133], v[0:3]
	v_mfma_f32_16x16x32_bf16 v[0:3], v[64:67], v[134:137], v[28:31]
	v_mfma_f32_16x16x32_bf16 v[44:47], v[182:185], v[194:197], v[0:3]
	v_mfma_f32_16x16x32_bf16 v[0:3], v[186:189], v[134:137], v[32:35]
	v_mfma_f32_16x16x32_bf16 v[36:39], v[190:193], v[194:197], v[0:3]
	v_mfma_f32_16x16x32_bf16 v[0:3], v[64:67], v[198:201], v[166:169]
	v_mfma_f32_16x16x32_bf16 v[28:31], v[182:185], v[202:205], v[0:3]
	v_mfma_f32_16x16x32_bf16 v[0:3], v[186:189], v[198:201], v[170:173]
	v_mfma_f32_16x16x32_bf16 v[20:23], v[190:193], v[202:205], v[0:3]
	v_mfma_f32_16x16x32_bf16 v[0:3], v[64:67], v[222:225], v[40:43]
	v_mfma_f32_16x16x32_bf16 v[12:15], v[182:185], v[226:229], v[0:3]
	v_mfma_f32_16x16x32_bf16 v[0:3], v[186:189], v[222:225], v[142:145]
	v_mfma_f32_16x16x32_bf16 v[4:7], v[190:193], v[226:229], v[0:3]
	v_mfma_f32_16x16x32_bf16 v[0:3], v[206:209], v[16:19], v[146:149]
	v_mfma_f32_16x16x32_bf16 v[72:75], v[210:213], v[130:133], v[0:3]
	v_mfma_f32_16x16x32_bf16 v[0:3], v[214:217], v[16:19], v[150:153]
	v_mfma_f32_16x16x32_bf16 v[64:67], v[218:221], v[130:133], v[0:3]
	v_mfma_f32_16x16x32_bf16 v[0:3], v[206:209], v[134:137], v[154:157]
	v_mfma_f32_16x16x32_bf16 v[40:43], v[210:213], v[194:197], v[0:3]
	v_mfma_f32_16x16x32_bf16 v[0:3], v[214:217], v[134:137], v[174:177]
	v_mfma_f32_16x16x32_bf16 v[32:35], v[218:221], v[194:197], v[0:3]
	v_mfma_f32_16x16x32_bf16 v[0:3], v[206:209], v[198:201], v[178:181]
	v_mfma_f32_16x16x32_bf16 v[24:27], v[210:213], v[202:205], v[0:3]
	v_mfma_f32_16x16x32_bf16 v[0:3], v[214:217], v[198:201], v[138:141]
	v_mfma_f32_16x16x32_bf16 v[16:19], v[218:221], v[202:205], v[0:3]
	v_mfma_f32_16x16x32_bf16 v[0:3], v[206:209], v[222:225], v[158:161]
	v_mfma_f32_16x16x32_bf16 v[8:11], v[210:213], v[226:229], v[0:3]
	v_mfma_f32_16x16x32_bf16 v[0:3], v[214:217], v[222:225], v[162:165]
	v_mfma_f32_16x16x32_bf16 v[0:3], v[218:221], v[226:229], v[0:3]
	s_barrier
	v_cndmask_b32_e64 v130, 0, 1, s[16:17]
	v_cmp_ne_u32_e64 s[4:5], 1, v130
	s_andn2_b64 vcc, exec, s[16:17]
	s_cbranch_vccnz .LBB0_486
	s_barrier

; #define PG8_STAGE(bufoff, gbase, voff) do { _Pragma("unroll") for (int _i = 0; _i < 2; ++_i) \
;         __builtin_amdgcn_global_load_lds((const unsigned*)((const char*)(gbase) + (voff)[_i]), (PG8_LAS unsigned*)(lds + (bufoff) + ldsw + _i * 8192), 16, 0, 0); } while (0)
; #define PG8_LDA(dst, b, h) do { _Pragma("unroll") for (int m = 0; m < 4; ++m) _Pragma("unroll") for (int k = 0; k < 2; ++k) dst[m][k] = *(const PG8_LAS bf16x8*)(lds + PG8_SA(b, h) + aoff + m * 2048 + k * 1024); } while (0)
; #define PG8_LDB(dst, b, h) do { _Pragma("unroll") for (int n = 0; n < 2; ++n) _Pragma("unroll") for (int k = 0; k < 2; ++k) dst[n][k] = *(const PG8_LAS bf16x8*)(lds + PG8_SB(b, h) + boff + n * 2048 + k * 1024); } while (0)
; #define PG8_MMA(ai, bj, At, Bt) do { __builtin_amdgcn_s_setprio(1); _Pragma("unroll") for (int m = 0; m < 4; ++m) _Pragma("unroll") for (int n = 0; n < 2; ++n) _Pragma("unroll") for (int k = 0; k < 2; ++k) \
;         acc[ai][bj][m][n] = __builtin_amdgcn_mfma_f32_16x16x32_bf16(Bt[n][k], At[m][k], acc[ai][bj][m][n], 0, 0, 0); __builtin_amdgcn_s_setprio(0); } while (0)
; #define PG8_WAIT_V(n) asm volatile("s_waitcnt vmcnt(" #n ")" ::: "memory")
; #define PG8_WAIT_L(n) asm volatile("s_waitcnt lgkmcnt(" #n ")" ::: "memory")
; #define PG8_BAR __builtin_amdgcn_s_barrier()
; #define PG8_SCHED __builtin_amdgcn_sched_barrier(0)
; template <class Epi, class Sched, bool ALIGN_EPI = false, bool SP2 = false>
; __device__ __forceinline__ void gemm_phase(PG8_LAS unsigned char* lds, const Gemm g, const Sched& S, const Epi& E, const int wave_id) {
;     ...
;             PG8_LDB(B0, 0, 0); PG8_LDB(B1, 0, 1); PG8_SCHED; PG8_LDA(At, 0, 0); PG8_STAGE(PG8_SA(1, 1), a1 + hstep, voffA);
;             PG8_WAIT_V(8); PG8_WAIT_L(0); PG8_BAR; PG8_MMA(0, 0, At, B0); PG8_MMA(0, 1, At, B1); PG8_BAR; PG8_SCHED;
;             PG8_LDA(At, 0, 1); PG8_STAGE(PG8_SB(0, 0), b2, voffB); PG8_STAGE(PG8_SB(0, 1), b2 + hstep, voffB); PG8_STAGE(PG8_SA(0, 0), a2, voffA);
;             PG8_WAIT_V(8); PG8_WAIT_L(0); PG8_BAR; PG8_MMA(1, 0, At, B0); PG8_MMA(1, 1, At, B1); PG8_BAR; PG8_SCHED;
.LBB0_522:
	ds_read_b128 v[132:135], v193
	ds_read_b128 v[136:139], v193 offset:1024
	ds_read_b128 v[140:143], v193 offset:2048
	ds_read_b128 v[144:147], v193 offset:3072
	ds_read_b128 v[148:151], v197
	ds_read_b128 v[152:155], v197 offset:1024
	ds_read_b128 v[156:159], v197 offset:2048
	ds_read_b128 v[160:163], v197 offset:3072
	s_add_u32 s50, s46, s48
	s_addc_u32 s51, s47, s49
	s_add_u32 s50, s50, 0x100
	s_addc_u32 s51, s51, 0
	s_add_u32 s92, s13, s48
	s_addc_u32 s93, s67, s49
	s_cmpk_eq_i32 s48, 0xf00
	s_cselect_b32 s55, vcc_lo, s51
	s_cselect_b32 s54, vcc_hi, s50
	s_cselect_b32 s51, s39, s93
	s_cselect_b32 s50, s38, s92
	s_mov_b32 m0, s79
	v_lshl_add_u64 v[186:187], v[128:129], 0, s[48:49]
	ds_read_b128 v[164:167], v201
	ds_read_b128 v[210:213], v201 offset:1024
	ds_read_b128 v[214:217], v201 offset:2048
	ds_read_b128 v[218:221], v201 offset:3072
	ds_read_b128 v[222:225], v201 offset:4096
	ds_read_b128 v[226:229], v201 offset:5120
	ds_read_b128 v[230:233], v201 offset:6144
	ds_read_b128 v[234:237], v201 offset:7168
	global_load_lds_dwordx4 v[186:187], off
	v_lshl_add_u64 v[186:187], v[130:131], 0, s[48:49]
	s_mov_b32 m0, s80
	s_nop 0
	global_load_lds_dwordx4 v[186:187], off
	s_waitcnt vmcnt(8)
	s_waitcnt lgkmcnt(0)
	s_barrier
	s_waitcnt lgkmcnt(0)
	v_mfma_f32_16x16x32_bf16 v[124:127], v[132:135], v[164:167], v[124:127]
	v_mfma_f32_16x16x32_bf16 v[120:123], v[140:143], v[164:167], v[120:123]
	v_mfma_f32_16x16x32_bf16 v[108:111], v[132:135], v[214:217], v[108:111]
	v_mfma_f32_16x16x32_bf16 v[104:107], v[140:143], v[214:217], v[104:107]
	v_mfma_f32_16x16x32_bf16 v[92:95], v[132:135], v[222:225], v[92:95]
	v_mfma_f32_16x16x32_bf16 v[88:91], v[140:143], v[222:225], v[88:91]
	v_mfma_f32_16x16x32_bf16 v[76:79], v[132:135], v[230:233], v[76:79]
	v_mfma_f32_16x16x32_bf16 v[72:75], v[140:143], v[230:233], v[72:75]
	v_mfma_f32_16x16x32_bf16 v[124:127], v[136:139], v[210:213], v[124:127]
	v_mfma_f32_16x16x32_bf16 v[120:123], v[144:147], v[210:213], v[120:123]
	v_mfma_f32_16x16x32_bf16 v[108:111], v[136:139], v[218:221], v[108:111]
	v_mfma_f32_16x16x32_bf16 v[104:107], v[144:147], v[218:221], v[104:107]
	v_mfma_f32_16x16x32_bf16 v[92:95], v[136:139], v[226:229], v[92:95]
	v_mfma_f32_16x16x32_bf16 v[88:91], v[144:147], v[226:229], v[88:91]
	v_mfma_f32_16x16x32_bf16 v[76:79], v[136:139], v[234:237], v[76:79]
	v_mfma_f32_16x16x32_bf16 v[72:75], v[144:147], v[234:237], v[72:75]
	v_mfma_f32_16x16x32_bf16 v[116:119], v[148:151], v[164:167], v[116:119]
	v_mfma_f32_16x16x32_bf16 v[112:115], v[156:159], v[164:167], v[112:115]
	v_mfma_f32_16x16x32_bf16 v[100:103], v[148:151], v[214:217], v[100:103]
	v_mfma_f32_16x16x32_bf16 v[96:99], v[156:159], v[214:217], v[96:99]
	v_mfma_f32_16x16x32_bf16 v[84:87], v[148:151], v[222:225], v[84:87]
	v_mfma_f32_16x16x32_bf16 v[80:83], v[156:159], v[222:225], v[80:83]
	v_mfma_f32_16x16x32_bf16 v[68:71], v[148:151], v[230:233], v[68:71]
	v_mfma_f32_16x16x32_bf16 v[64:67], v[156:159], v[230:233], v[64:67]
	v_mfma_f32_16x16x32_bf16 v[116:119], v[152:155], v[210:213], v[116:119]
	v_mfma_f32_16x16x32_bf16 v[112:115], v[160:163], v[210:213], v[112:115]
	v_mfma_f32_16x16x32_bf16 v[100:103], v[152:155], v[218:221], v[100:103]
	v_mfma_f32_16x16x32_bf16 v[96:99], v[160:163], v[218:221], v[96:99]
	v_mfma_f32_16x16x32_bf16 v[84:87], v[152:155], v[226:229], v[84:87]
	v_mfma_f32_16x16x32_bf16 v[80:83], v[160:163], v[226:229], v[80:83]
	v_mfma_f32_16x16x32_bf16 v[68:71], v[152:155], v[234:237], v[68:71]
	v_mfma_f32_16x16x32_bf16 v[64:67], v[160:163], v[234:237], v[64:67]
	s_barrier
	s_mov_b32 m0, s81
	v_lshl_add_u64 v[186:187], s[50:51], 0, v[168:169]
	s_add_u32 s92, s50, 0x80000
	ds_read_b128 v[164:167], v201 offset:16384
	ds_read_b128 v[210:213], v201 offset:17408
	ds_read_b128 v[214:217], v201 offset:18432
	ds_read_b128 v[218:221], v201 offset:19456
	ds_read_b128 v[222:225], v201 offset:20480
	ds_read_b128 v[226:229], v201 offset:21504
	ds_read_b128 v[230:233], v201 offset:22528
	ds_read_b128 v[234:237], v201 offset:23552
	global_load_lds_dwordx4 v[186:187], off
	v_lshl_add_u64 v[190:191], s[50:51], 0, v[174:175]
	s_mov_b32 m0, s82
	s_addc_u32 s93, s51, 0
	global_load_lds_dwordx4 v[190:191], off
	v_lshl_add_u64 v[194:195], s[92:93], 0, v[168:169]
	s_mov_b32 m0, s83
	v_lshl_add_u64 v[198:199], s[54:55], 0, v[172:173]
	global_load_lds_dwordx4 v[194:195], off
	v_lshl_add_u64 v[194:195], s[92:93], 0, v[174:175]
	s_mov_b32 m0, s84
	s_nop 0
	global_load_lds_dwordx4 v[194:195], off
	v_lshl_add_u64 v[194:195], s[54:55], 0, v[170:171]
	s_mov_b32 m0, s33
	s_nop 0
	global_load_lds_dwordx4 v[194:195], off
	s_mov_b32 m0, s63
	s_nop 0
	global_load_lds_dwordx4 v[198:199], off
	s_waitcnt vmcnt(8)
	s_waitcnt lgkmcnt(0)
	s_barrier
; #define PG8_STAGE(bufoff, gbase, voff) do { _Pragma("unroll") for (int _i = 0; _i < 2; ++_i) \
;         __builtin_amdgcn_global_load_lds((const unsigned*)((const char*)(gbase) + (voff)[_i]), (PG8_LAS unsigned*)(lds + (bufoff) + ldsw + _i * 8192), 16, 0, 0); } while (0)
; #define PG8_LDA(dst, b, h) do { _Pragma("unroll") for (int m = 0; m < 4; ++m) _Pragma("unroll") for (int k = 0; k < 2; ++k) dst[m][k] = *(const PG8_LAS bf16x8*)(lds + PG8_SA(b, h) + aoff + m * 2048 + k * 1024); } while (0)
; #define PG8_LDB(dst, b, h) do { _Pragma("unroll") for (int n = 0; n < 2; ++n) _Pragma("unroll") for (int k = 0; k < 2; ++k) dst[n][k] = *(const PG8_LAS bf16x8*)(lds + PG8_SB(b, h) + boff + n * 2048 + k * 1024); } while (0)
; #define PG8_MMA(ai, bj, At, Bt) do { __builtin_amdgcn_s_setprio(1); _Pragma("unroll") for (int m = 0; m < 4; ++m) _Pragma("unroll") for (int n = 0; n < 2; ++n) _Pragma("unroll") for (int k = 0; k < 2; ++k) \
;         acc[ai][bj][m][n] = __builtin_amdgcn_mfma_f32_16x16x32_bf16(Bt[n][k], At[m][k], acc[ai][bj][m][n], 0, 0, 0); __builtin_amdgcn_s_setprio(0); } while (0)
; #define PG8_WAIT_V(n) asm volatile("s_waitcnt vmcnt(" #n ")" ::: "memory")
; #define PG8_WAIT_L(n) asm volatile("s_waitcnt lgkmcnt(" #n ")" ::: "memory")
; #define PG8_BAR __builtin_amdgcn_s_barrier()
; #define PG8_SCHED __builtin_amdgcn_sched_barrier(0)
; template <class Epi, class Sched, bool ALIGN_EPI = false, bool SP2 = false>
; __device__ __forceinline__ void gemm_phase(PG8_LAS unsigned char* lds, const Gemm g, const Sched& S, const Epi& E, const int wave_id) {
;     ...
;             PG8_WAIT_V(8); PG8_WAIT_L(0); PG8_BAR; PG8_MMA(1, 0, At, B0); PG8_MMA(1, 1, At, B1); PG8_BAR; PG8_SCHED;
;             PG8_LDB(B0, 1, 0); PG8_LDB(B1, 1, 1); PG8_SCHED; PG8_LDA(At, 1, 0); PG8_STAGE(PG8_SA(0, 1), a2 + hstep, voffA);
;             PG8_WAIT_V(8); PG8_WAIT_L(0); PG8_BAR; PG8_MMA(0, 0, At, B0); PG8_MMA(0, 1, At, B1); PG8_BAR; PG8_SCHED;
	s_waitcnt lgkmcnt(0)
	v_mfma_f32_16x16x32_bf16 v[60:63], v[132:135], v[164:167], v[60:63]
	v_mfma_f32_16x16x32_bf16 v[56:59], v[140:143], v[164:167], v[56:59]
	v_mfma_f32_16x16x32_bf16 v[44:47], v[132:135], v[214:217], v[44:47]
	v_mfma_f32_16x16x32_bf16 v[40:43], v[140:143], v[214:217], v[40:43]
	v_mfma_f32_16x16x32_bf16 v[28:31], v[132:135], v[222:225], v[28:31]
	v_mfma_f32_16x16x32_bf16 v[24:27], v[140:143], v[222:225], v[24:27]
	v_mfma_f32_16x16x32_bf16 v[12:15], v[132:135], v[230:233], v[12:15]
	v_mfma_f32_16x16x32_bf16 v[8:11], v[140:143], v[230:233], v[8:11]
	v_mfma_f32_16x16x32_bf16 v[60:63], v[136:139], v[210:213], v[60:63]
	v_mfma_f32_16x16x32_bf16 v[56:59], v[144:147], v[210:213], v[56:59]
	v_mfma_f32_16x16x32_bf16 v[44:47], v[136:139], v[218:221], v[44:47]
	v_mfma_f32_16x16x32_bf16 v[40:43], v[144:147], v[218:221], v[40:43]
	v_mfma_f32_16x16x32_bf16 v[28:31], v[136:139], v[226:229], v[28:31]
	v_mfma_f32_16x16x32_bf16 v[24:27], v[144:147], v[226:229], v[24:27]
	v_mfma_f32_16x16x32_bf16 v[12:15], v[136:139], v[234:237], v[12:15]
	v_mfma_f32_16x16x32_bf16 v[8:11], v[144:147], v[234:237], v[8:11]
	v_mfma_f32_16x16x32_bf16 v[52:55], v[148:151], v[164:167], v[52:55]
	v_mfma_f32_16x16x32_bf16 v[48:51], v[156:159], v[164:167], v[48:51]
	v_mfma_f32_16x16x32_bf16 v[36:39], v[148:151], v[214:217], v[36:39]
	v_mfma_f32_16x16x32_bf16 v[32:35], v[156:159], v[214:217], v[32:35]
	v_mfma_f32_16x16x32_bf16 v[20:23], v[148:151], v[222:225], v[20:23]
	v_mfma_f32_16x16x32_bf16 v[16:19], v[156:159], v[222:225], v[16:19]
	v_mfma_f32_16x16x32_bf16 v[4:7], v[148:151], v[230:233], v[4:7]
	v_mfma_f32_16x16x32_bf16 v[0:3], v[156:159], v[230:233], v[0:3]
	v_mfma_f32_16x16x32_bf16 v[52:55], v[152:155], v[210:213], v[52:55]
	v_mfma_f32_16x16x32_bf16 v[48:51], v[160:163], v[210:213], v[48:51]
	v_mfma_f32_16x16x32_bf16 v[36:39], v[152:155], v[218:221], v[36:39]
	v_mfma_f32_16x16x32_bf16 v[32:35], v[160:163], v[218:221], v[32:35]
	v_mfma_f32_16x16x32_bf16 v[20:23], v[152:155], v[226:229], v[20:23]
	v_mfma_f32_16x16x32_bf16 v[16:19], v[160:163], v[226:229], v[16:19]
	v_mfma_f32_16x16x32_bf16 v[4:7], v[152:155], v[234:237], v[4:7]
	v_mfma_f32_16x16x32_bf16 v[0:3], v[160:163], v[234:237], v[0:3]
	s_barrier
	ds_read_b128 v[132:135], v205
	ds_read_b128 v[136:139], v205 offset:1024
	ds_read_b128 v[140:143], v205 offset:2048
	ds_read_b128 v[144:147], v205 offset:3072
	ds_read_b128 v[148:151], v208
	ds_read_b128 v[152:155], v208 offset:1024
	ds_read_b128 v[156:159], v208 offset:2048
	ds_read_b128 v[160:163], v208 offset:3072
	s_add_u32 s54, s54, 0x80000
	s_addc_u32 s55, s55, 0
	s_mov_b32 m0, s69
	v_lshl_add_u64 v[202:203], s[54:55], 0, v[170:171]
	ds_read_b128 v[164:167], v201 offset:32768
	ds_read_b128 v[210:213], v201 offset:33792
	ds_read_b128 v[214:217], v201 offset:34816
	ds_read_b128 v[218:221], v201 offset:35840
	ds_read_b128 v[222:225], v201 offset:36864
	ds_read_b128 v[226:229], v201 offset:37888
	ds_read_b128 v[230:233], v201 offset:38912
	ds_read_b128 v[234:237], v201 offset:39936
	global_load_lds_dwordx4 v[202:203], off
	v_lshl_add_u64 v[202:203], s[54:55], 0, v[172:173]
	s_mov_b32 m0, s70
	s_nop 0
	global_load_lds_dwordx4 v[202:203], off
	s_waitcnt vmcnt(8)
	s_waitcnt lgkmcnt(0)
	s_barrier
	s_waitcnt lgkmcnt(0)
	v_mfma_f32_16x16x32_bf16 v[124:127], v[132:135], v[164:167], v[124:127]
	v_mfma_f32_16x16x32_bf16 v[120:123], v[140:143], v[164:167], v[120:123]
	v_mfma_f32_16x16x32_bf16 v[108:111], v[132:135], v[214:217], v[108:111]
	v_mfma_f32_16x16x32_bf16 v[104:107], v[140:143], v[214:217], v[104:107]
	v_mfma_f32_16x16x32_bf16 v[92:95], v[132:135], v[222:225], v[92:95]
	v_mfma_f32_16x16x32_bf16 v[88:91], v[140:143], v[222:225], v[88:91]
	v_mfma_f32_16x16x32_bf16 v[76:79], v[132:135], v[230:233], v[76:79]
	v_mfma_f32_16x16x32_bf16 v[72:75], v[140:143], v[230:233], v[72:75]
	v_mfma_f32_16x16x32_bf16 v[124:127], v[136:139], v[210:213], v[124:127]
	v_mfma_f32_16x16x32_bf16 v[120:123], v[144:147], v[210:213], v[120:123]
	v_mfma_f32_16x16x32_bf16 v[108:111], v[136:139], v[218:221], v[108:111]
	v_mfma_f32_16x16x32_bf16 v[104:107], v[144:147], v[218:221], v[104:107]
	v_mfma_f32_16x16x32_bf16 v[92:95], v[136:139], v[226:229], v[92:95]
	v_mfma_f32_16x16x32_bf16 v[88:91], v[144:147], v[226:229], v[88:91]
	v_mfma_f32_16x16x32_bf16 v[76:79], v[136:139], v[234:237], v[76:79]
	v_mfma_f32_16x16x32_bf16 v[72:75], v[144:147], v[234:237], v[72:75]
	v_mfma_f32_16x16x32_bf16 v[116:119], v[148:151], v[164:167], v[116:119]
	v_mfma_f32_16x16x32_bf16 v[112:115], v[156:159], v[164:167], v[112:115]
	v_mfma_f32_16x16x32_bf16 v[100:103], v[148:151], v[214:217], v[100:103]
	v_mfma_f32_16x16x32_bf16 v[96:99], v[156:159], v[214:217], v[96:99]
	v_mfma_f32_16x16x32_bf16 v[84:87], v[148:151], v[222:225], v[84:87]
	v_mfma_f32_16x16x32_bf16 v[80:83], v[156:159], v[222:225], v[80:83]
	v_mfma_f32_16x16x32_bf16 v[68:71], v[148:151], v[230:233], v[68:71]
	v_mfma_f32_16x16x32_bf16 v[64:67], v[156:159], v[230:233], v[64:67]
	v_mfma_f32_16x16x32_bf16 v[116:119], v[152:155], v[210:213], v[116:119]
	v_mfma_f32_16x16x32_bf16 v[112:115], v[160:163], v[210:213], v[112:115]
	v_mfma_f32_16x16x32_bf16 v[100:103], v[152:155], v[218:221], v[100:103]
	v_mfma_f32_16x16x32_bf16 v[96:99], v[160:163], v[218:221], v[96:99]
	v_mfma_f32_16x16x32_bf16 v[84:87], v[152:155], v[226:229], v[84:87]
	v_mfma_f32_16x16x32_bf16 v[80:83], v[160:163], v[226:229], v[80:83]
	v_mfma_f32_16x16x32_bf16 v[68:71], v[152:155], v[234:237], v[68:71]
	v_mfma_f32_16x16x32_bf16 v[64:67], v[160:163], v[234:237], v[64:67]
	s_barrier
; #define PG8_STAGE(bufoff, gbase, voff) do { _Pragma("unroll") for (int _i = 0; _i < 2; ++_i) \
;         __builtin_amdgcn_global_load_lds((const unsigned*)((const char*)(gbase) + (voff)[_i]), (PG8_LAS unsigned*)(lds + (bufoff) + ldsw + _i * 8192), 16, 0, 0); } while (0)
; #define PG8_LDA(dst, b, h) do { _Pragma("unroll") for (int m = 0; m < 4; ++m) _Pragma("unroll") for (int k = 0; k < 2; ++k) dst[m][k] = *(const PG8_LAS bf16x8*)(lds + PG8_SA(b, h) + aoff + m * 2048 + k * 1024); } while (0)
; #define PG8_MMA(ai, bj, At, Bt) do { __builtin_amdgcn_s_setprio(1); _Pragma("unroll") for (int m = 0; m < 4; ++m) _Pragma("unroll") for (int n = 0; n < 2; ++n) _Pragma("unroll") for (int k = 0; k < 2; ++k) \
;         acc[ai][bj][m][n] = __builtin_amdgcn_mfma_f32_16x16x32_bf16(Bt[n][k], At[m][k], acc[ai][bj][m][n], 0, 0, 0); __builtin_amdgcn_s_setprio(0); } while (0)
; #define PG8_WAIT_V(n) asm volatile("s_waitcnt vmcnt(" #n ")" ::: "memory")
; #define PG8_WAIT_L(n) asm volatile("s_waitcnt lgkmcnt(" #n ")" ::: "memory")
; #define PG8_BAR __builtin_amdgcn_s_barrier()
; #define PG8_SCHED __builtin_amdgcn_sched_barrier(0)
; template <class Epi, class Sched, bool ALIGN_EPI = false, bool SP2 = false>
; __device__ __forceinline__ void gemm_phase(PG8_LAS unsigned char* lds, const Gemm g, const Sched& S, const Epi& E, const int wave_id) {
;     ...
;         for (int t = 0; t < nt; t += 2) {
;     ...
;             PG8_LDA(At, 1, 1); PG8_STAGE(PG8_SB(1, 0), b3, voffB); PG8_STAGE(PG8_SB(1, 1), b3 + hstep, voffB); PG8_STAGE(PG8_SA(1, 0), a3, voffA);
;             PG8_WAIT_V(8); PG8_WAIT_L(0); PG8_BAR; PG8_MMA(1, 0, At, B0); PG8_MMA(1, 1, At, B1); PG8_BAR; PG8_SCHED;
	s_mov_b32 m0, s87
	v_lshl_add_u64 v[186:187], v[186:187], 0, s[44:45]
	s_add_u32 s50, s50, 0x80080
	ds_read_b128 v[164:167], v201 offset:49152
	ds_read_b128 v[210:213], v201 offset:50176
	ds_read_b128 v[214:217], v201 offset:51200
	ds_read_b128 v[218:221], v201 offset:52224
	ds_read_b128 v[222:225], v201 offset:53248
	ds_read_b128 v[226:229], v201 offset:54272
	ds_read_b128 v[230:233], v201 offset:55296
	ds_read_b128 v[234:237], v201 offset:56320
	global_load_lds_dwordx4 v[186:187], off
	v_lshl_add_u64 v[186:187], v[190:191], 0, s[44:45]
	s_mov_b32 m0, s88
	s_addc_u32 s51, s51, 0
	global_load_lds_dwordx4 v[186:187], off
	v_lshl_add_u64 v[186:187], s[50:51], 0, v[168:169]
	s_mov_b32 m0, s89
	s_nop 0
	global_load_lds_dwordx4 v[186:187], off
	v_lshl_add_u64 v[186:187], s[50:51], 0, v[174:175]
	s_mov_b32 m0, s90
	s_nop 0
	global_load_lds_dwordx4 v[186:187], off
	v_lshl_add_u64 v[186:187], v[194:195], 0, s[44:45]
	s_mov_b32 m0, s73
	s_nop 0
	global_load_lds_dwordx4 v[186:187], off
	v_lshl_add_u64 v[186:187], v[198:199], 0, s[44:45]
	s_mov_b32 m0, s74
	s_nop 0
	global_load_lds_dwordx4 v[186:187], off
	s_waitcnt vmcnt(8)
	s_waitcnt lgkmcnt(0)
	s_barrier
	s_waitcnt lgkmcnt(0)
	v_mfma_f32_16x16x32_bf16 v[60:63], v[132:135], v[164:167], v[60:63]
	v_mfma_f32_16x16x32_bf16 v[56:59], v[140:143], v[164:167], v[56:59]
	v_mfma_f32_16x16x32_bf16 v[44:47], v[132:135], v[214:217], v[44:47]
	v_mfma_f32_16x16x32_bf16 v[40:43], v[140:143], v[214:217], v[40:43]
	v_mfma_f32_16x16x32_bf16 v[28:31], v[132:135], v[222:225], v[28:31]
	v_mfma_f32_16x16x32_bf16 v[24:27], v[140:143], v[222:225], v[24:27]
	v_mfma_f32_16x16x32_bf16 v[12:15], v[132:135], v[230:233], v[12:15]
	v_mfma_f32_16x16x32_bf16 v[8:11], v[140:143], v[230:233], v[8:11]
	v_mfma_f32_16x16x32_bf16 v[60:63], v[136:139], v[210:213], v[60:63]
	v_mfma_f32_16x16x32_bf16 v[56:59], v[144:147], v[210:213], v[56:59]
	v_mfma_f32_16x16x32_bf16 v[44:47], v[136:139], v[218:221], v[44:47]
	v_mfma_f32_16x16x32_bf16 v[40:43], v[144:147], v[218:221], v[40:43]
	v_mfma_f32_16x16x32_bf16 v[28:31], v[136:139], v[226:229], v[28:31]
	v_mfma_f32_16x16x32_bf16 v[24:27], v[144:147], v[226:229], v[24:27]
	v_mfma_f32_16x16x32_bf16 v[12:15], v[136:139], v[234:237], v[12:15]
	v_mfma_f32_16x16x32_bf16 v[8:11], v[144:147], v[234:237], v[8:11]
	v_mfma_f32_16x16x32_bf16 v[52:55], v[148:151], v[164:167], v[52:55]
	v_mfma_f32_16x16x32_bf16 v[48:51], v[156:159], v[164:167], v[48:51]
	v_mfma_f32_16x16x32_bf16 v[36:39], v[148:151], v[214:217], v[36:39]
	v_mfma_f32_16x16x32_bf16 v[32:35], v[156:159], v[214:217], v[32:35]
	v_mfma_f32_16x16x32_bf16 v[20:23], v[148:151], v[222:225], v[20:23]
	v_mfma_f32_16x16x32_bf16 v[16:19], v[156:159], v[222:225], v[16:19]
	v_mfma_f32_16x16x32_bf16 v[4:7], v[148:151], v[230:233], v[4:7]
	v_mfma_f32_16x16x32_bf16 v[0:3], v[156:159], v[230:233], v[0:3]
	v_mfma_f32_16x16x32_bf16 v[52:55], v[152:155], v[210:213], v[52:55]
	v_mfma_f32_16x16x32_bf16 v[48:51], v[160:163], v[210:213], v[48:51]
	v_mfma_f32_16x16x32_bf16 v[36:39], v[152:155], v[218:221], v[36:39]
	v_mfma_f32_16x16x32_bf16 v[32:35], v[160:163], v[218:221], v[32:35]
	v_mfma_f32_16x16x32_bf16 v[20:23], v[152:155], v[226:229], v[20:23]
	v_mfma_f32_16x16x32_bf16 v[16:19], v[160:163], v[226:229], v[16:19]
	v_mfma_f32_16x16x32_bf16 v[4:7], v[152:155], v[234:237], v[4:7]
	v_mfma_f32_16x16x32_bf16 v[0:3], v[160:163], v[234:237], v[0:3]
	s_barrier
	s_add_i32 s58, s58, 2
	s_add_u32 s48, s48, 0x100
	s_addc_u32 s49, s49, 0
	s_cmp_gt_u32 s58, 29
	s_cbranch_scc0 .LBB0_522
	s_and_b64 vcc, exec, s[16:17]
	s_cbranch_vccz .LBB0_525
	s_barrier

;     __device__ __forceinline__ bool next(int i, Unit& u) const { if (i != 0) return false; return base.next(which, u); }
;     __device__ __forceinline__ bool next(int i, Unit& u) const { if (i >= nrd) return false; u.pm = (rd0 + i) * 16 + 4 * xl + (j >> 3); u.pn = j & 7; return true; }
; template <class Epi, class Sched, bool ALIGN_EPI = false, bool SP2 = false>
; __device__ __forceinline__ void gemm_phase(PG8_LAS unsigned char* lds, const Gemm g, const Sched& S, const Epi& E, const int wave_id) {
;     ...
;         PG8_WAIT_V(2); PG8_BAR;
;         PG8_STAGE(PG8_SB(1, 0), cB + kstep, voffB); PG8_STAGE(PG8_SA(1, 0), cA + kstep, voffA); PG8_STAGE(PG8_SB(1, 1), cB + hstep + kstep, voffB);
;         PG8_WAIT_V(6); PG8_BAR;
;     } else {
;         PG8_STAGE(PG8_SB(0, 0), cB, voffB); PG8_STAGE(PG8_SA(0, 0), cA, voffA); PG8_STAGE(PG8_SB(0, 1), cB + hstep, voffB); PG8_STAGE(PG8_SA(0, 1), cA + hstep, voffA);
;         if (wr == 1) PG8_BAR;
;         PG8_WAIT_V(4); PG8_BAR;
;         PG8_STAGE(PG8_SB(1, 0), cB + kstep, voffB); PG8_STAGE(PG8_SA(1, 0), cA + kstep, voffA); PG8_STAGE(PG8_SB(1, 1), cB + hstep + kstep, voffB);
;         PG8_WAIT_V(6); PG8_BAR;
;     }
;     for (;;) {
;         const bool has_next = S.next(ui + 1, nxt);
;         const char* nA = has_next ? (const char*)g.A + (size_t)nxt.pm * tstep : cA; const char* nB = has_next ? (const char*)g.Bt + (size_t)nxt.pn * tstep : cB;
;         for (int t = 0; t < nt; t += 2) {
;             const bool last = (t == nt - 2);
;             const char* a1 = cA + (size_t)(t + 1) * kstep;
;             const char* a2 = last ? nA : cA + (size_t)(t + 2) * kstep; const char* b2 = last ? nB : cB + (size_t)(t + 2) * kstep;
;             const char* a3 = a2 + kstep; const char* b3 = b2 + kstep;
;             if (last && has_next) S.a_ready(nxt);
;             if constexpr (SP2) {
;             PG8_LDB(B0, 0, 0); PG8_LDB(B1, 0, 1); PG8_SCHED; PG8_LDA(At, 0, 0); PG8_STAGE(PG8_SA(1, 1), a1 + hstep, voffA);
;             PG8_WAIT_V(8); PG8_WAIT_L(0); PG8_BAR; PG8_MMA(0, 0, At, B0); PG8_MMA(0, 1, At, B1); PG8_BAR; PG8_SCHED;
;             PG8_LDA(At, 0, 1); PG8_STAGE(PG8_SB(0, 0), b2, voffB); PG8_STAGE(PG8_SB(0, 1), b2 + hstep, voffB); PG8_STAGE(PG8_SA(0, 0), a2, voffA);
;             PG8_WAIT_V(8); PG8_WAIT_L(0); PG8_BAR; PG8_MMA(1, 0, At, B0); PG8_MMA(1, 1, At, B1); PG8_BAR; PG8_SCHED;
.LBB0_556:
	s_mov_b64 s[0:1], 0x80
	s_mov_b32 m0, s87
	v_lshl_add_u64 v[4:5], v[28:29], 0, s[0:1]
	s_waitcnt vmcnt(2)
	s_barrier
	global_load_lds_dwordx4 v[4:5], off
	v_lshl_add_u64 v[6:7], v[30:31], 0, s[0:1]
	s_mov_b32 m0, s88
	v_lshl_add_u64 v[0:1], v[20:21], 0, s[0:1]
	global_load_lds_dwordx4 v[6:7], off
	s_mov_b32 m0, s73
	v_lshl_add_u64 v[2:3], v[22:23], 0, s[0:1]
	global_load_lds_dwordx4 v[0:1], off
	s_mov_b32 m0, s74
	v_lshl_add_u64 v[8:9], s[22:23], 0, v[32:33]
	global_load_lds_dwordx4 v[2:3], off
	s_mov_b32 m0, s89
	v_lshl_add_u64 v[10:11], s[22:23], 0, v[34:35]
	global_load_lds_dwordx4 v[8:9], off
	s_mov_b32 m0, s90
	v_and_b32_e32 v37, 15, v36
	global_load_lds_dwordx4 v[10:11], off
	v_lshrrev_b32_e32 v38, 1, v36
	v_or_b32_e32 v128, s57, v37
	v_and_b32_e32 v129, 24, v38
	v_lshlrev_b32_e32 v38, 6, v128
	v_lshlrev_b32_e32 v39, 1, v129
	s_movk_i32 s0, 0x3c0
	v_lshlrev_b32_e32 v36, 2, v36
	v_and_or_b32 v68, v38, s0, v39
	v_lshl_or_b32 v37, v37, 6, v39
	v_and_b32_e32 v36, 32, v36
	v_readlane_b32 s0, v254, 9
	v_lshlrev_b32_e32 v38, 2, v128
	v_and_b32_e32 v69, 32, v38
	v_bitop3_b32 v70, v37, s0, v36 bitop3:0xde
	v_add_u32_e32 v233, s78, v70
	s_waitcnt vmcnt(6)
	s_barrier
	v_add_u32_e32 v232, s77, v70
	ds_read_b128 v[36:39], v233 offset:3072
	ds_read_b128 v[40:43], v233 offset:2048
	ds_read_b128 v[44:47], v233 offset:1024
	ds_read_b128 v[48:51], v233
	ds_read_b128 v[52:55], v232 offset:3072
	ds_read_b128 v[56:59], v232 offset:2048
	ds_read_b128 v[60:63], v232 offset:1024
	ds_read_b128 v[64:67], v232
	v_bitop3_b32 v68, v68, s64, v69 bitop3:0xde
	v_add_u32_e32 v242, 0, v68
	v_add_u32_e32 v234, s85, v70
	v_add_u32_e32 v235, s86, v70
	s_add_u32 s0, s10, 0x10080
	s_addc_u32 s1, s11, 0
	s_mov_b32 m0, s79
	v_lshl_add_u64 v[100:101], s[0:1], 0, v[16:17]
	ds_read_b128 v[68:71], v242
	ds_read_b128 v[72:75], v242 offset:1024
	ds_read_b128 v[76:79], v242 offset:2048
	ds_read_b128 v[80:83], v242 offset:3072
	ds_read_b128 v[84:87], v242 offset:4096
	ds_read_b128 v[88:91], v242 offset:5120
	ds_read_b128 v[92:95], v242 offset:6144
	ds_read_b128 v[96:99], v242 offset:7168
	global_load_lds_dwordx4 v[100:101], off
	v_lshl_add_u64 v[100:101], s[0:1], 0, v[26:27]
	s_mov_b32 m0, s80
	s_nop 0
	global_load_lds_dwordx4 v[100:101], off
	s_waitcnt vmcnt(8)
	s_waitcnt lgkmcnt(0)
	s_barrier
	s_waitcnt lgkmcnt(0)
	v_mfma_f32_16x16x32_bf16 v[100:103], v[64:67], v[68:71], 0
	v_mfma_f32_16x16x32_bf16 v[104:107], v[56:59], v[68:71], 0
	v_mfma_f32_16x16x32_bf16 v[108:111], v[64:67], v[76:79], 0
	v_mfma_f32_16x16x32_bf16 v[112:115], v[56:59], v[76:79], 0
	v_mfma_f32_16x16x32_bf16 v[116:119], v[64:67], v[84:87], 0
	v_mfma_f32_16x16x32_bf16 v[120:123], v[56:59], v[84:87], 0
	v_mfma_f32_16x16x32_bf16 v[124:127], v[64:67], v[92:95], 0
	v_mfma_f32_16x16x32_bf16 v[100:103], v[60:63], v[72:75], v[100:103]
	v_mfma_f32_16x16x32_bf16 v[104:107], v[52:55], v[72:75], v[104:107]
	v_mfma_f32_16x16x32_bf16 v[108:111], v[60:63], v[80:83], v[108:111]
	v_mfma_f32_16x16x32_bf16 v[112:115], v[52:55], v[80:83], v[112:115]
	v_mfma_f32_16x16x32_bf16 v[116:119], v[60:63], v[88:91], v[116:119]
	v_mfma_f32_16x16x32_bf16 v[120:123], v[52:55], v[88:91], v[120:123]
	v_mfma_f32_16x16x32_bf16 v[124:127], v[60:63], v[96:99], v[124:127]
	v_mfma_f32_16x16x32_bf16 v[130:133], v[56:59], v[92:95], 0
	v_mfma_f32_16x16x32_bf16 v[130:133], v[52:55], v[96:99], v[130:133]
	v_mfma_f32_16x16x32_bf16 v[134:137], v[48:51], v[68:71], 0
	v_mfma_f32_16x16x32_bf16 v[68:71], v[40:43], v[68:71], 0
	v_mfma_f32_16x16x32_bf16 v[134:137], v[44:47], v[72:75], v[134:137]
	v_mfma_f32_16x16x32_bf16 v[68:71], v[36:39], v[72:75], v[68:71]
	v_mfma_f32_16x16x32_bf16 v[72:75], v[48:51], v[76:79], 0
	v_mfma_f32_16x16x32_bf16 v[76:79], v[40:43], v[76:79], 0
	v_mfma_f32_16x16x32_bf16 v[72:75], v[44:47], v[80:83], v[72:75]
	v_mfma_f32_16x16x32_bf16 v[76:79], v[36:39], v[80:83], v[76:79]
	v_mfma_f32_16x16x32_bf16 v[80:83], v[48:51], v[84:87], 0
	v_mfma_f32_16x16x32_bf16 v[84:87], v[40:43], v[84:87], 0
	v_mfma_f32_16x16x32_bf16 v[80:83], v[44:47], v[88:91], v[80:83]
	v_mfma_f32_16x16x32_bf16 v[84:87], v[36:39], v[88:91], v[84:87]
	v_mfma_f32_16x16x32_bf16 v[88:91], v[48:51], v[92:95], 0
	v_mfma_f32_16x16x32_bf16 v[92:95], v[40:43], v[92:95], 0
	v_mfma_f32_16x16x32_bf16 v[88:91], v[44:47], v[96:99], v[88:91]
	v_mfma_f32_16x16x32_bf16 v[92:95], v[36:39], v[96:99], v[92:95]
	s_barrier
	s_mov_b64 s[0:1], 0x100
	s_mov_b32 m0, s81
	v_lshl_add_u64 v[166:167], v[28:29], 0, s[0:1]
	ds_read_b128 v[96:99], v242 offset:16384
	ds_read_b128 v[138:141], v242 offset:17408
	ds_read_b128 v[142:145], v242 offset:18432
	ds_read_b128 v[146:149], v242 offset:19456
	ds_read_b128 v[150:153], v242 offset:20480
	ds_read_b128 v[154:157], v242 offset:21504
	ds_read_b128 v[158:161], v242 offset:22528
	ds_read_b128 v[162:165], v242 offset:23552
	global_load_lds_dwordx4 v[166:167], off
	v_lshl_add_u64 v[166:167], v[30:31], 0, s[0:1]
	s_mov_b32 m0, s82
	s_nop 0
	global_load_lds_dwordx4 v[166:167], off
	v_lshl_add_u64 v[166:167], s[24:25], 0, v[32:33]
	s_mov_b32 m0, s83
	s_nop 0
	global_load_lds_dwordx4 v[166:167], off
	v_lshl_add_u64 v[166:167], s[24:25], 0, v[34:35]
	s_mov_b32 m0, s84
	s_nop 0
	global_load_lds_dwordx4 v[166:167], off
	v_lshl_add_u64 v[166:167], v[20:21], 0, s[0:1]
	s_mov_b32 m0, s33
	s_nop 0
	global_load_lds_dwordx4 v[166:167], off
	v_lshl_add_u64 v[166:167], v[22:23], 0, s[0:1]
	s_mov_b32 m0, s63
	s_nop 0
	global_load_lds_dwordx4 v[166:167], off
	s_waitcnt vmcnt(8)
	s_waitcnt lgkmcnt(0)
	s_barrier
; #define PG8_STAGE(bufoff, gbase, voff) do { _Pragma("unroll") for (int _i = 0; _i < 2; ++_i) \
;         __builtin_amdgcn_global_load_lds((const unsigned*)((const char*)(gbase) + (voff)[_i]), (PG8_LAS unsigned*)(lds + (bufoff) + ldsw + _i * 8192), 16, 0, 0); } while (0)
; #define PG8_LDA(dst, b, h) do { _Pragma("unroll") for (int m = 0; m < 4; ++m) _Pragma("unroll") for (int k = 0; k < 2; ++k) dst[m][k] = *(const PG8_LAS bf16x8*)(lds + PG8_SA(b, h) + aoff + m * 2048 + k * 1024); } while (0)
; #define PG8_LDB(dst, b, h) do { _Pragma("unroll") for (int n = 0; n < 2; ++n) _Pragma("unroll") for (int k = 0; k < 2; ++k) dst[n][k] = *(const PG8_LAS bf16x8*)(lds + PG8_SB(b, h) + boff + n * 2048 + k * 1024); } while (0)
; #define PG8_MMA(ai, bj, At, Bt) do { __builtin_amdgcn_s_setprio(1); _Pragma("unroll") for (int m = 0; m < 4; ++m) _Pragma("unroll") for (int n = 0; n < 2; ++n) _Pragma("unroll") for (int k = 0; k < 2; ++k) \
;         acc[ai][bj][m][n] = __builtin_amdgcn_mfma_f32_16x16x32_bf16(Bt[n][k], At[m][k], acc[ai][bj][m][n], 0, 0, 0); __builtin_amdgcn_s_setprio(0); } while (0)
; #define PG8_BAR __builtin_amdgcn_s_barrier()
; template <class Epi, class Sched, bool ALIGN_EPI = false, bool SP2 = false>
; __device__ __forceinline__ void gemm_phase(PG8_LAS unsigned char* lds, const Gemm g, const Sched& S, const Epi& E, const int wave_id) {
;     ...
;             PG8_LDB(B0, 0, 0); PG8_LDB(B1, 0, 1); PG8_SCHED; PG8_LDA(At, 0, 0); PG8_STAGE(PG8_SA(1, 1), a1 + hstep, voffA);
;             PG8_WAIT_V(8); PG8_WAIT_L(0); PG8_BAR; PG8_MMA(0, 0, At, B0); PG8_MMA(0, 1, At, B1); PG8_BAR; PG8_SCHED;
;             PG8_LDA(At, 0, 1); PG8_STAGE(PG8_SB(0, 0), b2, voffB); PG8_STAGE(PG8_SB(0, 1), b2 + hstep, voffB); PG8_STAGE(PG8_SA(0, 0), a2, voffA);
;             PG8_WAIT_V(8); PG8_WAIT_L(0); PG8_BAR; PG8_MMA(1, 0, At, B0); PG8_MMA(1, 1, At, B1); PG8_BAR; PG8_SCHED;
;             PG8_LDB(B0, 1, 0); PG8_LDB(B1, 1, 1); PG8_SCHED; PG8_LDA(At, 1, 0); PG8_STAGE(PG8_SA(0, 1), a2 + hstep, voffA);
;             PG8_WAIT_V(8); PG8_WAIT_L(0); PG8_BAR; PG8_MMA(0, 0, At, B0); PG8_MMA(0, 1, At, B1); PG8_BAR; PG8_SCHED;
;             PG8_LDA(At, 1, 1); PG8_STAGE(PG8_SB(1, 0), b3, voffB); PG8_STAGE(PG8_SB(1, 1), b3 + hstep, voffB); PG8_STAGE(PG8_SA(1, 0), a3, voffA);
;             PG8_WAIT_V(8); PG8_WAIT_L(0); PG8_BAR; PG8_MMA(1, 0, At, B0); PG8_MMA(1, 1, At, B1); PG8_BAR; PG8_SCHED;
	s_waitcnt lgkmcnt(0)
	v_mfma_f32_16x16x32_bf16 v[166:169], v[64:67], v[96:99], 0
	v_mfma_f32_16x16x32_bf16 v[170:173], v[56:59], v[96:99], 0
	v_mfma_f32_16x16x32_bf16 v[174:177], v[64:67], v[142:145], 0
	v_mfma_f32_16x16x32_bf16 v[178:181], v[56:59], v[142:145], 0
	v_mfma_f32_16x16x32_bf16 v[182:185], v[64:67], v[150:153], 0
	v_mfma_f32_16x16x32_bf16 v[186:189], v[56:59], v[150:153], 0
	v_mfma_f32_16x16x32_bf16 v[64:67], v[64:67], v[158:161], 0
	v_mfma_f32_16x16x32_bf16 v[56:59], v[56:59], v[158:161], 0
	v_mfma_f32_16x16x32_bf16 v[166:169], v[60:63], v[138:141], v[166:169]
	v_mfma_f32_16x16x32_bf16 v[170:173], v[52:55], v[138:141], v[170:173]
	v_mfma_f32_16x16x32_bf16 v[174:177], v[60:63], v[146:149], v[174:177]
	v_mfma_f32_16x16x32_bf16 v[178:181], v[52:55], v[146:149], v[178:181]
	v_mfma_f32_16x16x32_bf16 v[182:185], v[60:63], v[154:157], v[182:185]
	v_mfma_f32_16x16x32_bf16 v[186:189], v[52:55], v[154:157], v[186:189]
	v_mfma_f32_16x16x32_bf16 v[60:63], v[60:63], v[162:165], v[64:67]
	v_mfma_f32_16x16x32_bf16 v[52:55], v[52:55], v[162:165], v[56:59]
	v_mfma_f32_16x16x32_bf16 v[56:59], v[48:51], v[96:99], 0
	v_mfma_f32_16x16x32_bf16 v[64:67], v[40:43], v[96:99], 0
	v_mfma_f32_16x16x32_bf16 v[56:59], v[44:47], v[138:141], v[56:59]
	v_mfma_f32_16x16x32_bf16 v[64:67], v[36:39], v[138:141], v[64:67]
	v_mfma_f32_16x16x32_bf16 v[96:99], v[48:51], v[142:145], 0
	v_mfma_f32_16x16x32_bf16 v[138:141], v[40:43], v[142:145], 0
	v_mfma_f32_16x16x32_bf16 v[96:99], v[44:47], v[146:149], v[96:99]
	v_mfma_f32_16x16x32_bf16 v[138:141], v[36:39], v[146:149], v[138:141]
	v_mfma_f32_16x16x32_bf16 v[142:145], v[48:51], v[150:153], 0
	v_mfma_f32_16x16x32_bf16 v[146:149], v[40:43], v[150:153], 0
	v_mfma_f32_16x16x32_bf16 v[48:51], v[48:51], v[158:161], 0
	v_mfma_f32_16x16x32_bf16 v[40:43], v[40:43], v[158:161], 0
	v_mfma_f32_16x16x32_bf16 v[142:145], v[44:47], v[154:157], v[142:145]
	v_mfma_f32_16x16x32_bf16 v[146:149], v[36:39], v[154:157], v[146:149]
	v_mfma_f32_16x16x32_bf16 v[44:47], v[44:47], v[162:165], v[48:51]
	v_mfma_f32_16x16x32_bf16 v[36:39], v[36:39], v[162:165], v[40:43]
	s_barrier
	s_nop 1
	ds_read_b128 v[40:43], v234
	ds_read_b128 v[48:51], v234 offset:1024
	ds_read_b128 v[150:153], v234 offset:2048
	ds_read_b128 v[154:157], v234 offset:3072
	ds_read_b128 v[158:161], v235
	ds_read_b128 v[162:165], v235 offset:1024
	ds_read_b128 v[190:193], v235 offset:2048
	ds_read_b128 v[194:197], v235 offset:3072
	s_add_u32 s0, s10, 0x10100
	s_addc_u32 s1, s11, 0
	s_mov_b32 m0, s69
	v_lshl_add_u64 v[230:231], s[0:1], 0, v[16:17]
	ds_read_b128 v[198:201], v242 offset:32768
	ds_read_b128 v[202:205], v242 offset:33792
	ds_read_b128 v[206:209], v242 offset:34816
	ds_read_b128 v[210:213], v242 offset:35840
	ds_read_b128 v[214:217], v242 offset:36864
	ds_read_b128 v[218:221], v242 offset:37888
	ds_read_b128 v[222:225], v242 offset:38912
	ds_read_b128 v[226:229], v242 offset:39936
	global_load_lds_dwordx4 v[230:231], off
	v_lshl_add_u64 v[230:231], s[0:1], 0, v[26:27]
	s_mov_b32 m0, s70
	s_nop 0
	global_load_lds_dwordx4 v[230:231], off
	s_waitcnt vmcnt(8)
	s_waitcnt lgkmcnt(0)
	s_barrier
	s_waitcnt lgkmcnt(0)
	v_mfma_f32_16x16x32_bf16 v[100:103], v[40:43], v[198:201], v[100:103]
	v_mfma_f32_16x16x32_bf16 v[104:107], v[150:153], v[198:201], v[104:107]
	v_mfma_f32_16x16x32_bf16 v[108:111], v[40:43], v[206:209], v[108:111]
	v_mfma_f32_16x16x32_bf16 v[112:115], v[150:153], v[206:209], v[112:115]
	v_mfma_f32_16x16x32_bf16 v[116:119], v[40:43], v[214:217], v[116:119]
	v_mfma_f32_16x16x32_bf16 v[120:123], v[150:153], v[214:217], v[120:123]
	v_mfma_f32_16x16x32_bf16 v[124:127], v[40:43], v[222:225], v[124:127]
	v_mfma_f32_16x16x32_bf16 v[100:103], v[48:51], v[202:205], v[100:103]
	v_mfma_f32_16x16x32_bf16 v[104:107], v[154:157], v[202:205], v[104:107]
	v_mfma_f32_16x16x32_bf16 v[108:111], v[48:51], v[210:213], v[108:111]
	v_mfma_f32_16x16x32_bf16 v[112:115], v[154:157], v[210:213], v[112:115]
	v_mfma_f32_16x16x32_bf16 v[116:119], v[48:51], v[218:221], v[116:119]
	v_mfma_f32_16x16x32_bf16 v[120:123], v[154:157], v[218:221], v[120:123]
	v_mfma_f32_16x16x32_bf16 v[124:127], v[48:51], v[226:229], v[124:127]
	v_mfma_f32_16x16x32_bf16 v[130:133], v[150:153], v[222:225], v[130:133]
	v_mfma_f32_16x16x32_bf16 v[130:133], v[154:157], v[226:229], v[130:133]
	v_mfma_f32_16x16x32_bf16 v[68:71], v[190:193], v[198:201], v[68:71]
	v_mfma_f32_16x16x32_bf16 v[72:75], v[158:161], v[206:209], v[72:75]
	v_mfma_f32_16x16x32_bf16 v[76:79], v[190:193], v[206:209], v[76:79]
	v_mfma_f32_16x16x32_bf16 v[80:83], v[158:161], v[214:217], v[80:83]
	v_mfma_f32_16x16x32_bf16 v[84:87], v[190:193], v[214:217], v[84:87]
	v_mfma_f32_16x16x32_bf16 v[88:91], v[158:161], v[222:225], v[88:91]
	v_mfma_f32_16x16x32_bf16 v[92:95], v[190:193], v[222:225], v[92:95]
	v_mfma_f32_16x16x32_bf16 v[134:137], v[158:161], v[198:201], v[134:137]
	v_mfma_f32_16x16x32_bf16 v[68:71], v[194:197], v[202:205], v[68:71]
	v_mfma_f32_16x16x32_bf16 v[72:75], v[162:165], v[210:213], v[72:75]
	v_mfma_f32_16x16x32_bf16 v[76:79], v[194:197], v[210:213], v[76:79]
	v_mfma_f32_16x16x32_bf16 v[80:83], v[162:165], v[218:221], v[80:83]
	v_mfma_f32_16x16x32_bf16 v[84:87], v[194:197], v[218:221], v[84:87]
	v_mfma_f32_16x16x32_bf16 v[88:91], v[162:165], v[226:229], v[88:91]
	v_mfma_f32_16x16x32_bf16 v[92:95], v[194:197], v[226:229], v[92:95]
	v_mfma_f32_16x16x32_bf16 v[134:137], v[162:165], v[202:205], v[134:137]
	s_barrier
; #define PG8_STAGE(bufoff, gbase, voff) do { _Pragma("unroll") for (int _i = 0; _i < 2; ++_i) \
;         __builtin_amdgcn_global_load_lds((const unsigned*)((const char*)(gbase) + (voff)[_i]), (PG8_LAS unsigned*)(lds + (bufoff) + ldsw + _i * 8192), 16, 0, 0); } while (0)
; #define PG8_LDA(dst, b, h) do { _Pragma("unroll") for (int m = 0; m < 4; ++m) _Pragma("unroll") for (int k = 0; k < 2; ++k) dst[m][k] = *(const PG8_LAS bf16x8*)(lds + PG8_SA(b, h) + aoff + m * 2048 + k * 1024); } while (0)
; #define PG8_LDB(dst, b, h) do { _Pragma("unroll") for (int n = 0; n < 2; ++n) _Pragma("unroll") for (int k = 0; k < 2; ++k) dst[n][k] = *(const PG8_LAS bf16x8*)(lds + PG8_SB(b, h) + boff + n * 2048 + k * 1024); } while (0)
; #define PG8_MMA(ai, bj, At, Bt) do { __builtin_amdgcn_s_setprio(1); _Pragma("unroll") for (int m = 0; m < 4; ++m) _Pragma("unroll") for (int n = 0; n < 2; ++n) _Pragma("unroll") for (int k = 0; k < 2; ++k) \
;         acc[ai][bj][m][n] = __builtin_amdgcn_mfma_f32_16x16x32_bf16(Bt[n][k], At[m][k], acc[ai][bj][m][n], 0, 0, 0); __builtin_amdgcn_s_setprio(0); } while (0)
; #define PG8_BAR __builtin_amdgcn_s_barrier()
; template <class Epi, class Sched, bool ALIGN_EPI = false, bool SP2 = false>
; __device__ __forceinline__ void gemm_phase(PG8_LAS unsigned char* lds, const Gemm g, const Sched& S, const Epi& E, const int wave_id) {
;     ...
;             PG8_LDB(B0, 0, 0); PG8_LDB(B1, 0, 1); PG8_SCHED; PG8_LDA(At, 0, 0); PG8_STAGE(PG8_SA(1, 1), a1 + hstep, voffA);
;             PG8_WAIT_V(8); PG8_WAIT_L(0); PG8_BAR; PG8_MMA(0, 0, At, B0); PG8_MMA(0, 1, At, B1); PG8_BAR; PG8_SCHED;
;             PG8_LDA(At, 0, 1); PG8_STAGE(PG8_SB(0, 0), b2, voffB); PG8_STAGE(PG8_SB(0, 1), b2 + hstep, voffB); PG8_STAGE(PG8_SA(0, 0), a2, voffA);
;             PG8_WAIT_V(8); PG8_WAIT_L(0); PG8_BAR; PG8_MMA(1, 0, At, B0); PG8_MMA(1, 1, At, B1); PG8_BAR; PG8_SCHED;
;             PG8_LDB(B0, 1, 0); PG8_LDB(B1, 1, 1); PG8_SCHED; PG8_LDA(At, 1, 0); PG8_STAGE(PG8_SA(0, 1), a2 + hstep, voffA);
;             PG8_WAIT_V(8); PG8_WAIT_L(0); PG8_BAR; PG8_MMA(0, 0, At, B0); PG8_MMA(0, 1, At, B1); PG8_BAR; PG8_SCHED;
;             PG8_LDA(At, 1, 1); PG8_STAGE(PG8_SB(1, 0), b3, voffB); PG8_STAGE(PG8_SB(1, 1), b3 + hstep, voffB); PG8_STAGE(PG8_SA(1, 0), a3, voffA);
;             PG8_WAIT_V(8); PG8_WAIT_L(0); PG8_BAR; PG8_MMA(1, 0, At, B0); PG8_MMA(1, 1, At, B1); PG8_BAR; PG8_SCHED;
	s_mov_b64 s[0:1], 0x180
	s_mov_b32 m0, s87
	v_lshl_add_u64 v[230:231], v[28:29], 0, s[0:1]
	ds_read_b128 v[198:201], v242 offset:49152
	ds_read_b128 v[202:205], v242 offset:50176
	ds_read_b128 v[206:209], v242 offset:51200
	ds_read_b128 v[210:213], v242 offset:52224
	ds_read_b128 v[214:217], v242 offset:53248
	ds_read_b128 v[218:221], v242 offset:54272
	ds_read_b128 v[222:225], v242 offset:55296
	ds_read_b128 v[226:229], v242 offset:56320
	global_load_lds_dwordx4 v[230:231], off
	v_lshl_add_u64 v[230:231], v[30:31], 0, s[0:1]
	s_mov_b32 m0, s88
	v_lshl_add_u64 v[32:33], s[26:27], 0, v[32:33]
	global_load_lds_dwordx4 v[230:231], off
	s_mov_b32 m0, s89
	s_nop 0
	global_load_lds_dwordx4 v[32:33], off
	v_lshl_add_u64 v[32:33], s[26:27], 0, v[34:35]
	s_mov_b32 m0, s90
	s_nop 0
	global_load_lds_dwordx4 v[32:33], off
	v_lshl_add_u64 v[32:33], v[20:21], 0, s[0:1]
	s_mov_b32 m0, s73
	s_nop 0
	global_load_lds_dwordx4 v[32:33], off
	v_lshl_add_u64 v[32:33], v[22:23], 0, s[0:1]
	s_mov_b32 m0, s74
	s_nop 0
	global_load_lds_dwordx4 v[32:33], off
	s_waitcnt vmcnt(8)
	s_waitcnt lgkmcnt(0)
	s_barrier
	s_waitcnt lgkmcnt(0)
	v_mfma_f32_16x16x32_bf16 v[32:35], v[40:43], v[198:201], v[166:169]
	v_mfma_f32_16x16x32_bf16 v[166:169], v[150:153], v[198:201], v[170:173]
	v_mfma_f32_16x16x32_bf16 v[170:173], v[40:43], v[206:209], v[174:177]
	v_mfma_f32_16x16x32_bf16 v[174:177], v[150:153], v[206:209], v[178:181]
	v_mfma_f32_16x16x32_bf16 v[178:181], v[40:43], v[214:217], v[182:185]
	v_mfma_f32_16x16x32_bf16 v[40:43], v[40:43], v[222:225], v[60:63]
	v_mfma_f32_16x16x32_bf16 v[32:35], v[48:51], v[202:205], v[32:35]
	v_mfma_f32_16x16x32_bf16 v[170:173], v[48:51], v[210:213], v[170:173]
	v_mfma_f32_16x16x32_bf16 v[178:181], v[48:51], v[218:221], v[178:181]
	v_mfma_f32_16x16x32_bf16 v[40:43], v[48:51], v[226:229], v[40:43]
	v_mfma_f32_16x16x32_bf16 v[48:51], v[150:153], v[222:225], v[52:55]
	v_mfma_f32_16x16x32_bf16 v[182:185], v[150:153], v[214:217], v[186:189]
	v_mfma_f32_16x16x32_bf16 v[48:51], v[154:157], v[226:229], v[48:51]
	v_mfma_f32_16x16x32_bf16 v[166:169], v[154:157], v[202:205], v[166:169]
	v_mfma_f32_16x16x32_bf16 v[174:177], v[154:157], v[210:213], v[174:177]
	v_mfma_f32_16x16x32_bf16 v[182:185], v[154:157], v[218:221], v[182:185]
	v_mfma_f32_16x16x32_bf16 v[52:55], v[158:161], v[198:201], v[56:59]
	v_mfma_f32_16x16x32_bf16 v[56:59], v[190:193], v[198:201], v[64:67]
	v_mfma_f32_16x16x32_bf16 v[60:63], v[158:161], v[206:209], v[96:99]
	v_mfma_f32_16x16x32_bf16 v[64:67], v[190:193], v[206:209], v[138:141]
	v_mfma_f32_16x16x32_bf16 v[96:99], v[158:161], v[214:217], v[142:145]
	v_mfma_f32_16x16x32_bf16 v[44:47], v[158:161], v[222:225], v[44:47]
	v_mfma_f32_16x16x32_bf16 v[36:39], v[190:193], v[222:225], v[36:39]
	v_mfma_f32_16x16x32_bf16 v[52:55], v[162:165], v[202:205], v[52:55]
	v_mfma_f32_16x16x32_bf16 v[56:59], v[194:197], v[202:205], v[56:59]
	v_mfma_f32_16x16x32_bf16 v[60:63], v[162:165], v[210:213], v[60:63]
	v_mfma_f32_16x16x32_bf16 v[64:67], v[194:197], v[210:213], v[64:67]
	v_mfma_f32_16x16x32_bf16 v[96:99], v[162:165], v[218:221], v[96:99]
	v_mfma_f32_16x16x32_bf16 v[138:141], v[190:193], v[214:217], v[146:149]
	v_mfma_f32_16x16x32_bf16 v[44:47], v[162:165], v[226:229], v[44:47]
	v_mfma_f32_16x16x32_bf16 v[36:39], v[194:197], v[226:229], v[36:39]
	v_mfma_f32_16x16x32_bf16 v[138:141], v[194:197], v[218:221], v[138:141]
	s_barrier
	ds_read_b128 v[142:145], v232
	ds_read_b128 v[146:149], v232 offset:1024
	ds_read_b128 v[150:153], v232 offset:2048
	ds_read_b128 v[154:157], v232 offset:3072
	ds_read_b128 v[158:161], v233
	ds_read_b128 v[162:165], v233 offset:1024
	ds_read_b128 v[186:189], v233 offset:2048
	ds_read_b128 v[190:193], v233 offset:3072
	s_add_u32 s0, s10, 0x10180
	s_addc_u32 s1, s11, 0
	s_mov_b32 m0, s79
	v_lshl_add_u64 v[16:17], s[0:1], 0, v[16:17]
	ds_read_b128 v[194:197], v242
	ds_read_b128 v[198:201], v242 offset:1024
	ds_read_b128 v[202:205], v242 offset:2048
	ds_read_b128 v[206:209], v242 offset:3072
	ds_read_b128 v[210:213], v242 offset:4096
	ds_read_b128 v[214:217], v242 offset:5120
	ds_read_b128 v[218:221], v242 offset:6144
	ds_read_b128 v[222:225], v242 offset:7168
	global_load_lds_dwordx4 v[16:17], off
	v_lshl_add_u64 v[16:17], s[0:1], 0, v[26:27]
	s_mov_b32 m0, s80
	s_nop 0
	global_load_lds_dwordx4 v[16:17], off
	s_waitcnt vmcnt(8)
	s_waitcnt lgkmcnt(0)
	s_barrier
	s_waitcnt lgkmcnt(0)
	v_mfma_f32_16x16x32_bf16 v[112:115], v[150:153], v[202:205], v[112:115]
	v_mfma_f32_16x16x32_bf16 v[226:229], v[154:157], v[206:209], v[112:115]
	v_mfma_f32_16x16x32_bf16 v[112:115], v[142:145], v[210:213], v[116:119]
	v_mfma_f32_16x16x32_bf16 v[116:119], v[146:149], v[214:217], v[112:115]
	v_mfma_f32_16x16x32_bf16 v[112:115], v[150:153], v[210:213], v[120:123]
	v_mfma_f32_16x16x32_bf16 v[100:103], v[142:145], v[194:197], v[100:103]
	v_mfma_f32_16x16x32_bf16 v[104:107], v[150:153], v[194:197], v[104:107]
	v_mfma_f32_16x16x32_bf16 v[108:111], v[142:145], v[202:205], v[108:111]
	v_mfma_f32_16x16x32_bf16 v[230:233], v[154:157], v[214:217], v[112:115]
	v_mfma_f32_16x16x32_bf16 v[112:115], v[142:145], v[218:221], v[124:127]
	v_mfma_f32_16x16x32_bf16 v[100:103], v[146:149], v[198:201], v[100:103]
	v_mfma_f32_16x16x32_bf16 v[104:107], v[154:157], v[198:201], v[104:107]
	v_mfma_f32_16x16x32_bf16 v[108:111], v[146:149], v[206:209], v[108:111]
	v_mfma_f32_16x16x32_bf16 v[124:127], v[146:149], v[222:225], v[112:115]
	v_mfma_f32_16x16x32_bf16 v[112:115], v[150:153], v[218:221], v[130:133]
	v_mfma_f32_16x16x32_bf16 v[130:133], v[154:157], v[222:225], v[112:115]
	v_mfma_f32_16x16x32_bf16 v[80:83], v[158:161], v[210:213], v[80:83]
	v_mfma_f32_16x16x32_bf16 v[112:115], v[158:161], v[194:197], v[134:137]
	v_mfma_f32_16x16x32_bf16 v[68:71], v[186:189], v[194:197], v[68:71]
	v_mfma_f32_16x16x32_bf16 v[194:197], v[162:165], v[214:217], v[80:83]
	v_mfma_f32_16x16x32_bf16 v[80:83], v[186:189], v[210:213], v[84:87]
	v_mfma_f32_16x16x32_bf16 v[72:75], v[158:161], v[202:205], v[72:75]
	v_mfma_f32_16x16x32_bf16 v[76:79], v[186:189], v[202:205], v[76:79]
	v_mfma_f32_16x16x32_bf16 v[84:87], v[190:193], v[214:217], v[80:83]
	v_mfma_f32_16x16x32_bf16 v[80:83], v[158:161], v[218:221], v[88:91]
	v_mfma_f32_16x16x32_bf16 v[134:137], v[162:165], v[198:201], v[112:115]
	v_mfma_f32_16x16x32_bf16 v[68:71], v[190:193], v[198:201], v[68:71]
	v_mfma_f32_16x16x32_bf16 v[72:75], v[162:165], v[206:209], v[72:75]
	v_mfma_f32_16x16x32_bf16 v[76:79], v[190:193], v[206:209], v[76:79]
	v_mfma_f32_16x16x32_bf16 v[198:201], v[162:165], v[222:225], v[80:83]
	v_mfma_f32_16x16x32_bf16 v[80:83], v[186:189], v[218:221], v[92:95]
	v_mfma_f32_16x16x32_bf16 v[202:205], v[190:193], v[222:225], v[80:83]
	s_barrier
; #define PG8_STAGE(bufoff, gbase, voff) do { _Pragma("unroll") for (int _i = 0; _i < 2; ++_i) \
;         __builtin_amdgcn_global_load_lds((const unsigned*)((const char*)(gbase) + (voff)[_i]), (PG8_LAS unsigned*)(lds + (bufoff) + ldsw + _i * 8192), 16, 0, 0); } while (0)
; #define PG8_LDA(dst, b, h) do { _Pragma("unroll") for (int m = 0; m < 4; ++m) _Pragma("unroll") for (int k = 0; k < 2; ++k) dst[m][k] = *(const PG8_LAS bf16x8*)(lds + PG8_SA(b, h) + aoff + m * 2048 + k * 1024); } while (0)
; #define PG8_LDB(dst, b, h) do { _Pragma("unroll") for (int n = 0; n < 2; ++n) _Pragma("unroll") for (int k = 0; k < 2; ++k) dst[n][k] = *(const PG8_LAS bf16x8*)(lds + PG8_SB(b, h) + boff + n * 2048 + k * 1024); } while (0)
; #define PG8_MMA(ai, bj, At, Bt) do { __builtin_amdgcn_s_setprio(1); _Pragma("unroll") for (int m = 0; m < 4; ++m) _Pragma("unroll") for (int n = 0; n < 2; ++n) _Pragma("unroll") for (int k = 0; k < 2; ++k) \
;         acc[ai][bj][m][n] = __builtin_amdgcn_mfma_f32_16x16x32_bf16(Bt[n][k], At[m][k], acc[ai][bj][m][n], 0, 0, 0); __builtin_amdgcn_s_setprio(0); } while (0)
; #define PG8_BAR __builtin_amdgcn_s_barrier()
; template <class Epi, class Sched, bool ALIGN_EPI = false, bool SP2 = false>
; __device__ __forceinline__ void gemm_phase(PG8_LAS unsigned char* lds, const Gemm g, const Sched& S, const Epi& E, const int wave_id) {
;     ...
;             PG8_LDB(B0, 0, 0); PG8_LDB(B1, 0, 1); PG8_SCHED; PG8_LDA(At, 0, 0); PG8_STAGE(PG8_SA(1, 1), a1 + hstep, voffA);
;             PG8_WAIT_V(8); PG8_WAIT_L(0); PG8_BAR; PG8_MMA(0, 0, At, B0); PG8_MMA(0, 1, At, B1); PG8_BAR; PG8_SCHED;
;             PG8_LDA(At, 0, 1); PG8_STAGE(PG8_SB(0, 0), b2, voffB); PG8_STAGE(PG8_SB(0, 1), b2 + hstep, voffB); PG8_STAGE(PG8_SA(0, 0), a2, voffA);
;             PG8_WAIT_V(8); PG8_WAIT_L(0); PG8_BAR; PG8_MMA(1, 0, At, B0); PG8_MMA(1, 1, At, B1); PG8_BAR; PG8_SCHED;
;             PG8_LDB(B0, 1, 0); PG8_LDB(B1, 1, 1); PG8_SCHED; PG8_LDA(At, 1, 0); PG8_STAGE(PG8_SA(0, 1), a2 + hstep, voffA);
;             PG8_WAIT_V(8); PG8_WAIT_L(0); PG8_BAR; PG8_MMA(0, 0, At, B0); PG8_MMA(0, 1, At, B1); PG8_BAR; PG8_SCHED;
;             PG8_LDA(At, 1, 1); PG8_STAGE(PG8_SB(1, 0), b3, voffB); PG8_STAGE(PG8_SB(1, 1), b3 + hstep, voffB); PG8_STAGE(PG8_SA(1, 0), a3, voffA);
;             PG8_WAIT_V(8); PG8_WAIT_L(0); PG8_BAR; PG8_MMA(1, 0, At, B0); PG8_MMA(1, 1, At, B1); PG8_BAR; PG8_SCHED;
	s_mov_b32 m0, s81
	s_nop 3
	ds_read_b128 v[80:83], v242 offset:16384
	ds_read_b128 v[88:91], v242 offset:17408
	ds_read_b128 v[92:95], v242 offset:18432
	ds_read_b128 v[112:115], v242 offset:19456
	ds_read_b128 v[120:123], v242 offset:20480
	ds_read_b128 v[206:209], v242 offset:21504
	ds_read_b128 v[210:213], v242 offset:22528
	ds_read_b128 v[214:217], v242 offset:23552
	global_load_lds_dwordx4 v[28:29], off
	s_mov_b32 m0, s82
	s_nop 0
	global_load_lds_dwordx4 v[30:31], off
	s_mov_b32 m0, s83
	s_nop 0
	global_load_lds_dwordx4 v[24:25], off
	s_mov_b32 m0, s84
	s_nop 0
	global_load_lds_dwordx4 v[18:19], off
	s_mov_b32 m0, s33
	s_nop 0
	global_load_lds_dwordx4 v[20:21], off
	s_mov_b32 m0, s63
	s_nop 0
	global_load_lds_dwordx4 v[22:23], off
	s_waitcnt vmcnt(8)
	s_waitcnt lgkmcnt(0)
	s_barrier
	s_waitcnt lgkmcnt(0)
	v_mfma_f32_16x16x32_bf16 v[16:19], v[142:145], v[80:83], v[32:35]
	v_mfma_f32_16x16x32_bf16 v[20:23], v[150:153], v[80:83], v[166:169]
	v_mfma_f32_16x16x32_bf16 v[24:27], v[142:145], v[92:95], v[170:173]
	v_mfma_f32_16x16x32_bf16 v[28:31], v[150:153], v[92:95], v[174:177]
	v_mfma_f32_16x16x32_bf16 v[32:35], v[142:145], v[120:123], v[178:181]
	v_mfma_f32_16x16x32_bf16 v[40:43], v[142:145], v[210:213], v[40:43]
	v_mfma_f32_16x16x32_bf16 v[16:19], v[146:149], v[88:91], v[16:19]
	v_mfma_f32_16x16x32_bf16 v[20:23], v[154:157], v[88:91], v[20:23]
	v_mfma_f32_16x16x32_bf16 v[24:27], v[146:149], v[112:115], v[24:27]
	v_mfma_f32_16x16x32_bf16 v[28:31], v[154:157], v[112:115], v[28:31]
	v_mfma_f32_16x16x32_bf16 v[32:35], v[146:149], v[206:209], v[32:35]
	v_mfma_f32_16x16x32_bf16 v[166:169], v[150:153], v[120:123], v[182:185]
	v_mfma_f32_16x16x32_bf16 v[40:43], v[146:149], v[214:217], v[40:43]
	v_mfma_f32_16x16x32_bf16 v[48:51], v[150:153], v[210:213], v[48:51]
	v_mfma_f32_16x16x32_bf16 v[166:169], v[154:157], v[206:209], v[166:169]
	v_mfma_f32_16x16x32_bf16 v[142:145], v[154:157], v[214:217], v[48:51]
	v_mfma_f32_16x16x32_bf16 v[48:51], v[158:161], v[80:83], v[52:55]
	v_mfma_f32_16x16x32_bf16 v[146:149], v[162:165], v[88:91], v[48:51]
	v_mfma_f32_16x16x32_bf16 v[48:51], v[186:189], v[80:83], v[56:59]
	v_mfma_f32_16x16x32_bf16 v[150:153], v[190:193], v[88:91], v[48:51]
	v_mfma_f32_16x16x32_bf16 v[48:51], v[158:161], v[92:95], v[60:63]
	v_mfma_f32_16x16x32_bf16 v[154:157], v[162:165], v[112:115], v[48:51]
	v_mfma_f32_16x16x32_bf16 v[48:51], v[186:189], v[92:95], v[64:67]
	v_mfma_f32_16x16x32_bf16 v[170:173], v[190:193], v[112:115], v[48:51]
	v_mfma_f32_16x16x32_bf16 v[48:51], v[158:161], v[120:123], v[96:99]
	v_mfma_f32_16x16x32_bf16 v[174:177], v[162:165], v[206:209], v[48:51]
	v_mfma_f32_16x16x32_bf16 v[48:51], v[186:189], v[120:123], v[138:141]
	v_mfma_f32_16x16x32_bf16 v[44:47], v[158:161], v[210:213], v[44:47]
	v_mfma_f32_16x16x32_bf16 v[36:39], v[186:189], v[210:213], v[36:39]
	v_mfma_f32_16x16x32_bf16 v[138:141], v[190:193], v[206:209], v[48:51]
	v_mfma_f32_16x16x32_bf16 v[158:161], v[162:165], v[214:217], v[44:47]
	v_mfma_f32_16x16x32_bf16 v[162:165], v[190:193], v[214:217], v[36:39]
	s_barrier
	ds_read_b128 v[64:67], v234
	ds_read_b128 v[178:181], v234 offset:1024
	ds_read_b128 v[182:185], v234 offset:2048
	ds_read_b128 v[186:189], v234 offset:3072
	ds_read_b128 v[190:193], v235
	ds_read_b128 v[206:209], v235 offset:1024
	ds_read_b128 v[210:213], v235 offset:2048
	ds_read_b128 v[214:217], v235 offset:3072
	s_mov_b32 m0, s69
	ds_read_b128 v[36:39], v242 offset:32768
	ds_read_b128 v[44:47], v242 offset:33792
	ds_read_b128 v[52:55], v242 offset:34816
	ds_read_b128 v[60:63], v242 offset:35840
	ds_read_b128 v[218:221], v242 offset:36864
	ds_read_b128 v[222:225], v242 offset:37888
	ds_read_b128 v[234:237], v242 offset:38912
	ds_read_b128 v[238:241], v242 offset:39936
	global_load_lds_dwordx4 v[12:13], off
	s_mov_b32 m0, s70
	s_nop 0
	global_load_lds_dwordx4 v[14:15], off
	s_waitcnt vmcnt(8)
	s_waitcnt lgkmcnt(0)
	s_barrier
; #define PG8_STAGE(bufoff, gbase, voff) do { _Pragma("unroll") for (int _i = 0; _i < 2; ++_i) \
;         __builtin_amdgcn_global_load_lds((const unsigned*)((const char*)(gbase) + (voff)[_i]), (PG8_LAS unsigned*)(lds + (bufoff) + ldsw + _i * 8192), 16, 0, 0); } while (0)
; #define PG8_LDA(dst, b, h) do { _Pragma("unroll") for (int m = 0; m < 4; ++m) _Pragma("unroll") for (int k = 0; k < 2; ++k) dst[m][k] = *(const PG8_LAS bf16x8*)(lds + PG8_SA(b, h) + aoff + m * 2048 + k * 1024); } while (0)
; #define PG8_LDB(dst, b, h) do { _Pragma("unroll") for (int n = 0; n < 2; ++n) _Pragma("unroll") for (int k = 0; k < 2; ++k) dst[n][k] = *(const PG8_LAS bf16x8*)(lds + PG8_SB(b, h) + boff + n * 2048 + k * 1024); } while (0)
; #define PG8_MMA(ai, bj, At, Bt) do { __builtin_amdgcn_s_setprio(1); _Pragma("unroll") for (int m = 0; m < 4; ++m) _Pragma("unroll") for (int n = 0; n < 2; ++n) _Pragma("unroll") for (int k = 0; k < 2; ++k) \
;         acc[ai][bj][m][n] = __builtin_amdgcn_mfma_f32_16x16x32_bf16(Bt[n][k], At[m][k], acc[ai][bj][m][n], 0, 0, 0); __builtin_amdgcn_s_setprio(0); } while (0)
; template <class Epi, class Sched, bool ALIGN_EPI = false, bool SP2 = false>
; __device__ __forceinline__ void gemm_phase(PG8_LAS unsigned char* lds, const Gemm g, const Sched& S, const Epi& E, const int wave_id) {
;     ...
;             PG8_LDB(B0, 0, 0); PG8_LDB(B1, 0, 1); PG8_SCHED; PG8_LDA(At, 0, 0); PG8_STAGE(PG8_SA(1, 1), a1 + hstep, voffA);
;             PG8_WAIT_V(8); PG8_WAIT_L(0); PG8_BAR; PG8_MMA(0, 0, At, B0); PG8_MMA(0, 1, At, B1); PG8_BAR; PG8_SCHED;
;             PG8_LDA(At, 0, 1); PG8_STAGE(PG8_SB(0, 0), b2, voffB); PG8_STAGE(PG8_SB(0, 1), b2 + hstep, voffB); PG8_STAGE(PG8_SA(0, 0), a2, voffA);
;             PG8_WAIT_V(8); PG8_WAIT_L(0); PG8_BAR; PG8_MMA(1, 0, At, B0); PG8_MMA(1, 1, At, B1); PG8_BAR; PG8_SCHED;
;             PG8_LDB(B0, 1, 0); PG8_LDB(B1, 1, 1); PG8_SCHED; PG8_LDA(At, 1, 0); PG8_STAGE(PG8_SA(0, 1), a2 + hstep, voffA);
;             PG8_WAIT_V(8); PG8_WAIT_L(0); PG8_BAR; PG8_MMA(0, 0, At, B0); PG8_MMA(0, 1, At, B1); PG8_BAR; PG8_SCHED;
;             PG8_LDA(At, 1, 1); PG8_STAGE(PG8_SB(1, 0), b3, voffB); PG8_STAGE(PG8_SB(1, 1), b3 + hstep, voffB); PG8_STAGE(PG8_SA(1, 0), a3, voffA);
;             PG8_WAIT_V(8); PG8_WAIT_L(0); PG8_BAR; PG8_MMA(1, 0, At, B0); PG8_MMA(1, 1, At, B1); PG8_BAR; PG8_SCHED;
;     ...
;         if constexpr (ALIGN_EPI) { if (wr == 0) PG8_BAR; }
	s_waitcnt lgkmcnt(0)
	v_mfma_f32_16x16x32_bf16 v[12:15], v[64:67], v[36:39], v[100:103]
	v_mfma_f32_16x16x32_bf16 v[120:123], v[178:181], v[44:47], v[12:15]
	v_mfma_f32_16x16x32_bf16 v[12:15], v[182:185], v[36:39], v[104:107]
	v_mfma_f32_16x16x32_bf16 v[112:115], v[186:189], v[44:47], v[12:15]
	v_mfma_f32_16x16x32_bf16 v[12:15], v[64:67], v[52:55], v[108:111]
	v_mfma_f32_16x16x32_bf16 v[104:107], v[178:181], v[60:63], v[12:15]
	v_mfma_f32_16x16x32_bf16 v[12:15], v[182:185], v[52:55], v[226:229]
	v_mfma_f32_16x16x32_bf16 v[96:99], v[186:189], v[60:63], v[12:15]
	v_mfma_f32_16x16x32_bf16 v[12:15], v[64:67], v[218:221], v[116:119]
	v_mfma_f32_16x16x32_bf16 v[88:91], v[178:181], v[222:225], v[12:15]
	v_mfma_f32_16x16x32_bf16 v[12:15], v[182:185], v[218:221], v[230:233]
	v_mfma_f32_16x16x32_bf16 v[80:83], v[186:189], v[222:225], v[12:15]
	v_mfma_f32_16x16x32_bf16 v[12:15], v[64:67], v[234:237], v[124:127]
	v_mfma_f32_16x16x32_bf16 v[56:59], v[178:181], v[238:241], v[12:15]
	v_mfma_f32_16x16x32_bf16 v[12:15], v[182:185], v[234:237], v[130:133]
	v_mfma_f32_16x16x32_bf16 v[48:51], v[186:189], v[238:241], v[12:15]
	v_mfma_f32_16x16x32_bf16 v[12:15], v[190:193], v[36:39], v[134:137]
	v_mfma_f32_16x16x32_bf16 v[124:127], v[206:209], v[44:47], v[12:15]
	v_mfma_f32_16x16x32_bf16 v[12:15], v[210:213], v[36:39], v[68:71]
	v_mfma_f32_16x16x32_bf16 v[116:119], v[214:217], v[44:47], v[12:15]
	v_mfma_f32_16x16x32_bf16 v[12:15], v[190:193], v[52:55], v[72:75]
	v_mfma_f32_16x16x32_bf16 v[108:111], v[206:209], v[60:63], v[12:15]
	v_mfma_f32_16x16x32_bf16 v[12:15], v[210:213], v[52:55], v[76:79]
	v_mfma_f32_16x16x32_bf16 v[100:103], v[214:217], v[60:63], v[12:15]
	v_mfma_f32_16x16x32_bf16 v[12:15], v[190:193], v[218:221], v[194:197]
	v_mfma_f32_16x16x32_bf16 v[92:95], v[206:209], v[222:225], v[12:15]
	v_mfma_f32_16x16x32_bf16 v[12:15], v[210:213], v[218:221], v[84:87]
	v_mfma_f32_16x16x32_bf16 v[84:87], v[214:217], v[222:225], v[12:15]
	v_mfma_f32_16x16x32_bf16 v[12:15], v[190:193], v[234:237], v[198:201]
	v_mfma_f32_16x16x32_bf16 v[60:63], v[206:209], v[238:241], v[12:15]
	v_mfma_f32_16x16x32_bf16 v[12:15], v[210:213], v[234:237], v[202:205]
	v_mfma_f32_16x16x32_bf16 v[52:55], v[214:217], v[238:241], v[12:15]
	s_barrier
	s_mov_b32 m0, s87
	ds_read_b128 v[130:133], v242 offset:49152
	ds_read_b128 v[134:137], v242 offset:50176
	ds_read_b128 v[194:197], v242 offset:51200
	ds_read_b128 v[198:201], v242 offset:52224
	ds_read_b128 v[202:205], v242 offset:53248
	ds_read_b128 v[218:221], v242 offset:54272
	ds_read_b128 v[222:225], v242 offset:55296
	ds_read_b128 v[226:229], v242 offset:56320
	global_load_lds_dwordx4 v[4:5], off
	s_mov_b32 m0, s88
	s_nop 0
	global_load_lds_dwordx4 v[6:7], off
	s_mov_b32 m0, s89
	s_nop 0
	global_load_lds_dwordx4 v[8:9], off
	s_mov_b32 m0, s90
	s_nop 0
	global_load_lds_dwordx4 v[10:11], off
	s_mov_b32 m0, s73
	s_nop 0
	global_load_lds_dwordx4 v[0:1], off
	s_mov_b32 m0, s74
	s_nop 0
	global_load_lds_dwordx4 v[2:3], off
	s_waitcnt vmcnt(8)
	s_waitcnt lgkmcnt(0)
	s_barrier
	s_waitcnt lgkmcnt(0)
	v_mfma_f32_16x16x32_bf16 v[0:3], v[64:67], v[130:133], v[16:19]
	v_mfma_f32_16x16x32_bf16 v[76:79], v[178:181], v[134:137], v[0:3]
	v_mfma_f32_16x16x32_bf16 v[0:3], v[182:185], v[130:133], v[20:23]
	v_mfma_f32_16x16x32_bf16 v[72:75], v[186:189], v[134:137], v[0:3]
	v_mfma_f32_16x16x32_bf16 v[0:3], v[64:67], v[194:197], v[24:27]
	v_mfma_f32_16x16x32_bf16 v[44:47], v[178:181], v[198:201], v[0:3]
	v_mfma_f32_16x16x32_bf16 v[0:3], v[182:185], v[194:197], v[28:31]
	v_mfma_f32_16x16x32_bf16 v[36:39], v[186:189], v[198:201], v[0:3]
	v_mfma_f32_16x16x32_bf16 v[0:3], v[64:67], v[202:205], v[32:35]
	v_mfma_f32_16x16x32_bf16 v[28:31], v[178:181], v[218:221], v[0:3]
	v_mfma_f32_16x16x32_bf16 v[0:3], v[182:185], v[202:205], v[166:169]
	v_mfma_f32_16x16x32_bf16 v[20:23], v[186:189], v[218:221], v[0:3]
	v_mfma_f32_16x16x32_bf16 v[0:3], v[64:67], v[222:225], v[40:43]
	v_mfma_f32_16x16x32_bf16 v[12:15], v[178:181], v[226:229], v[0:3]
	v_mfma_f32_16x16x32_bf16 v[0:3], v[182:185], v[222:225], v[142:145]
	v_mfma_f32_16x16x32_bf16 v[4:7], v[186:189], v[226:229], v[0:3]
	v_mfma_f32_16x16x32_bf16 v[0:3], v[190:193], v[130:133], v[146:149]
	v_mfma_f32_16x16x32_bf16 v[68:71], v[206:209], v[134:137], v[0:3]
	v_mfma_f32_16x16x32_bf16 v[0:3], v[210:213], v[130:133], v[150:153]
	v_mfma_f32_16x16x32_bf16 v[64:67], v[214:217], v[134:137], v[0:3]
	v_mfma_f32_16x16x32_bf16 v[0:3], v[190:193], v[194:197], v[154:157]
	v_mfma_f32_16x16x32_bf16 v[40:43], v[206:209], v[198:201], v[0:3]
	v_mfma_f32_16x16x32_bf16 v[0:3], v[210:213], v[194:197], v[170:173]
	v_mfma_f32_16x16x32_bf16 v[32:35], v[214:217], v[198:201], v[0:3]
	v_mfma_f32_16x16x32_bf16 v[0:3], v[190:193], v[202:205], v[174:177]
	v_mfma_f32_16x16x32_bf16 v[24:27], v[206:209], v[218:221], v[0:3]
	v_mfma_f32_16x16x32_bf16 v[0:3], v[210:213], v[202:205], v[138:141]
	v_mfma_f32_16x16x32_bf16 v[16:19], v[214:217], v[218:221], v[0:3]
	v_mfma_f32_16x16x32_bf16 v[0:3], v[190:193], v[222:225], v[158:161]
	v_mfma_f32_16x16x32_bf16 v[8:11], v[206:209], v[226:229], v[0:3]
	v_mfma_f32_16x16x32_bf16 v[0:3], v[210:213], v[222:225], v[162:165]
	v_mfma_f32_16x16x32_bf16 v[0:3], v[214:217], v[226:229], v[0:3]
	s_barrier
	s_and_b64 vcc, exec, s[4:5]
	s_cbranch_vccnz .LBB0_558
	s_barrier

; #define PG8_STAGE(bufoff, gbase, voff) do { _Pragma("unroll") for (int _i = 0; _i < 2; ++_i) \
;         __builtin_amdgcn_global_load_lds((const unsigned*)((const char*)(gbase) + (voff)[_i]), (PG8_LAS unsigned*)(lds + (bufoff) + ldsw + _i * 8192), 16, 0, 0); } while (0)
; #define PG8_LDA(dst, b, h) do { _Pragma("unroll") for (int m = 0; m < 4; ++m) _Pragma("unroll") for (int k = 0; k < 2; ++k) dst[m][k] = *(const PG8_LAS bf16x8*)(lds + PG8_SA(b, h) + aoff + m * 2048 + k * 1024); } while (0)
; #define PG8_WAIT_V(n) asm volatile("s_waitcnt vmcnt(" #n ")" ::: "memory")
; #define PG8_WAIT_L(n) asm volatile("s_waitcnt lgkmcnt(" #n ")" ::: "memory")
; #define PG8_BAR __builtin_amdgcn_s_barrier()
; template <class Epi, class Sched, bool ALIGN_EPI = false, bool SP2 = false>
; __device__ __forceinline__ void gemm_phase(PG8_LAS unsigned char* lds, const Gemm g, const Sched& S, const Epi& E, const int wave_id) {
;     ...
;         for (int t = 0; t < nt; t += 2) {
;             const bool last = (t == nt - 2);
;             const char* a1 = cA + (size_t)(t + 1) * kstep;
;             const char* a2 = last ? nA : cA + (size_t)(t + 2) * kstep; const char* b2 = last ? nB : cB + (size_t)(t + 2) * kstep;
;             const char* a3 = a2 + kstep; const char* b3 = b2 + kstep;
;             if (last && has_next) S.a_ready(nxt);
;             if constexpr (SP2) {
;             PG8_LDB(B0, 0, 0); PG8_LDB(B1, 0, 1); PG8_SCHED; PG8_LDA(At, 0, 0); PG8_STAGE(PG8_SA(1, 1), a1 + hstep, voffA);
;             PG8_WAIT_V(8); PG8_WAIT_L(0); PG8_BAR; PG8_MMA(0, 0, At, B0); PG8_MMA(0, 1, At, B1); PG8_BAR; PG8_SCHED;
;             PG8_LDA(At, 0, 1); PG8_STAGE(PG8_SB(0, 0), b2, voffB); PG8_STAGE(PG8_SB(0, 1), b2 + hstep, voffB); PG8_STAGE(PG8_SA(0, 0), a2, voffA);
;             PG8_WAIT_V(8); PG8_WAIT_L(0); PG8_BAR; PG8_MMA(1, 0, At, B0); PG8_MMA(1, 1, At, B1); PG8_BAR; PG8_SCHED;
;             PG8_LDB(B0, 1, 0); PG8_LDB(B1, 1, 1); PG8_SCHED; PG8_LDA(At, 1, 0); PG8_STAGE(PG8_SA(0, 1), a2 + hstep, voffA);
;             PG8_WAIT_V(8); PG8_WAIT_L(0); PG8_BAR; PG8_MMA(0, 0, At, B0); PG8_MMA(0, 1, At, B1); PG8_BAR; PG8_SCHED;
;             PG8_LDA(At, 1, 1); PG8_STAGE(PG8_SB(1, 0), b3, voffB); PG8_STAGE(PG8_SB(1, 1), b3 + hstep, voffB); PG8_STAGE(PG8_SA(1, 0), a3, voffA);
;             PG8_WAIT_V(8); PG8_WAIT_L(0); PG8_BAR; PG8_MMA(1, 0, At, B0); PG8_MMA(1, 1, At, B1); PG8_BAR; PG8_SCHED;
.LBB0_581:
	v_add_u32_e32 v152, s77, v138
	v_add_u32_e32 v168, s78, v138
	ds_read_b128 v[140:143], v152
	ds_read_b128 v[144:147], v152 offset:1024
	ds_read_b128 v[148:151], v152 offset:2048
	ds_read_b128 v[152:155], v152 offset:3072
	ds_read_b128 v[156:159], v168
	ds_read_b128 v[160:163], v168 offset:1024
	ds_read_b128 v[164:167], v168 offset:2048
	ds_read_b128 v[168:171], v168 offset:3072
	s_add_u32 s44, s34, s43
	s_addc_u32 s45, s35, s48
	s_add_u32 s93, s34, s6
	s_addc_u32 s94, s35, s7
	s_cmp_eq_u32 s49, 28
	s_cselect_b32 s47, s1, s45
	s_cselect_b32 s46, s0, s44
	s_cselect_b32 s45, s17, s94
	s_cselect_b32 s44, s16, s93
	s_mov_b32 m0, s79
	v_lshl_add_u64 v[204:205], s[34:35], 0, v[134:135]
	ds_read_b128 v[172:175], v139
	ds_read_b128 v[176:179], v139 offset:1024
	ds_read_b128 v[180:183], v139 offset:2048
	ds_read_b128 v[184:187], v139 offset:3072
	ds_read_b128 v[188:191], v139 offset:4096
	ds_read_b128 v[192:195], v139 offset:5120
	ds_read_b128 v[196:199], v139 offset:6144
	ds_read_b128 v[200:203], v139 offset:7168
	global_load_lds_dwordx4 v[204:205], off
	v_lshl_add_u64 v[204:205], s[34:35], 0, v[136:137]
	s_mov_b32 m0, s80
	s_nop 0
	global_load_lds_dwordx4 v[204:205], off
	s_waitcnt vmcnt(8)
	s_waitcnt lgkmcnt(0)
	s_barrier
	s_waitcnt lgkmcnt(0)
	v_mfma_f32_16x16x32_bf16 v[116:119], v[140:143], v[172:175], v[116:119]
	v_mfma_f32_16x16x32_bf16 v[112:115], v[148:151], v[172:175], v[112:115]
	v_mfma_f32_16x16x32_bf16 v[84:87], v[140:143], v[180:183], v[84:87]
	v_mfma_f32_16x16x32_bf16 v[80:83], v[148:151], v[180:183], v[80:83]
	v_mfma_f32_16x16x32_bf16 v[60:63], v[140:143], v[188:191], v[60:63]
	v_mfma_f32_16x16x32_bf16 v[56:59], v[148:151], v[188:191], v[56:59]
	v_mfma_f32_16x16x32_bf16 v[36:39], v[140:143], v[196:199], v[36:39]
	v_mfma_f32_16x16x32_bf16 v[32:35], v[148:151], v[196:199], v[32:35]
	v_mfma_f32_16x16x32_bf16 v[116:119], v[144:147], v[176:179], v[116:119]
	v_mfma_f32_16x16x32_bf16 v[112:115], v[152:155], v[176:179], v[112:115]
	v_mfma_f32_16x16x32_bf16 v[84:87], v[144:147], v[184:187], v[84:87]
	v_mfma_f32_16x16x32_bf16 v[80:83], v[152:155], v[184:187], v[80:83]
	v_mfma_f32_16x16x32_bf16 v[60:63], v[144:147], v[192:195], v[60:63]
	v_mfma_f32_16x16x32_bf16 v[56:59], v[152:155], v[192:195], v[56:59]
	v_mfma_f32_16x16x32_bf16 v[36:39], v[144:147], v[200:203], v[36:39]
	v_mfma_f32_16x16x32_bf16 v[32:35], v[152:155], v[200:203], v[32:35]
	v_mfma_f32_16x16x32_bf16 v[100:103], v[156:159], v[172:175], v[100:103]
	v_mfma_f32_16x16x32_bf16 v[96:99], v[164:167], v[172:175], v[96:99]
	v_mfma_f32_16x16x32_bf16 v[76:79], v[156:159], v[180:183], v[76:79]
	v_mfma_f32_16x16x32_bf16 v[72:75], v[164:167], v[180:183], v[72:75]
	v_mfma_f32_16x16x32_bf16 v[48:51], v[156:159], v[188:191], v[48:51]
	v_mfma_f32_16x16x32_bf16 v[40:43], v[164:167], v[188:191], v[40:43]
	v_mfma_f32_16x16x32_bf16 v[28:31], v[156:159], v[196:199], v[28:31]
	v_mfma_f32_16x16x32_bf16 v[24:27], v[164:167], v[196:199], v[24:27]
	v_mfma_f32_16x16x32_bf16 v[100:103], v[160:163], v[176:179], v[100:103]
	v_mfma_f32_16x16x32_bf16 v[96:99], v[168:171], v[176:179], v[96:99]
	v_mfma_f32_16x16x32_bf16 v[76:79], v[160:163], v[184:187], v[76:79]
	v_mfma_f32_16x16x32_bf16 v[72:75], v[168:171], v[184:187], v[72:75]
	v_mfma_f32_16x16x32_bf16 v[48:51], v[160:163], v[192:195], v[48:51]
	v_mfma_f32_16x16x32_bf16 v[40:43], v[168:171], v[192:195], v[40:43]
	v_mfma_f32_16x16x32_bf16 v[28:31], v[160:163], v[200:203], v[28:31]
	v_mfma_f32_16x16x32_bf16 v[24:27], v[168:171], v[200:203], v[24:27]
	s_barrier
	s_mov_b32 m0, s81
	v_lshl_add_u64 v[204:205], s[44:45], 0, v[224:225]
	s_add_u32 s94, s44, 0x80000
	ds_read_b128 v[172:175], v139 offset:16384
	ds_read_b128 v[176:179], v139 offset:17408
	ds_read_b128 v[180:183], v139 offset:18432
	ds_read_b128 v[184:187], v139 offset:19456
	ds_read_b128 v[188:191], v139 offset:20480
	ds_read_b128 v[192:195], v139 offset:21504
	ds_read_b128 v[196:199], v139 offset:22528
	ds_read_b128 v[200:203], v139 offset:23552
	global_load_lds_dwordx4 v[204:205], off
	v_lshl_add_u64 v[206:207], s[44:45], 0, v[132:133]
	s_mov_b32 m0, s82
	s_addc_u32 s95, s45, 0
	global_load_lds_dwordx4 v[206:207], off
	v_lshl_add_u64 v[208:209], s[94:95], 0, v[224:225]
	s_mov_b32 m0, s83
	v_lshl_add_u64 v[210:211], s[46:47], 0, v[130:131]
	global_load_lds_dwordx4 v[208:209], off
	v_lshl_add_u64 v[208:209], s[94:95], 0, v[132:133]
	s_mov_b32 m0, s84
	s_nop 0
	global_load_lds_dwordx4 v[208:209], off
	v_lshl_add_u64 v[208:209], s[46:47], 0, v[128:129]
	s_mov_b32 m0, s33
	s_nop 0
	global_load_lds_dwordx4 v[208:209], off
	s_mov_b32 m0, s63
	s_nop 0
	global_load_lds_dwordx4 v[210:211], off
	s_waitcnt vmcnt(8)
	s_waitcnt lgkmcnt(0)
	s_barrier
; #define PG8_STAGE(bufoff, gbase, voff) do { _Pragma("unroll") for (int _i = 0; _i < 2; ++_i) \
;         __builtin_amdgcn_global_load_lds((const unsigned*)((const char*)(gbase) + (voff)[_i]), (PG8_LAS unsigned*)(lds + (bufoff) + ldsw + _i * 8192), 16, 0, 0); } while (0)
; #define PG8_LDA(dst, b, h) do { _Pragma("unroll") for (int m = 0; m < 4; ++m) _Pragma("unroll") for (int k = 0; k < 2; ++k) dst[m][k] = *(const PG8_LAS bf16x8*)(lds + PG8_SA(b, h) + aoff + m * 2048 + k * 1024); } while (0)
; #define PG8_WAIT_V(n) asm volatile("s_waitcnt vmcnt(" #n ")" ::: "memory")
; #define PG8_WAIT_L(n) asm volatile("s_waitcnt lgkmcnt(" #n ")" ::: "memory")
; #define PG8_BAR __builtin_amdgcn_s_barrier()
; template <class Epi, class Sched, bool ALIGN_EPI = false, bool SP2 = false>
; __device__ __forceinline__ void gemm_phase(PG8_LAS unsigned char* lds, const Gemm g, const Sched& S, const Epi& E, const int wave_id) {
;     ...
;         for (int t = 0; t < nt; t += 2) {
;             const bool last = (t == nt - 2);
;             const char* a1 = cA + (size_t)(t + 1) * kstep;
;             const char* a2 = last ? nA : cA + (size_t)(t + 2) * kstep; const char* b2 = last ? nB : cB + (size_t)(t + 2) * kstep;
;             const char* a3 = a2 + kstep; const char* b3 = b2 + kstep;
;             if (last && has_next) S.a_ready(nxt);
;             if constexpr (SP2) {
;             PG8_LDB(B0, 0, 0); PG8_LDB(B1, 0, 1); PG8_SCHED; PG8_LDA(At, 0, 0); PG8_STAGE(PG8_SA(1, 1), a1 + hstep, voffA);
;             PG8_WAIT_V(8); PG8_WAIT_L(0); PG8_BAR; PG8_MMA(0, 0, At, B0); PG8_MMA(0, 1, At, B1); PG8_BAR; PG8_SCHED;
;             PG8_LDA(At, 0, 1); PG8_STAGE(PG8_SB(0, 0), b2, voffB); PG8_STAGE(PG8_SB(0, 1), b2 + hstep, voffB); PG8_STAGE(PG8_SA(0, 0), a2, voffA);
;             PG8_WAIT_V(8); PG8_WAIT_L(0); PG8_BAR; PG8_MMA(1, 0, At, B0); PG8_MMA(1, 1, At, B1); PG8_BAR; PG8_SCHED;
;             PG8_LDB(B0, 1, 0); PG8_LDB(B1, 1, 1); PG8_SCHED; PG8_LDA(At, 1, 0); PG8_STAGE(PG8_SA(0, 1), a2 + hstep, voffA);
;             PG8_WAIT_V(8); PG8_WAIT_L(0); PG8_BAR; PG8_MMA(0, 0, At, B0); PG8_MMA(0, 1, At, B1); PG8_BAR; PG8_SCHED;
;             PG8_LDA(At, 1, 1); PG8_STAGE(PG8_SB(1, 0), b3, voffB); PG8_STAGE(PG8_SB(1, 1), b3 + hstep, voffB); PG8_STAGE(PG8_SA(1, 0), a3, voffA);
;             PG8_WAIT_V(8); PG8_WAIT_L(0); PG8_BAR; PG8_MMA(1, 0, At, B0); PG8_MMA(1, 1, At, B1); PG8_BAR; PG8_SCHED;
	s_waitcnt lgkmcnt(0)
	v_mfma_f32_16x16x32_bf16 v[124:127], v[140:143], v[172:175], v[124:127]
	v_mfma_f32_16x16x32_bf16 v[120:123], v[148:151], v[172:175], v[120:123]
	v_mfma_f32_16x16x32_bf16 v[92:95], v[140:143], v[180:183], v[92:95]
	v_mfma_f32_16x16x32_bf16 v[88:91], v[148:151], v[180:183], v[88:91]
	v_mfma_f32_16x16x32_bf16 v[52:55], v[140:143], v[188:191], v[52:55]
	v_mfma_f32_16x16x32_bf16 v[44:47], v[148:151], v[188:191], v[44:47]
	v_mfma_f32_16x16x32_bf16 v[12:15], v[140:143], v[196:199], v[12:15]
	v_mfma_f32_16x16x32_bf16 v[8:11], v[148:151], v[196:199], v[8:11]
	v_mfma_f32_16x16x32_bf16 v[124:127], v[144:147], v[176:179], v[124:127]
	v_mfma_f32_16x16x32_bf16 v[120:123], v[152:155], v[176:179], v[120:123]
	v_mfma_f32_16x16x32_bf16 v[92:95], v[144:147], v[184:187], v[92:95]
	v_mfma_f32_16x16x32_bf16 v[88:91], v[152:155], v[184:187], v[88:91]
	v_mfma_f32_16x16x32_bf16 v[52:55], v[144:147], v[192:195], v[52:55]
	v_mfma_f32_16x16x32_bf16 v[44:47], v[152:155], v[192:195], v[44:47]
	v_mfma_f32_16x16x32_bf16 v[12:15], v[144:147], v[200:203], v[12:15]
	v_mfma_f32_16x16x32_bf16 v[8:11], v[152:155], v[200:203], v[8:11]
	v_mfma_f32_16x16x32_bf16 v[108:111], v[156:159], v[172:175], v[108:111]
	v_mfma_f32_16x16x32_bf16 v[104:107], v[164:167], v[172:175], v[104:107]
	v_mfma_f32_16x16x32_bf16 v[68:71], v[156:159], v[180:183], v[68:71]
	v_mfma_f32_16x16x32_bf16 v[64:67], v[164:167], v[180:183], v[64:67]
	v_mfma_f32_16x16x32_bf16 v[20:23], v[156:159], v[188:191], v[20:23]
	v_mfma_f32_16x16x32_bf16 v[16:19], v[164:167], v[188:191], v[16:19]
	v_mfma_f32_16x16x32_bf16 v[4:7], v[156:159], v[196:199], v[4:7]
	v_mfma_f32_16x16x32_bf16 v[0:3], v[164:167], v[196:199], v[0:3]
	v_mfma_f32_16x16x32_bf16 v[108:111], v[160:163], v[176:179], v[108:111]
	v_mfma_f32_16x16x32_bf16 v[104:107], v[168:171], v[176:179], v[104:107]
	v_mfma_f32_16x16x32_bf16 v[68:71], v[160:163], v[184:187], v[68:71]
	v_mfma_f32_16x16x32_bf16 v[64:67], v[168:171], v[184:187], v[64:67]
	v_mfma_f32_16x16x32_bf16 v[20:23], v[160:163], v[192:195], v[20:23]
	v_mfma_f32_16x16x32_bf16 v[16:19], v[168:171], v[192:195], v[16:19]
	v_mfma_f32_16x16x32_bf16 v[4:7], v[160:163], v[200:203], v[4:7]
	v_mfma_f32_16x16x32_bf16 v[0:3], v[168:171], v[200:203], v[0:3]
	s_barrier
	v_add_u32_e32 v152, s85, v138
	v_add_u32_e32 v168, s86, v138
	ds_read_b128 v[140:143], v152
	ds_read_b128 v[144:147], v152 offset:1024
	ds_read_b128 v[148:151], v152 offset:2048
	ds_read_b128 v[152:155], v152 offset:3072
	ds_read_b128 v[156:159], v168
	ds_read_b128 v[160:163], v168 offset:1024
	ds_read_b128 v[164:167], v168 offset:2048
	ds_read_b128 v[168:171], v168 offset:3072
	s_add_u32 s46, s46, 0x80000
	s_addc_u32 s47, s47, 0
	s_mov_b32 m0, s69
	v_lshl_add_u64 v[212:213], s[46:47], 0, v[128:129]
	ds_read_b128 v[172:175], v139 offset:32768
	ds_read_b128 v[176:179], v139 offset:33792
	ds_read_b128 v[180:183], v139 offset:34816
	ds_read_b128 v[184:187], v139 offset:35840
	ds_read_b128 v[188:191], v139 offset:36864
	ds_read_b128 v[192:195], v139 offset:37888
	ds_read_b128 v[196:199], v139 offset:38912
	ds_read_b128 v[200:203], v139 offset:39936
	global_load_lds_dwordx4 v[212:213], off
	v_lshl_add_u64 v[212:213], s[46:47], 0, v[130:131]
	s_mov_b32 m0, s70
	s_nop 0
	global_load_lds_dwordx4 v[212:213], off
	s_waitcnt vmcnt(8)
	s_waitcnt lgkmcnt(0)
	s_barrier
	s_waitcnt lgkmcnt(0)
	v_mfma_f32_16x16x32_bf16 v[116:119], v[140:143], v[172:175], v[116:119]
	v_mfma_f32_16x16x32_bf16 v[112:115], v[148:151], v[172:175], v[112:115]
	v_mfma_f32_16x16x32_bf16 v[84:87], v[140:143], v[180:183], v[84:87]
	v_mfma_f32_16x16x32_bf16 v[80:83], v[148:151], v[180:183], v[80:83]
	v_mfma_f32_16x16x32_bf16 v[60:63], v[140:143], v[188:191], v[60:63]
	v_mfma_f32_16x16x32_bf16 v[56:59], v[148:151], v[188:191], v[56:59]
	v_mfma_f32_16x16x32_bf16 v[36:39], v[140:143], v[196:199], v[36:39]
	v_mfma_f32_16x16x32_bf16 v[32:35], v[148:151], v[196:199], v[32:35]
	v_mfma_f32_16x16x32_bf16 v[116:119], v[144:147], v[176:179], v[116:119]
	v_mfma_f32_16x16x32_bf16 v[112:115], v[152:155], v[176:179], v[112:115]
	v_mfma_f32_16x16x32_bf16 v[84:87], v[144:147], v[184:187], v[84:87]
	v_mfma_f32_16x16x32_bf16 v[80:83], v[152:155], v[184:187], v[80:83]
	v_mfma_f32_16x16x32_bf16 v[60:63], v[144:147], v[192:195], v[60:63]
	v_mfma_f32_16x16x32_bf16 v[56:59], v[152:155], v[192:195], v[56:59]
	v_mfma_f32_16x16x32_bf16 v[36:39], v[144:147], v[200:203], v[36:39]
	v_mfma_f32_16x16x32_bf16 v[32:35], v[152:155], v[200:203], v[32:35]
	v_mfma_f32_16x16x32_bf16 v[100:103], v[156:159], v[172:175], v[100:103]
	v_mfma_f32_16x16x32_bf16 v[96:99], v[164:167], v[172:175], v[96:99]
	v_mfma_f32_16x16x32_bf16 v[76:79], v[156:159], v[180:183], v[76:79]
	v_mfma_f32_16x16x32_bf16 v[72:75], v[164:167], v[180:183], v[72:75]
	v_mfma_f32_16x16x32_bf16 v[48:51], v[156:159], v[188:191], v[48:51]
	v_mfma_f32_16x16x32_bf16 v[40:43], v[164:167], v[188:191], v[40:43]
	v_mfma_f32_16x16x32_bf16 v[28:31], v[156:159], v[196:199], v[28:31]
	v_mfma_f32_16x16x32_bf16 v[24:27], v[164:167], v[196:199], v[24:27]
	v_mfma_f32_16x16x32_bf16 v[100:103], v[160:163], v[176:179], v[100:103]
	v_mfma_f32_16x16x32_bf16 v[96:99], v[168:171], v[176:179], v[96:99]
	v_mfma_f32_16x16x32_bf16 v[76:79], v[160:163], v[184:187], v[76:79]
	v_mfma_f32_16x16x32_bf16 v[72:75], v[168:171], v[184:187], v[72:75]
	v_mfma_f32_16x16x32_bf16 v[48:51], v[160:163], v[192:195], v[48:51]
	v_mfma_f32_16x16x32_bf16 v[40:43], v[168:171], v[192:195], v[40:43]
	v_mfma_f32_16x16x32_bf16 v[28:31], v[160:163], v[200:203], v[28:31]
	v_mfma_f32_16x16x32_bf16 v[24:27], v[168:171], v[200:203], v[24:27]
	s_barrier
; #define PG8_STAGE(bufoff, gbase, voff) do { _Pragma("unroll") for (int _i = 0; _i < 2; ++_i) \
;         __builtin_amdgcn_global_load_lds((const unsigned*)((const char*)(gbase) + (voff)[_i]), (PG8_LAS unsigned*)(lds + (bufoff) + ldsw + _i * 8192), 16, 0, 0); } while (0)
; #define PG8_LDA(dst, b, h) do { _Pragma("unroll") for (int m = 0; m < 4; ++m) _Pragma("unroll") for (int k = 0; k < 2; ++k) dst[m][k] = *(const PG8_LAS bf16x8*)(lds + PG8_SA(b, h) + aoff + m * 2048 + k * 1024); } while (0)
; #define PG8_WAIT_V(n) asm volatile("s_waitcnt vmcnt(" #n ")" ::: "memory")
; template <class Epi, class Sched, bool ALIGN_EPI = false, bool SP2 = false>
; __device__ __forceinline__ void gemm_phase(PG8_LAS unsigned char* lds, const Gemm g, const Sched& S, const Epi& E, const int wave_id) {
;     ...
;         for (int t = 0; t < nt; t += 2) {
;             const bool last = (t == nt - 2);
;             const char* a1 = cA + (size_t)(t + 1) * kstep;
;             const char* a2 = last ? nA : cA + (size_t)(t + 2) * kstep; const char* b2 = last ? nB : cB + (size_t)(t + 2) * kstep;
;             const char* a3 = a2 + kstep; const char* b3 = b2 + kstep;
;             if (last && has_next) S.a_ready(nxt);
;             if constexpr (SP2) {
;             PG8_LDB(B0, 0, 0); PG8_LDB(B1, 0, 1); PG8_SCHED; PG8_LDA(At, 0, 0); PG8_STAGE(PG8_SA(1, 1), a1 + hstep, voffA);
;             PG8_WAIT_V(8); PG8_WAIT_L(0); PG8_BAR; PG8_MMA(0, 0, At, B0); PG8_MMA(0, 1, At, B1); PG8_BAR; PG8_SCHED;
;             PG8_LDA(At, 0, 1); PG8_STAGE(PG8_SB(0, 0), b2, voffB); PG8_STAGE(PG8_SB(0, 1), b2 + hstep, voffB); PG8_STAGE(PG8_SA(0, 0), a2, voffA);
;             PG8_WAIT_V(8); PG8_WAIT_L(0); PG8_BAR; PG8_MMA(1, 0, At, B0); PG8_MMA(1, 1, At, B1); PG8_BAR; PG8_SCHED;
;             PG8_LDB(B0, 1, 0); PG8_LDB(B1, 1, 1); PG8_SCHED; PG8_LDA(At, 1, 0); PG8_STAGE(PG8_SA(0, 1), a2 + hstep, voffA);
;             PG8_WAIT_V(8); PG8_WAIT_L(0); PG8_BAR; PG8_MMA(0, 0, At, B0); PG8_MMA(0, 1, At, B1); PG8_BAR; PG8_SCHED;
;             PG8_LDA(At, 1, 1); PG8_STAGE(PG8_SB(1, 0), b3, voffB); PG8_STAGE(PG8_SB(1, 1), b3 + hstep, voffB); PG8_STAGE(PG8_SA(1, 0), a3, voffA);
;             PG8_WAIT_V(8); PG8_WAIT_L(0); PG8_BAR; PG8_MMA(1, 0, At, B0); PG8_MMA(1, 1, At, B1); PG8_BAR; PG8_SCHED;
;     ...
;     PG8_WAIT_V(0);
;     if constexpr (!ALIGN_EPI) { if (wr == 0) PG8_BAR; }
;     PG8_BAR;
	s_mov_b32 m0, s87
	v_lshl_add_u64 v[204:205], v[204:205], 0, s[36:37]
	s_add_u32 s44, s44, 0x80080
	ds_read_b128 v[172:175], v139 offset:49152
	ds_read_b128 v[176:179], v139 offset:50176
	ds_read_b128 v[180:183], v139 offset:51200
	ds_read_b128 v[184:187], v139 offset:52224
	ds_read_b128 v[188:191], v139 offset:53248
	ds_read_b128 v[192:195], v139 offset:54272
	ds_read_b128 v[196:199], v139 offset:55296
	ds_read_b128 v[200:203], v139 offset:56320
	global_load_lds_dwordx4 v[204:205], off
	v_lshl_add_u64 v[204:205], v[206:207], 0, s[36:37]
	s_mov_b32 m0, s88
	s_addc_u32 s45, s45, 0
	global_load_lds_dwordx4 v[204:205], off
	v_lshl_add_u64 v[204:205], s[44:45], 0, v[224:225]
	s_mov_b32 m0, s89
	s_nop 0
	global_load_lds_dwordx4 v[204:205], off
	v_lshl_add_u64 v[204:205], s[44:45], 0, v[132:133]
	s_mov_b32 m0, s90
	s_nop 0
	global_load_lds_dwordx4 v[204:205], off
	v_lshl_add_u64 v[204:205], v[208:209], 0, s[36:37]
	s_mov_b32 m0, s73
	s_nop 0
	global_load_lds_dwordx4 v[204:205], off
	v_lshl_add_u64 v[204:205], v[210:211], 0, s[36:37]
	s_mov_b32 m0, s74
	s_nop 0
	global_load_lds_dwordx4 v[204:205], off
	s_waitcnt vmcnt(8)
	s_waitcnt lgkmcnt(0)
	s_barrier
	s_waitcnt lgkmcnt(0)
	v_mfma_f32_16x16x32_bf16 v[124:127], v[140:143], v[172:175], v[124:127]
	v_mfma_f32_16x16x32_bf16 v[120:123], v[148:151], v[172:175], v[120:123]
	v_mfma_f32_16x16x32_bf16 v[92:95], v[140:143], v[180:183], v[92:95]
	v_mfma_f32_16x16x32_bf16 v[88:91], v[148:151], v[180:183], v[88:91]
	v_mfma_f32_16x16x32_bf16 v[52:55], v[140:143], v[188:191], v[52:55]
	v_mfma_f32_16x16x32_bf16 v[44:47], v[148:151], v[188:191], v[44:47]
	v_mfma_f32_16x16x32_bf16 v[12:15], v[140:143], v[196:199], v[12:15]
	v_mfma_f32_16x16x32_bf16 v[8:11], v[148:151], v[196:199], v[8:11]
	v_mfma_f32_16x16x32_bf16 v[124:127], v[144:147], v[176:179], v[124:127]
	v_mfma_f32_16x16x32_bf16 v[120:123], v[152:155], v[176:179], v[120:123]
	v_mfma_f32_16x16x32_bf16 v[92:95], v[144:147], v[184:187], v[92:95]
	v_mfma_f32_16x16x32_bf16 v[88:91], v[152:155], v[184:187], v[88:91]
	v_mfma_f32_16x16x32_bf16 v[52:55], v[144:147], v[192:195], v[52:55]
	v_mfma_f32_16x16x32_bf16 v[44:47], v[152:155], v[192:195], v[44:47]
	v_mfma_f32_16x16x32_bf16 v[12:15], v[144:147], v[200:203], v[12:15]
	v_mfma_f32_16x16x32_bf16 v[8:11], v[152:155], v[200:203], v[8:11]
	v_mfma_f32_16x16x32_bf16 v[108:111], v[156:159], v[172:175], v[108:111]
	v_mfma_f32_16x16x32_bf16 v[104:107], v[164:167], v[172:175], v[104:107]
	v_mfma_f32_16x16x32_bf16 v[68:71], v[156:159], v[180:183], v[68:71]
	v_mfma_f32_16x16x32_bf16 v[64:67], v[164:167], v[180:183], v[64:67]
	v_mfma_f32_16x16x32_bf16 v[20:23], v[156:159], v[188:191], v[20:23]
	v_mfma_f32_16x16x32_bf16 v[16:19], v[164:167], v[188:191], v[16:19]
	v_mfma_f32_16x16x32_bf16 v[4:7], v[156:159], v[196:199], v[4:7]
	v_mfma_f32_16x16x32_bf16 v[0:3], v[164:167], v[196:199], v[0:3]
	v_mfma_f32_16x16x32_bf16 v[108:111], v[160:163], v[176:179], v[108:111]
	v_mfma_f32_16x16x32_bf16 v[104:107], v[168:171], v[176:179], v[104:107]
	v_mfma_f32_16x16x32_bf16 v[68:71], v[160:163], v[184:187], v[68:71]
	v_mfma_f32_16x16x32_bf16 v[64:67], v[168:171], v[184:187], v[64:67]
	v_mfma_f32_16x16x32_bf16 v[20:23], v[160:163], v[192:195], v[20:23]
	v_mfma_f32_16x16x32_bf16 v[16:19], v[168:171], v[192:195], v[16:19]
	v_mfma_f32_16x16x32_bf16 v[4:7], v[160:163], v[200:203], v[4:7]
	v_mfma_f32_16x16x32_bf16 v[0:3], v[168:171], v[200:203], v[0:3]
	s_barrier
	s_add_i32 s49, s49, 2
	s_add_u32 s43, s43, 0x100
	s_addc_u32 s48, s48, 0
	s_add_u32 s6, s6, 0x100
	s_addc_u32 s7, s7, 0
	v_lshl_add_u64 v[134:135], v[134:135], 0, s[38:39]
	s_cmp_lt_u32 s49, 30
	v_lshl_add_u64 v[136:137], v[136:137], 0, s[38:39]
	s_cbranch_scc1 .LBB0_581
	s_waitcnt vmcnt(0)
	s_and_b64 vcc, exec, s[4:5]
	s_cbranch_vccnz .LBB0_584
	s_barrier
